# MLA attention: 12-step specialised steady-state loop (static ring slots as ds_read immediates, guards resolved per wave class), bit-identical
# speedup vs baseline: 1.0141x; 1.0141x over previous
.LBB0_1278:
	s_cmp_eq_u32 s13, 0
	s_cbranch_scc1 .Lmla_dispatch
	s_add_i32 s13, s13, 2
	s_cmpk_gt_u32 s13, 0x7c
	s_mov_b64 s[24:25], -1
	s_cbranch_scc0 .LBB0_1280
	s_waitcnt vmcnt(0) lgkmcnt(0)
	s_barrier
	s_mov_b64 s[24:25], 0

.Lmla_fast_w03:
	s_waitcnt vmcnt(6) lgkmcnt(0)
	s_barrier
	s_waitcnt lgkmcnt(6)
	v_mfma_f32_32x32x16_bf16 v[2:17], v[134:137], v[166:169], v[2:17]
	ds_read_b64_tr_b16 v[66:67], v189 offset:28672
	ds_read_b64_tr_b16 v[68:69], v189 offset:29184
	v_exp_f32_e32 v34, v34
	v_exp_f32_e32 v35, v35
	v_exp_f32_e32 v36, v36
	s_waitcnt lgkmcnt(6)
	v_mfma_f32_32x32x16_bf16 v[2:17], v[130:133], v[162:165], v[2:17]
	ds_read_b64_tr_b16 v[70:71], v189 offset:29696
	ds_read_b64_tr_b16 v[72:73], v189 offset:30208
	v_add_f32_e32 v74, v193, v34
	v_exp_f32_e32 v37, v37
	v_cvt_pk_bf16_f32 v150, v34, v35
	v_add_f32_e32 v78, v35, v74
	s_waitcnt lgkmcnt(6)
	v_mfma_f32_32x32x16_bf16 v[2:17], v[126:129], v[158:161], v[2:17]
	ds_read_b64_tr_b16 v[74:75], v189 offset:30720
	ds_read_b64_tr_b16 v[76:77], v189 offset:31232
	v_exp_f32_e32 v38, v38
	v_exp_f32_e32 v39, v39
	v_add_f32_e32 v82, v78, v36
	v_cvt_pk_bf16_f32 v151, v36, v37
	s_waitcnt lgkmcnt(6)
	v_mfma_f32_32x32x16_bf16 v[2:17], v[122:125], v[154:157], v[2:17]
	ds_read_b64_tr_b16 v[78:79], v189 offset:31744
	ds_read_b64_tr_b16 v[80:81], v189 offset:32256
	v_add_f32_e32 v82, v82, v37
	v_exp_f32_e32 v40, v40
	v_exp_f32_e32 v41, v41
	v_add_f32_e32 v86, v38, v82
	s_waitcnt lgkmcnt(6)
	v_mfma_f32_32x32x16_bf16 v[18:33], v[134:137], v[66:69], v[18:33]
	ds_read_b128 v[82:85], v182 offset:36864
	v_cvt_pk_bf16_f32 v152, v38, v39
	v_add_f32_e32 v90, v86, v39
	v_exp_f32_e32 v42, v42
	v_exp_f32_e32 v43, v43
	s_waitcnt lgkmcnt(5)
	v_mfma_f32_32x32x16_bf16 v[18:33], v[130:133], v[70:73], v[18:33]
	ds_read_b128 v[86:89], v182 offset:40960
	v_add_f32_e32 v66, v90, v40
	v_exp_f32_e32 v44, v44
	v_cvt_pk_bf16_f32 v153, v40, v41
	v_add_f32_e32 v66, v41, v66
	s_waitcnt lgkmcnt(4)
	v_mfma_f32_32x32x16_bf16 v[18:33], v[126:129], v[74:77], v[18:33]
	ds_read_b128 v[154:157], v183 offset:36864
	v_add_f32_e32 v66, v66, v42
	v_exp_f32_e32 v45, v45
	v_cvt_pk_bf16_f32 v146, v42, v43
	v_add_f32_e32 v66, v43, v66
	s_waitcnt lgkmcnt(3)
	v_mfma_f32_32x32x16_bf16 v[18:33], v[122:125], v[78:81], v[18:33]
	ds_read_b128 v[162:165], v183 offset:40960
	v_exp_f32_e32 v46, v46
	v_exp_f32_e32 v47, v47
	v_add_f32_e32 v66, v66, v44
	v_cvt_pk_bf16_f32 v147, v44, v45
	s_nop 0
	v_add_f32_e32 v66, v66, v45
	v_add_f32_e32 v91, v46, v66
	s_waitcnt lgkmcnt(3)
	v_mfma_f32_32x32x16_bf16 v[66:81], v[82:85], v[98:101], 0
	ds_read_b128 v[166:169], v184 offset:36864
	v_exp_f32_e32 v48, v48
	v_exp_f32_e32 v49, v49
	ds_read_b128 v[158:161], v184 offset:40960
	v_add_f32_e32 v193, v91, v47
	s_waitcnt lgkmcnt(4)
	v_mfma_f32_32x32x16_bf16 v[82:97], v[86:89], v[98:101], 0
	v_exp_f32_e32 v50, v50
	v_exp_f32_e32 v51, v51
	v_cvt_pk_bf16_f32 v148, v46, v47
	s_add_u32 s26, s20, 0xfffe0000
	s_addc_u32 s27, s21, -1
	s_add_i32 s31, 0x6000, s8
	s_add_i32 s33, 0, s12
	s_add_u32 s28, s22, 0xfffff000
	s_addc_u32 s29, s23, -1
	s_add_i32 s40, s31, 0x2000
	s_nop 4
	s_mov_b32 s41, m0
	s_mov_b32 m0, s31
	s_nop 0
	global_load_lds_dwordx4 v174, s[26:27]
	s_mov_b32 m0, s40
	s_nop 0
	global_load_lds_dwordx4 v192, s[28:29]
	s_mov_b32 m0, s33
	s_nop 0
	global_load_lds_dwordx4 v191, s[26:27]
	s_mov_b32 m0, s41
	s_waitcnt lgkmcnt(3)
	v_mfma_f32_32x32x16_bf16 v[66:81], v[154:157], v[102:105], v[66:81]
	ds_read_b128 v[194:197], v185 offset:36864
	v_add_f32_e32 v193, v193, v48
	v_cvt_pk_bf16_f32 v149, v48, v49
	v_add_f32_e32 v193, v49, v193
	v_exp_f32_e32 v52, v52
	s_waitcnt lgkmcnt(3)
	v_mfma_f32_32x32x16_bf16 v[82:97], v[162:165], v[102:105], v[82:97]
	ds_read_b128 v[154:157], v185 offset:40960
	v_add_f32_e32 v193, v193, v50
	v_exp_f32_e32 v53, v53
	v_cvt_pk_bf16_f32 v142, v50, v51
	v_add_f32_e32 v193, v51, v193
	s_waitcnt lgkmcnt(3)
	v_mfma_f32_32x32x16_bf16 v[66:81], v[166:169], v[106:109], v[66:81]
	ds_read_b128 v[162:165], v187 offset:45056
	v_exp_f32_e32 v54, v54
	v_exp_f32_e32 v55, v55
	v_add_f32_e32 v193, v193, v52
	v_cvt_pk_bf16_f32 v143, v52, v53
	s_waitcnt lgkmcnt(3)
	v_mfma_f32_32x32x16_bf16 v[82:97], v[158:161], v[106:109], v[82:97]
	ds_read_b128 v[198:201], v187 offset:47104
	v_add_f32_e32 v166, v193, v53
	v_exp_f32_e32 v56, v56
	v_exp_f32_e32 v57, v57
	v_add_f32_e32 v166, v54, v166
	s_waitcnt lgkmcnt(3)
	v_mfma_f32_32x32x16_bf16 v[66:81], v[194:197], v[110:113], v[66:81]
	ds_read_b128 v[202:205], v188 offset:45056
	v_cvt_pk_bf16_f32 v144, v54, v55
	v_add_f32_e32 v159, v166, v55
	v_exp_f32_e32 v58, v58
	v_exp_f32_e32 v59, v59
	s_waitcnt lgkmcnt(3)
	v_mfma_f32_32x32x16_bf16 v[82:97], v[154:157], v[110:113], v[82:97]
	ds_read_b128 v[194:197], v188 offset:47104
	v_add_f32_e32 v158, v159, v56
	v_exp_f32_e32 v60, v60
	v_cvt_pk_bf16_f32 v145, v56, v57
	v_add_f32_e32 v158, v57, v158
	s_waitcnt lgkmcnt(3)
	v_mfma_f32_32x32x16_bf16 v[66:81], v[162:165], v[114:117], v[66:81]
	ds_read_b64_tr_b16 v[166:167], v189 offset:32768
	ds_read_b64_tr_b16 v[168:169], v189 offset:33280
	v_add_f32_e32 v154, v158, v58
	v_exp_f32_e32 v61, v61
	v_cvt_pk_bf16_f32 v138, v58, v59
	v_add_f32_e32 v154, v59, v154
	s_waitcnt lgkmcnt(4)
	v_mfma_f32_32x32x16_bf16 v[82:97], v[198:201], v[114:117], v[82:97]
	ds_read_b64_tr_b16 v[162:163], v189 offset:33792
	ds_read_b64_tr_b16 v[164:165], v189 offset:34304
	v_exp_f32_e32 v62, v62
	v_exp_f32_e32 v63, v63
	v_add_f32_e32 v154, v154, v60
	v_cvt_pk_bf16_f32 v139, v60, v61
	s_waitcnt lgkmcnt(5)
	v_mfma_f32_32x32x16_bf16 v[66:81], v[202:205], v[118:121], v[66:81]
	ds_read_b64_tr_b16 v[158:159], v189 offset:34816
	ds_read_b64_tr_b16 v[160:161], v189 offset:35328
	v_add_f32_e32 v154, v154, v61
	v_exp_f32_e32 v64, v64
	v_exp_f32_e32 v65, v65
	v_add_f32_e32 v198, v62, v154
	s_waitcnt lgkmcnt(6)
	v_mfma_f32_32x32x16_bf16 v[82:97], v[194:197], v[118:121], v[82:97]
	ds_read_b64_tr_b16 v[154:155], v189 offset:35840
	ds_read_b64_tr_b16 v[156:157], v189 offset:36352
	v_add_f32_e32 v141, v198, v63
	v_add_f32_e32 v198, v64, v141
	v_cvt_pk_bf16_f32 v140, v62, v63
	v_cvt_pk_bf16_f32 v141, v64, v65
	v_add_f32_e32 v194, v65, v198
	s_waitcnt vmcnt(6) lgkmcnt(0)
	s_barrier
	s_waitcnt lgkmcnt(6)
	v_mfma_f32_32x32x16_bf16 v[2:17], v[150:153], v[166:169], v[2:17]
	ds_read_b64_tr_b16 v[34:35], v189 offset:36864
	ds_read_b64_tr_b16 v[36:37], v189 offset:37376
	v_exp_f32_e32 v66, v66
	v_exp_f32_e32 v67, v67
	v_exp_f32_e32 v68, v68
	s_waitcnt lgkmcnt(6)
	v_mfma_f32_32x32x16_bf16 v[2:17], v[146:149], v[162:165], v[2:17]
	ds_read_b64_tr_b16 v[38:39], v189 offset:37888
	ds_read_b64_tr_b16 v[40:41], v189 offset:38400
	v_add_f32_e32 v42, v194, v66
	v_exp_f32_e32 v69, v69
	v_cvt_pk_bf16_f32 v134, v66, v67
	v_add_f32_e32 v46, v67, v42
	s_waitcnt lgkmcnt(6)
	v_mfma_f32_32x32x16_bf16 v[2:17], v[142:145], v[158:161], v[2:17]
	ds_read_b64_tr_b16 v[42:43], v189 offset:38912
	ds_read_b64_tr_b16 v[44:45], v189 offset:39424
	v_exp_f32_e32 v70, v70
	v_exp_f32_e32 v71, v71
	v_add_f32_e32 v50, v46, v68
	v_cvt_pk_bf16_f32 v135, v68, v69
	s_waitcnt lgkmcnt(6)
	v_mfma_f32_32x32x16_bf16 v[2:17], v[138:141], v[154:157], v[2:17]
	ds_read_b64_tr_b16 v[46:47], v189 offset:39936
	ds_read_b64_tr_b16 v[48:49], v189 offset:40448
	v_add_f32_e32 v50, v50, v69
	v_exp_f32_e32 v72, v72
	v_exp_f32_e32 v73, v73
	v_add_f32_e32 v54, v70, v50
	s_waitcnt lgkmcnt(6)
	v_mfma_f32_32x32x16_bf16 v[18:33], v[150:153], v[34:37], v[18:33]
	ds_read_b128 v[50:53], v182
	v_cvt_pk_bf16_f32 v136, v70, v71
	v_add_f32_e32 v58, v54, v71
	v_exp_f32_e32 v74, v74
	v_exp_f32_e32 v75, v75
	s_waitcnt lgkmcnt(5)
	v_mfma_f32_32x32x16_bf16 v[18:33], v[146:149], v[38:41], v[18:33]
	ds_read_b128 v[54:57], v182 offset:4096
	v_add_f32_e32 v34, v58, v72
	v_exp_f32_e32 v76, v76
	v_cvt_pk_bf16_f32 v137, v72, v73
	v_add_f32_e32 v34, v73, v34
	s_waitcnt lgkmcnt(4)
	v_mfma_f32_32x32x16_bf16 v[18:33], v[142:145], v[42:45], v[18:33]
	ds_read_b128 v[154:157], v183
	v_add_f32_e32 v34, v34, v74
	v_exp_f32_e32 v77, v77
	v_cvt_pk_bf16_f32 v130, v74, v75
	v_add_f32_e32 v34, v75, v34
	s_waitcnt lgkmcnt(3)
	v_mfma_f32_32x32x16_bf16 v[18:33], v[138:141], v[46:49], v[18:33]
	ds_read_b128 v[162:165], v183 offset:4096
	v_exp_f32_e32 v78, v78
	v_exp_f32_e32 v79, v79
	v_add_f32_e32 v34, v34, v76
	v_cvt_pk_bf16_f32 v131, v76, v77
	s_nop 0
	v_add_f32_e32 v34, v34, v77
	v_add_f32_e32 v59, v78, v34
	s_waitcnt lgkmcnt(3)
	v_mfma_f32_32x32x16_bf16 v[34:49], v[50:53], v[98:101], 0
	ds_read_b128 v[166:169], v184
	v_exp_f32_e32 v80, v80
	v_exp_f32_e32 v81, v81
	ds_read_b128 v[158:161], v184 offset:4096
	v_add_f32_e32 v193, v59, v79
	s_waitcnt lgkmcnt(4)
	v_mfma_f32_32x32x16_bf16 v[50:65], v[54:57], v[98:101], 0
	v_exp_f32_e32 v82, v82
	v_exp_f32_e32 v83, v83
	v_cvt_pk_bf16_f32 v132, v78, v79
	s_add_i32 s26, 0x9000, s8
	s_add_i32 s28, 0x2000, s12
	s_add_i32 s24, s26, 0x2000
	s_nop 4
	s_mov_b32 s25, m0
	s_mov_b32 m0, s26
	s_nop 0
	global_load_lds_dwordx4 v174, s[20:21]
	s_mov_b32 m0, s24
	s_nop 0
	global_load_lds_dwordx4 v192, s[22:23]
	s_mov_b32 m0, s28
	s_nop 0
	global_load_lds_dwordx4 v191, s[20:21]
	s_mov_b32 m0, s25
	s_waitcnt lgkmcnt(3)
	v_mfma_f32_32x32x16_bf16 v[34:49], v[154:157], v[102:105], v[34:49]
	ds_read_b128 v[194:197], v185
	v_add_f32_e32 v154, v193, v80
	v_exp_f32_e32 v84, v84
	v_cvt_pk_bf16_f32 v133, v80, v81
	v_add_f32_e32 v193, v81, v154
	s_waitcnt lgkmcnt(3)
	v_mfma_f32_32x32x16_bf16 v[50:65], v[162:165], v[102:105], v[50:65]
	ds_read_b128 v[154:157], v185 offset:4096
	v_add_f32_e32 v193, v193, v82
	v_exp_f32_e32 v85, v85
	v_cvt_pk_bf16_f32 v126, v82, v83
	v_add_f32_e32 v193, v83, v193
	s_waitcnt lgkmcnt(3)
	v_mfma_f32_32x32x16_bf16 v[34:49], v[166:169], v[106:109], v[34:49]
	ds_read_b128 v[162:165], v187 offset:8192
	v_exp_f32_e32 v86, v86
	v_exp_f32_e32 v87, v87
	v_add_f32_e32 v193, v193, v84
	v_cvt_pk_bf16_f32 v127, v84, v85
	s_waitcnt lgkmcnt(3)
	v_mfma_f32_32x32x16_bf16 v[50:65], v[158:161], v[106:109], v[50:65]
	ds_read_b128 v[198:201], v187 offset:10240
	v_add_f32_e32 v166, v193, v85
	v_exp_f32_e32 v88, v88
	v_exp_f32_e32 v89, v89
	v_add_f32_e32 v166, v86, v166
	s_waitcnt lgkmcnt(3)
	v_mfma_f32_32x32x16_bf16 v[34:49], v[194:197], v[110:113], v[34:49]
	ds_read_b128 v[202:205], v188 offset:8192
	v_cvt_pk_bf16_f32 v128, v86, v87
	v_add_f32_e32 v159, v166, v87
	v_exp_f32_e32 v90, v90
	v_exp_f32_e32 v91, v91
	s_waitcnt lgkmcnt(3)
	v_mfma_f32_32x32x16_bf16 v[50:65], v[154:157], v[110:113], v[50:65]
	ds_read_b128 v[194:197], v188 offset:10240
	v_add_f32_e32 v158, v159, v88
	v_exp_f32_e32 v92, v92
	v_cvt_pk_bf16_f32 v129, v88, v89
	v_add_f32_e32 v158, v89, v158
	s_waitcnt lgkmcnt(3)
	v_mfma_f32_32x32x16_bf16 v[34:49], v[162:165], v[114:117], v[34:49]
	ds_read_b64_tr_b16 v[166:167], v189 offset:40960
	ds_read_b64_tr_b16 v[168:169], v189 offset:41472
	v_add_f32_e32 v154, v158, v90
	v_exp_f32_e32 v93, v93
	v_cvt_pk_bf16_f32 v122, v90, v91
	v_add_f32_e32 v154, v91, v154
	s_waitcnt lgkmcnt(4)
	v_mfma_f32_32x32x16_bf16 v[50:65], v[198:201], v[114:117], v[50:65]
	ds_read_b64_tr_b16 v[162:163], v189 offset:41984
	ds_read_b64_tr_b16 v[164:165], v189 offset:42496
	v_exp_f32_e32 v94, v94
	v_exp_f32_e32 v95, v95
	v_add_f32_e32 v154, v154, v92
	v_cvt_pk_bf16_f32 v123, v92, v93
	s_waitcnt lgkmcnt(5)
	v_mfma_f32_32x32x16_bf16 v[34:49], v[202:205], v[118:121], v[34:49]
	ds_read_b64_tr_b16 v[158:159], v189 offset:43008
	ds_read_b64_tr_b16 v[160:161], v189 offset:43520
	v_add_f32_e32 v154, v154, v93
	v_exp_f32_e32 v96, v96
	v_exp_f32_e32 v97, v97
	v_add_f32_e32 v193, v94, v154
	s_waitcnt lgkmcnt(6)
	v_mfma_f32_32x32x16_bf16 v[50:65], v[194:197], v[118:121], v[50:65]
	ds_read_b64_tr_b16 v[154:155], v189 offset:44032
	ds_read_b64_tr_b16 v[156:157], v189 offset:44544
	v_add_f32_e32 v125, v193, v95
	v_add_f32_e32 v193, v96, v125
	v_cvt_pk_bf16_f32 v124, v94, v95
	v_cvt_pk_bf16_f32 v125, v96, v97
	v_add_f32_e32 v193, v97, v193
	s_add_u32 s22, s22, 0x2000
	s_addc_u32 s23, s23, 0
	s_add_u32 s20, s20, 0x40000
	s_addc_u32 s21, s21, 0
	s_waitcnt vmcnt(6) lgkmcnt(0)
	s_barrier
	s_waitcnt lgkmcnt(6)
	v_mfma_f32_32x32x16_bf16 v[2:17], v[134:137], v[166:169], v[2:17]
	ds_read_b64_tr_b16 v[66:67], v189 offset:45056
	ds_read_b64_tr_b16 v[68:69], v189 offset:45568
	v_exp_f32_e32 v34, v34
	v_exp_f32_e32 v35, v35
	v_exp_f32_e32 v36, v36
	s_waitcnt lgkmcnt(6)
	v_mfma_f32_32x32x16_bf16 v[2:17], v[130:133], v[162:165], v[2:17]
	ds_read_b64_tr_b16 v[70:71], v189 offset:46080
	ds_read_b64_tr_b16 v[72:73], v189 offset:46592
	v_add_f32_e32 v74, v193, v34
	v_exp_f32_e32 v37, v37
	v_cvt_pk_bf16_f32 v150, v34, v35
	v_add_f32_e32 v78, v35, v74
	s_waitcnt lgkmcnt(6)
	v_mfma_f32_32x32x16_bf16 v[2:17], v[126:129], v[158:161], v[2:17]
	ds_read_b64_tr_b16 v[74:75], v189 offset:47104
	ds_read_b64_tr_b16 v[76:77], v189 offset:47616
	v_exp_f32_e32 v38, v38
	v_exp_f32_e32 v39, v39
	v_add_f32_e32 v82, v78, v36
	v_cvt_pk_bf16_f32 v151, v36, v37
	s_waitcnt lgkmcnt(6)
	v_mfma_f32_32x32x16_bf16 v[2:17], v[122:125], v[154:157], v[2:17]
	ds_read_b64_tr_b16 v[78:79], v189 offset:48128
	ds_read_b64_tr_b16 v[80:81], v189 offset:48640
	v_add_f32_e32 v82, v82, v37
	v_exp_f32_e32 v40, v40
	v_exp_f32_e32 v41, v41
	v_add_f32_e32 v86, v38, v82
	s_waitcnt lgkmcnt(6)
	v_mfma_f32_32x32x16_bf16 v[18:33], v[134:137], v[66:69], v[18:33]
	ds_read_b128 v[82:85], v182 offset:12288
	v_cvt_pk_bf16_f32 v152, v38, v39
	v_add_f32_e32 v90, v86, v39
	v_exp_f32_e32 v42, v42
	v_exp_f32_e32 v43, v43
	s_waitcnt lgkmcnt(5)
	v_mfma_f32_32x32x16_bf16 v[18:33], v[130:133], v[70:73], v[18:33]
	ds_read_b128 v[86:89], v182 offset:16384
	v_add_f32_e32 v66, v90, v40
	v_exp_f32_e32 v44, v44
	v_cvt_pk_bf16_f32 v153, v40, v41
	v_add_f32_e32 v66, v41, v66
	s_waitcnt lgkmcnt(4)
	v_mfma_f32_32x32x16_bf16 v[18:33], v[126:129], v[74:77], v[18:33]
	ds_read_b128 v[154:157], v183 offset:12288
	v_add_f32_e32 v66, v66, v42
	v_exp_f32_e32 v45, v45
	v_cvt_pk_bf16_f32 v146, v42, v43
	v_add_f32_e32 v66, v43, v66
	s_waitcnt lgkmcnt(3)
	v_mfma_f32_32x32x16_bf16 v[18:33], v[122:125], v[78:81], v[18:33]
	ds_read_b128 v[162:165], v183 offset:16384
	v_exp_f32_e32 v46, v46
	v_exp_f32_e32 v47, v47
	v_add_f32_e32 v66, v66, v44
	v_cvt_pk_bf16_f32 v147, v44, v45
	s_nop 0
	v_add_f32_e32 v66, v66, v45
	v_add_f32_e32 v91, v46, v66
	s_waitcnt lgkmcnt(3)
	v_mfma_f32_32x32x16_bf16 v[66:81], v[82:85], v[98:101], 0
	ds_read_b128 v[166:169], v184 offset:12288
	v_exp_f32_e32 v48, v48
	v_exp_f32_e32 v49, v49
	ds_read_b128 v[158:161], v184 offset:16384
	v_add_f32_e32 v193, v91, v47
	s_waitcnt lgkmcnt(4)
	v_mfma_f32_32x32x16_bf16 v[82:97], v[86:89], v[98:101], 0
	v_exp_f32_e32 v50, v50
	v_exp_f32_e32 v51, v51
	v_cvt_pk_bf16_f32 v148, v46, v47
	s_add_u32 s26, s20, 0xfffe0000
	s_addc_u32 s27, s21, -1
	s_add_i32 s31, 0, s8
	s_add_i32 s33, 0x4000, s12
	s_add_u32 s28, s22, 0xfffff000
	s_addc_u32 s29, s23, -1
	s_add_i32 s40, s31, 0x2000
	s_nop 4
	s_mov_b32 s41, m0
	s_mov_b32 m0, s31
	s_nop 0
	global_load_lds_dwordx4 v174, s[26:27]
	s_mov_b32 m0, s40
	s_nop 0
	global_load_lds_dwordx4 v192, s[28:29]
	s_mov_b32 m0, s33
	s_nop 0
	global_load_lds_dwordx4 v191, s[26:27]
	s_mov_b32 m0, s41
	s_waitcnt lgkmcnt(3)
	v_mfma_f32_32x32x16_bf16 v[66:81], v[154:157], v[102:105], v[66:81]
	ds_read_b128 v[194:197], v185 offset:12288
	v_add_f32_e32 v193, v193, v48
	v_cvt_pk_bf16_f32 v149, v48, v49
	v_add_f32_e32 v193, v49, v193
	v_exp_f32_e32 v52, v52
	s_waitcnt lgkmcnt(3)
	v_mfma_f32_32x32x16_bf16 v[82:97], v[162:165], v[102:105], v[82:97]
	ds_read_b128 v[154:157], v185 offset:16384
	v_add_f32_e32 v193, v193, v50
	v_exp_f32_e32 v53, v53
	v_cvt_pk_bf16_f32 v142, v50, v51
	v_add_f32_e32 v193, v51, v193
	s_waitcnt lgkmcnt(3)
	v_mfma_f32_32x32x16_bf16 v[66:81], v[166:169], v[106:109], v[66:81]
	ds_read_b128 v[162:165], v187 offset:20480
	v_exp_f32_e32 v54, v54
	v_exp_f32_e32 v55, v55
	v_add_f32_e32 v193, v193, v52
	v_cvt_pk_bf16_f32 v143, v52, v53
	s_waitcnt lgkmcnt(3)
	v_mfma_f32_32x32x16_bf16 v[82:97], v[158:161], v[106:109], v[82:97]
	ds_read_b128 v[198:201], v187 offset:22528
	v_add_f32_e32 v166, v193, v53
	v_exp_f32_e32 v56, v56
	v_exp_f32_e32 v57, v57
	v_add_f32_e32 v166, v54, v166
	s_waitcnt lgkmcnt(3)
	v_mfma_f32_32x32x16_bf16 v[66:81], v[194:197], v[110:113], v[66:81]
	ds_read_b128 v[202:205], v188 offset:20480
	v_cvt_pk_bf16_f32 v144, v54, v55
	v_add_f32_e32 v159, v166, v55
	v_exp_f32_e32 v58, v58
	v_exp_f32_e32 v59, v59
	s_waitcnt lgkmcnt(3)
	v_mfma_f32_32x32x16_bf16 v[82:97], v[154:157], v[110:113], v[82:97]
	ds_read_b128 v[194:197], v188 offset:22528
	v_add_f32_e32 v158, v159, v56
	v_exp_f32_e32 v60, v60
	v_cvt_pk_bf16_f32 v145, v56, v57
	v_add_f32_e32 v158, v57, v158
	s_waitcnt lgkmcnt(3)
	v_mfma_f32_32x32x16_bf16 v[66:81], v[162:165], v[114:117], v[66:81]
	ds_read_b64_tr_b16 v[166:167], v189 offset:49152
	ds_read_b64_tr_b16 v[168:169], v189 offset:49664
	v_add_f32_e32 v154, v158, v58
	v_exp_f32_e32 v61, v61
	v_cvt_pk_bf16_f32 v138, v58, v59
	v_add_f32_e32 v154, v59, v154
	s_waitcnt lgkmcnt(4)
	v_mfma_f32_32x32x16_bf16 v[82:97], v[198:201], v[114:117], v[82:97]
	ds_read_b64_tr_b16 v[162:163], v189 offset:50176
	ds_read_b64_tr_b16 v[164:165], v189 offset:50688
	v_exp_f32_e32 v62, v62
	v_exp_f32_e32 v63, v63
	v_add_f32_e32 v154, v154, v60
	v_cvt_pk_bf16_f32 v139, v60, v61
	s_waitcnt lgkmcnt(5)
	v_mfma_f32_32x32x16_bf16 v[66:81], v[202:205], v[118:121], v[66:81]
	ds_read_b64_tr_b16 v[158:159], v189 offset:51200
	ds_read_b64_tr_b16 v[160:161], v189 offset:51712
	v_add_f32_e32 v154, v154, v61
	v_exp_f32_e32 v64, v64
	v_exp_f32_e32 v65, v65
	v_add_f32_e32 v198, v62, v154
	s_waitcnt lgkmcnt(6)
	v_mfma_f32_32x32x16_bf16 v[82:97], v[194:197], v[118:121], v[82:97]
	ds_read_b64_tr_b16 v[154:155], v189 offset:52224
	ds_read_b64_tr_b16 v[156:157], v189 offset:52736
	v_add_f32_e32 v141, v198, v63
	v_add_f32_e32 v198, v64, v141
	v_cvt_pk_bf16_f32 v140, v62, v63
	v_cvt_pk_bf16_f32 v141, v64, v65
	v_add_f32_e32 v194, v65, v198
	s_waitcnt vmcnt(6) lgkmcnt(0)
	s_barrier
	s_waitcnt lgkmcnt(6)
	v_mfma_f32_32x32x16_bf16 v[2:17], v[150:153], v[166:169], v[2:17]
	ds_read_b64_tr_b16 v[34:35], v189 offset:53248
	ds_read_b64_tr_b16 v[36:37], v189 offset:53760
	v_exp_f32_e32 v66, v66
	v_exp_f32_e32 v67, v67
	v_exp_f32_e32 v68, v68
	s_waitcnt lgkmcnt(6)
	v_mfma_f32_32x32x16_bf16 v[2:17], v[146:149], v[162:165], v[2:17]
	ds_read_b64_tr_b16 v[38:39], v189 offset:54272
	ds_read_b64_tr_b16 v[40:41], v189 offset:54784
	v_add_f32_e32 v42, v194, v66
	v_exp_f32_e32 v69, v69
	v_cvt_pk_bf16_f32 v134, v66, v67
	v_add_f32_e32 v46, v67, v42
	s_waitcnt lgkmcnt(6)
	v_mfma_f32_32x32x16_bf16 v[2:17], v[142:145], v[158:161], v[2:17]
	ds_read_b64_tr_b16 v[42:43], v189 offset:55296
	ds_read_b64_tr_b16 v[44:45], v189 offset:55808
	v_exp_f32_e32 v70, v70
	v_exp_f32_e32 v71, v71
	v_add_f32_e32 v50, v46, v68
	v_cvt_pk_bf16_f32 v135, v68, v69
	s_waitcnt lgkmcnt(6)
	v_mfma_f32_32x32x16_bf16 v[2:17], v[138:141], v[154:157], v[2:17]
	ds_read_b64_tr_b16 v[46:47], v189 offset:56320
	ds_read_b64_tr_b16 v[48:49], v189 offset:56832
	v_add_f32_e32 v50, v50, v69
	v_exp_f32_e32 v72, v72
	v_exp_f32_e32 v73, v73
	v_add_f32_e32 v54, v70, v50
	s_waitcnt lgkmcnt(6)
	v_mfma_f32_32x32x16_bf16 v[18:33], v[150:153], v[34:37], v[18:33]
	ds_read_b128 v[50:53], v182 offset:24576
	v_cvt_pk_bf16_f32 v136, v70, v71
	v_add_f32_e32 v58, v54, v71
	v_exp_f32_e32 v74, v74
	v_exp_f32_e32 v75, v75
	s_waitcnt lgkmcnt(5)
	v_mfma_f32_32x32x16_bf16 v[18:33], v[146:149], v[38:41], v[18:33]
	ds_read_b128 v[54:57], v182 offset:28672
	v_add_f32_e32 v34, v58, v72
	v_exp_f32_e32 v76, v76
	v_cvt_pk_bf16_f32 v137, v72, v73
	v_add_f32_e32 v34, v73, v34
	s_waitcnt lgkmcnt(4)
	v_mfma_f32_32x32x16_bf16 v[18:33], v[142:145], v[42:45], v[18:33]
	ds_read_b128 v[154:157], v183 offset:24576
	v_add_f32_e32 v34, v34, v74
	v_exp_f32_e32 v77, v77
	v_cvt_pk_bf16_f32 v130, v74, v75
	v_add_f32_e32 v34, v75, v34
	s_waitcnt lgkmcnt(3)
	v_mfma_f32_32x32x16_bf16 v[18:33], v[138:141], v[46:49], v[18:33]
	ds_read_b128 v[162:165], v183 offset:28672
	v_exp_f32_e32 v78, v78
	v_exp_f32_e32 v79, v79
	v_add_f32_e32 v34, v34, v76
	v_cvt_pk_bf16_f32 v131, v76, v77
	s_nop 0
	v_add_f32_e32 v34, v34, v77
	v_add_f32_e32 v59, v78, v34
	s_waitcnt lgkmcnt(3)
	v_mfma_f32_32x32x16_bf16 v[34:49], v[50:53], v[98:101], 0
	ds_read_b128 v[166:169], v184 offset:24576
	v_exp_f32_e32 v80, v80
	v_exp_f32_e32 v81, v81
	ds_read_b128 v[158:161], v184 offset:28672
	v_add_f32_e32 v193, v59, v79
	s_waitcnt lgkmcnt(4)
	v_mfma_f32_32x32x16_bf16 v[50:65], v[54:57], v[98:101], 0
	v_exp_f32_e32 v82, v82
	v_exp_f32_e32 v83, v83
	v_cvt_pk_bf16_f32 v132, v78, v79
	s_add_i32 s26, 0x3000, s8
	s_add_i32 s28, 0x6000, s12
	s_add_i32 s24, s26, 0x2000
	s_nop 4
	s_mov_b32 s25, m0
	s_mov_b32 m0, s26
	s_nop 0
	global_load_lds_dwordx4 v174, s[20:21]
	s_mov_b32 m0, s24
	s_nop 0
	global_load_lds_dwordx4 v192, s[22:23]
	s_mov_b32 m0, s28
	s_nop 0
	global_load_lds_dwordx4 v191, s[20:21]
	s_mov_b32 m0, s25
	s_waitcnt lgkmcnt(3)
	v_mfma_f32_32x32x16_bf16 v[34:49], v[154:157], v[102:105], v[34:49]
	ds_read_b128 v[194:197], v185 offset:24576
	v_add_f32_e32 v154, v193, v80
	v_exp_f32_e32 v84, v84
	v_cvt_pk_bf16_f32 v133, v80, v81
	v_add_f32_e32 v193, v81, v154
	s_waitcnt lgkmcnt(3)
	v_mfma_f32_32x32x16_bf16 v[50:65], v[162:165], v[102:105], v[50:65]
	ds_read_b128 v[154:157], v185 offset:28672
	v_add_f32_e32 v193, v193, v82
	v_exp_f32_e32 v85, v85
	v_cvt_pk_bf16_f32 v126, v82, v83
	v_add_f32_e32 v193, v83, v193
	s_waitcnt lgkmcnt(3)
	v_mfma_f32_32x32x16_bf16 v[34:49], v[166:169], v[106:109], v[34:49]
	ds_read_b128 v[162:165], v187 offset:32768
	v_exp_f32_e32 v86, v86
	v_exp_f32_e32 v87, v87
	v_add_f32_e32 v193, v193, v84
	v_cvt_pk_bf16_f32 v127, v84, v85
	s_waitcnt lgkmcnt(3)
	v_mfma_f32_32x32x16_bf16 v[50:65], v[158:161], v[106:109], v[50:65]
	ds_read_b128 v[198:201], v187 offset:34816
	v_add_f32_e32 v166, v193, v85
	v_exp_f32_e32 v88, v88
	v_exp_f32_e32 v89, v89
	v_add_f32_e32 v166, v86, v166
	s_waitcnt lgkmcnt(3)
	v_mfma_f32_32x32x16_bf16 v[34:49], v[194:197], v[110:113], v[34:49]
	ds_read_b128 v[202:205], v188 offset:32768
	v_cvt_pk_bf16_f32 v128, v86, v87
	v_add_f32_e32 v159, v166, v87
	v_exp_f32_e32 v90, v90
	v_exp_f32_e32 v91, v91
	s_waitcnt lgkmcnt(3)
	v_mfma_f32_32x32x16_bf16 v[50:65], v[154:157], v[110:113], v[50:65]
	ds_read_b128 v[194:197], v188 offset:34816
	v_add_f32_e32 v158, v159, v88
	v_exp_f32_e32 v92, v92
	v_cvt_pk_bf16_f32 v129, v88, v89
	v_add_f32_e32 v158, v89, v158
	s_waitcnt lgkmcnt(3)
	v_mfma_f32_32x32x16_bf16 v[34:49], v[162:165], v[114:117], v[34:49]
	ds_read_b64_tr_b16 v[166:167], v189 offset:57344
	ds_read_b64_tr_b16 v[168:169], v189 offset:57856
	v_add_f32_e32 v154, v158, v90
	v_exp_f32_e32 v93, v93
	v_cvt_pk_bf16_f32 v122, v90, v91
	v_add_f32_e32 v154, v91, v154
	s_waitcnt lgkmcnt(4)
	v_mfma_f32_32x32x16_bf16 v[50:65], v[198:201], v[114:117], v[50:65]
	ds_read_b64_tr_b16 v[162:163], v189 offset:58368
	ds_read_b64_tr_b16 v[164:165], v189 offset:58880
	v_exp_f32_e32 v94, v94
	v_exp_f32_e32 v95, v95
	v_add_f32_e32 v154, v154, v92
	v_cvt_pk_bf16_f32 v123, v92, v93
	s_waitcnt lgkmcnt(5)
	v_mfma_f32_32x32x16_bf16 v[34:49], v[202:205], v[118:121], v[34:49]
	ds_read_b64_tr_b16 v[158:159], v189 offset:59392
	ds_read_b64_tr_b16 v[160:161], v189 offset:59904
	v_add_f32_e32 v154, v154, v93
	v_exp_f32_e32 v96, v96
	v_exp_f32_e32 v97, v97
	v_add_f32_e32 v193, v94, v154
	s_waitcnt lgkmcnt(6)
	v_mfma_f32_32x32x16_bf16 v[50:65], v[194:197], v[118:121], v[50:65]
	ds_read_b64_tr_b16 v[154:155], v189 offset:60416
	ds_read_b64_tr_b16 v[156:157], v189 offset:60928
	v_add_f32_e32 v125, v193, v95
	v_add_f32_e32 v193, v96, v125
	v_cvt_pk_bf16_f32 v124, v94, v95
	v_cvt_pk_bf16_f32 v125, v96, v97
	v_add_f32_e32 v193, v97, v193
	s_add_u32 s22, s22, 0x2000
	s_addc_u32 s23, s23, 0
	s_add_u32 s20, s20, 0x40000
	s_addc_u32 s21, s21, 0
	s_waitcnt vmcnt(6) lgkmcnt(0)
	s_barrier
	s_waitcnt lgkmcnt(6)
	v_mfma_f32_32x32x16_bf16 v[2:17], v[134:137], v[166:169], v[2:17]
	ds_read_b64_tr_b16 v[66:67], v189 offset:61440
	ds_read_b64_tr_b16 v[68:69], v189 offset:61952
	v_exp_f32_e32 v34, v34
	v_exp_f32_e32 v35, v35
	v_exp_f32_e32 v36, v36
	s_waitcnt lgkmcnt(6)
	v_mfma_f32_32x32x16_bf16 v[2:17], v[130:133], v[162:165], v[2:17]
	ds_read_b64_tr_b16 v[70:71], v189 offset:62464
	ds_read_b64_tr_b16 v[72:73], v189 offset:62976
	v_add_f32_e32 v74, v193, v34
	v_exp_f32_e32 v37, v37
	v_cvt_pk_bf16_f32 v150, v34, v35
	v_add_f32_e32 v78, v35, v74
	s_waitcnt lgkmcnt(6)
	v_mfma_f32_32x32x16_bf16 v[2:17], v[126:129], v[158:161], v[2:17]
	ds_read_b64_tr_b16 v[74:75], v189 offset:63488
	ds_read_b64_tr_b16 v[76:77], v189 offset:64000
	v_exp_f32_e32 v38, v38
	v_exp_f32_e32 v39, v39
	v_add_f32_e32 v82, v78, v36
	v_cvt_pk_bf16_f32 v151, v36, v37
	s_waitcnt lgkmcnt(6)
	v_mfma_f32_32x32x16_bf16 v[2:17], v[122:125], v[154:157], v[2:17]
	ds_read_b64_tr_b16 v[78:79], v189 offset:64512
	ds_read_b64_tr_b16 v[80:81], v189 offset:65024
	v_add_f32_e32 v82, v82, v37
	v_exp_f32_e32 v40, v40
	v_exp_f32_e32 v41, v41
	v_add_f32_e32 v86, v38, v82
	s_waitcnt lgkmcnt(6)
	v_mfma_f32_32x32x16_bf16 v[18:33], v[134:137], v[66:69], v[18:33]
	ds_read_b128 v[82:85], v182 offset:36864
	v_cvt_pk_bf16_f32 v152, v38, v39
	v_add_f32_e32 v90, v86, v39
	v_exp_f32_e32 v42, v42
	v_exp_f32_e32 v43, v43
	s_waitcnt lgkmcnt(5)
	v_mfma_f32_32x32x16_bf16 v[18:33], v[130:133], v[70:73], v[18:33]
	ds_read_b128 v[86:89], v182 offset:40960
	v_add_f32_e32 v66, v90, v40
	v_exp_f32_e32 v44, v44
	v_cvt_pk_bf16_f32 v153, v40, v41
	v_add_f32_e32 v66, v41, v66
	s_waitcnt lgkmcnt(4)
	v_mfma_f32_32x32x16_bf16 v[18:33], v[126:129], v[74:77], v[18:33]
	ds_read_b128 v[154:157], v183 offset:36864
	v_add_f32_e32 v66, v66, v42
	v_exp_f32_e32 v45, v45
	v_cvt_pk_bf16_f32 v146, v42, v43
	v_add_f32_e32 v66, v43, v66
	s_waitcnt lgkmcnt(3)
	v_mfma_f32_32x32x16_bf16 v[18:33], v[122:125], v[78:81], v[18:33]
	ds_read_b128 v[162:165], v183 offset:40960
	v_exp_f32_e32 v46, v46
	v_exp_f32_e32 v47, v47
	v_add_f32_e32 v66, v66, v44
	v_cvt_pk_bf16_f32 v147, v44, v45
	s_nop 0
	v_add_f32_e32 v66, v66, v45
	v_add_f32_e32 v91, v46, v66
	s_waitcnt lgkmcnt(3)
	v_mfma_f32_32x32x16_bf16 v[66:81], v[82:85], v[98:101], 0
	ds_read_b128 v[166:169], v184 offset:36864
	v_exp_f32_e32 v48, v48
	v_exp_f32_e32 v49, v49
	ds_read_b128 v[158:161], v184 offset:40960
	v_add_f32_e32 v193, v91, v47
	s_waitcnt lgkmcnt(4)
	v_mfma_f32_32x32x16_bf16 v[82:97], v[86:89], v[98:101], 0
	v_exp_f32_e32 v50, v50
	v_exp_f32_e32 v51, v51
	v_cvt_pk_bf16_f32 v148, v46, v47
	s_add_u32 s26, s20, 0xfffe0000
	s_addc_u32 s27, s21, -1
	s_add_i32 s31, 0x6000, s8
	s_add_i32 s33, 0x8000, s12
	s_add_u32 s28, s22, 0xfffff000
	s_addc_u32 s29, s23, -1
	s_add_i32 s40, s31, 0x2000
	s_nop 4
	s_mov_b32 s41, m0
	s_mov_b32 m0, s31
	s_nop 0
	global_load_lds_dwordx4 v174, s[26:27]
	s_mov_b32 m0, s40
	s_nop 0
	global_load_lds_dwordx4 v192, s[28:29]
	s_mov_b32 m0, s33
	s_nop 0
	global_load_lds_dwordx4 v191, s[26:27]
	s_mov_b32 m0, s41
	s_waitcnt lgkmcnt(3)
	v_mfma_f32_32x32x16_bf16 v[66:81], v[154:157], v[102:105], v[66:81]
	ds_read_b128 v[194:197], v185 offset:36864
	v_add_f32_e32 v193, v193, v48
	v_cvt_pk_bf16_f32 v149, v48, v49
	v_add_f32_e32 v193, v49, v193
	v_exp_f32_e32 v52, v52
	s_waitcnt lgkmcnt(3)
	v_mfma_f32_32x32x16_bf16 v[82:97], v[162:165], v[102:105], v[82:97]
	ds_read_b128 v[154:157], v185 offset:40960
	v_add_f32_e32 v193, v193, v50
	v_exp_f32_e32 v53, v53
	v_cvt_pk_bf16_f32 v142, v50, v51
	v_add_f32_e32 v193, v51, v193
	s_waitcnt lgkmcnt(3)
	v_mfma_f32_32x32x16_bf16 v[66:81], v[166:169], v[106:109], v[66:81]
	ds_read_b128 v[162:165], v187 offset:45056
	v_exp_f32_e32 v54, v54
	v_exp_f32_e32 v55, v55
	v_add_f32_e32 v193, v193, v52
	v_cvt_pk_bf16_f32 v143, v52, v53
	s_waitcnt lgkmcnt(3)
	v_mfma_f32_32x32x16_bf16 v[82:97], v[158:161], v[106:109], v[82:97]
	ds_read_b128 v[198:201], v187 offset:47104
	v_add_f32_e32 v166, v193, v53
	v_exp_f32_e32 v56, v56
	v_exp_f32_e32 v57, v57
	v_add_f32_e32 v166, v54, v166
	s_waitcnt lgkmcnt(3)
	v_mfma_f32_32x32x16_bf16 v[66:81], v[194:197], v[110:113], v[66:81]
	ds_read_b128 v[202:205], v188 offset:45056
	v_cvt_pk_bf16_f32 v144, v54, v55
	v_add_f32_e32 v159, v166, v55
	v_exp_f32_e32 v58, v58
	v_exp_f32_e32 v59, v59
	s_waitcnt lgkmcnt(3)
	v_mfma_f32_32x32x16_bf16 v[82:97], v[154:157], v[110:113], v[82:97]
	ds_read_b128 v[194:197], v188 offset:47104
	v_add_f32_e32 v158, v159, v56
	v_exp_f32_e32 v60, v60
	v_cvt_pk_bf16_f32 v145, v56, v57
	v_add_f32_e32 v158, v57, v158
	s_waitcnt lgkmcnt(3)
	v_mfma_f32_32x32x16_bf16 v[66:81], v[162:165], v[114:117], v[66:81]
	ds_read_b64_tr_b16 v[166:167], v189 offset:16384
	ds_read_b64_tr_b16 v[168:169], v189 offset:16896
	v_add_f32_e32 v154, v158, v58
	v_exp_f32_e32 v61, v61
	v_cvt_pk_bf16_f32 v138, v58, v59
	v_add_f32_e32 v154, v59, v154
	s_waitcnt lgkmcnt(4)
	v_mfma_f32_32x32x16_bf16 v[82:97], v[198:201], v[114:117], v[82:97]
	ds_read_b64_tr_b16 v[162:163], v189 offset:17408
	ds_read_b64_tr_b16 v[164:165], v189 offset:17920
	v_exp_f32_e32 v62, v62
	v_exp_f32_e32 v63, v63
	v_add_f32_e32 v154, v154, v60
	v_cvt_pk_bf16_f32 v139, v60, v61
	s_waitcnt lgkmcnt(5)
	v_mfma_f32_32x32x16_bf16 v[66:81], v[202:205], v[118:121], v[66:81]
	ds_read_b64_tr_b16 v[158:159], v189 offset:18432
	ds_read_b64_tr_b16 v[160:161], v189 offset:18944
	v_add_f32_e32 v154, v154, v61
	v_exp_f32_e32 v64, v64
	v_exp_f32_e32 v65, v65
	v_add_f32_e32 v198, v62, v154
	s_waitcnt lgkmcnt(6)
	v_mfma_f32_32x32x16_bf16 v[82:97], v[194:197], v[118:121], v[82:97]
	ds_read_b64_tr_b16 v[154:155], v189 offset:19456
	ds_read_b64_tr_b16 v[156:157], v189 offset:19968
	v_add_f32_e32 v141, v198, v63
	v_add_f32_e32 v198, v64, v141
	v_cvt_pk_bf16_f32 v140, v62, v63
	v_cvt_pk_bf16_f32 v141, v64, v65
	v_add_f32_e32 v194, v65, v198
	s_waitcnt vmcnt(6) lgkmcnt(0)
	s_barrier
	s_waitcnt lgkmcnt(6)
	v_mfma_f32_32x32x16_bf16 v[2:17], v[150:153], v[166:169], v[2:17]
	ds_read_b64_tr_b16 v[34:35], v189 offset:20480
	ds_read_b64_tr_b16 v[36:37], v189 offset:20992
	v_exp_f32_e32 v66, v66
	v_exp_f32_e32 v67, v67
	v_exp_f32_e32 v68, v68
	s_waitcnt lgkmcnt(6)
	v_mfma_f32_32x32x16_bf16 v[2:17], v[146:149], v[162:165], v[2:17]
	ds_read_b64_tr_b16 v[38:39], v189 offset:21504
	ds_read_b64_tr_b16 v[40:41], v189 offset:22016
	v_add_f32_e32 v42, v194, v66
	v_exp_f32_e32 v69, v69
	v_cvt_pk_bf16_f32 v134, v66, v67
	v_add_f32_e32 v46, v67, v42
	s_waitcnt lgkmcnt(6)
	v_mfma_f32_32x32x16_bf16 v[2:17], v[142:145], v[158:161], v[2:17]
	ds_read_b64_tr_b16 v[42:43], v189 offset:22528
	ds_read_b64_tr_b16 v[44:45], v189 offset:23040
	v_exp_f32_e32 v70, v70
	v_exp_f32_e32 v71, v71
	v_add_f32_e32 v50, v46, v68
	v_cvt_pk_bf16_f32 v135, v68, v69
	s_waitcnt lgkmcnt(6)
	v_mfma_f32_32x32x16_bf16 v[2:17], v[138:141], v[154:157], v[2:17]
	ds_read_b64_tr_b16 v[46:47], v189 offset:23552
	ds_read_b64_tr_b16 v[48:49], v189 offset:24064
	v_add_f32_e32 v50, v50, v69
	v_exp_f32_e32 v72, v72
	v_exp_f32_e32 v73, v73
	v_add_f32_e32 v54, v70, v50
	s_waitcnt lgkmcnt(6)
	v_mfma_f32_32x32x16_bf16 v[18:33], v[150:153], v[34:37], v[18:33]
	ds_read_b128 v[50:53], v182
	v_cvt_pk_bf16_f32 v136, v70, v71
	v_add_f32_e32 v58, v54, v71
	v_exp_f32_e32 v74, v74
	v_exp_f32_e32 v75, v75
	s_waitcnt lgkmcnt(5)
	v_mfma_f32_32x32x16_bf16 v[18:33], v[146:149], v[38:41], v[18:33]
	ds_read_b128 v[54:57], v182 offset:4096
	v_add_f32_e32 v34, v58, v72
	v_exp_f32_e32 v76, v76
	v_cvt_pk_bf16_f32 v137, v72, v73
	v_add_f32_e32 v34, v73, v34
	s_waitcnt lgkmcnt(4)
	v_mfma_f32_32x32x16_bf16 v[18:33], v[142:145], v[42:45], v[18:33]
	ds_read_b128 v[154:157], v183
	v_add_f32_e32 v34, v34, v74
	v_exp_f32_e32 v77, v77
	v_cvt_pk_bf16_f32 v130, v74, v75
	v_add_f32_e32 v34, v75, v34
	s_waitcnt lgkmcnt(3)
	v_mfma_f32_32x32x16_bf16 v[18:33], v[138:141], v[46:49], v[18:33]
	ds_read_b128 v[162:165], v183 offset:4096
	v_exp_f32_e32 v78, v78
	v_exp_f32_e32 v79, v79
	v_add_f32_e32 v34, v34, v76
	v_cvt_pk_bf16_f32 v131, v76, v77
	s_nop 0
	v_add_f32_e32 v34, v34, v77
	v_add_f32_e32 v59, v78, v34
	s_waitcnt lgkmcnt(3)
	v_mfma_f32_32x32x16_bf16 v[34:49], v[50:53], v[98:101], 0
	ds_read_b128 v[166:169], v184
	v_exp_f32_e32 v80, v80
	v_exp_f32_e32 v81, v81
	ds_read_b128 v[158:161], v184 offset:4096
	v_add_f32_e32 v193, v59, v79
	s_waitcnt lgkmcnt(4)
	v_mfma_f32_32x32x16_bf16 v[50:65], v[54:57], v[98:101], 0
	v_exp_f32_e32 v82, v82
	v_exp_f32_e32 v83, v83
	v_cvt_pk_bf16_f32 v132, v78, v79
	s_add_i32 s26, 0x9000, s8
	s_add_i32 s28, 0xa000, s12
	s_add_i32 s24, s26, 0x2000
	s_nop 4
	s_mov_b32 s25, m0
	s_mov_b32 m0, s26
	s_nop 0
	global_load_lds_dwordx4 v174, s[20:21]
	s_mov_b32 m0, s24
	s_nop 0
	global_load_lds_dwordx4 v192, s[22:23]
	s_mov_b32 m0, s28
	s_nop 0
	global_load_lds_dwordx4 v191, s[20:21]
	s_mov_b32 m0, s25
	s_waitcnt lgkmcnt(3)
	v_mfma_f32_32x32x16_bf16 v[34:49], v[154:157], v[102:105], v[34:49]
	ds_read_b128 v[194:197], v185
	v_add_f32_e32 v154, v193, v80
	v_exp_f32_e32 v84, v84
	v_cvt_pk_bf16_f32 v133, v80, v81
	v_add_f32_e32 v193, v81, v154
	s_waitcnt lgkmcnt(3)
	v_mfma_f32_32x32x16_bf16 v[50:65], v[162:165], v[102:105], v[50:65]
	ds_read_b128 v[154:157], v185 offset:4096
	v_add_f32_e32 v193, v193, v82
	v_exp_f32_e32 v85, v85
	v_cvt_pk_bf16_f32 v126, v82, v83
	v_add_f32_e32 v193, v83, v193
	s_waitcnt lgkmcnt(3)
	v_mfma_f32_32x32x16_bf16 v[34:49], v[166:169], v[106:109], v[34:49]
	ds_read_b128 v[162:165], v187 offset:8192
	v_exp_f32_e32 v86, v86
	v_exp_f32_e32 v87, v87
	v_add_f32_e32 v193, v193, v84
	v_cvt_pk_bf16_f32 v127, v84, v85
	s_waitcnt lgkmcnt(3)
	v_mfma_f32_32x32x16_bf16 v[50:65], v[158:161], v[106:109], v[50:65]
	ds_read_b128 v[198:201], v187 offset:10240
	v_add_f32_e32 v166, v193, v85
	v_exp_f32_e32 v88, v88
	v_exp_f32_e32 v89, v89
	v_add_f32_e32 v166, v86, v166
	s_waitcnt lgkmcnt(3)
	v_mfma_f32_32x32x16_bf16 v[34:49], v[194:197], v[110:113], v[34:49]
	ds_read_b128 v[202:205], v188 offset:8192
	v_cvt_pk_bf16_f32 v128, v86, v87
	v_add_f32_e32 v159, v166, v87
	v_exp_f32_e32 v90, v90
	v_exp_f32_e32 v91, v91
	s_waitcnt lgkmcnt(3)
	v_mfma_f32_32x32x16_bf16 v[50:65], v[154:157], v[110:113], v[50:65]
	ds_read_b128 v[194:197], v188 offset:10240
	v_add_f32_e32 v158, v159, v88
	v_exp_f32_e32 v92, v92
	v_cvt_pk_bf16_f32 v129, v88, v89
	v_add_f32_e32 v158, v89, v158
	s_waitcnt lgkmcnt(3)
	v_mfma_f32_32x32x16_bf16 v[34:49], v[162:165], v[114:117], v[34:49]
	ds_read_b64_tr_b16 v[166:167], v189 offset:24576
	ds_read_b64_tr_b16 v[168:169], v189 offset:25088
	v_add_f32_e32 v154, v158, v90
	v_exp_f32_e32 v93, v93
	v_cvt_pk_bf16_f32 v122, v90, v91
	v_add_f32_e32 v154, v91, v154
	s_waitcnt lgkmcnt(4)
	v_mfma_f32_32x32x16_bf16 v[50:65], v[198:201], v[114:117], v[50:65]
	ds_read_b64_tr_b16 v[162:163], v189 offset:25600
	ds_read_b64_tr_b16 v[164:165], v189 offset:26112
	v_exp_f32_e32 v94, v94
	v_exp_f32_e32 v95, v95
	v_add_f32_e32 v154, v154, v92
	v_cvt_pk_bf16_f32 v123, v92, v93
	s_waitcnt lgkmcnt(5)
	v_mfma_f32_32x32x16_bf16 v[34:49], v[202:205], v[118:121], v[34:49]
	ds_read_b64_tr_b16 v[158:159], v189 offset:26624
	ds_read_b64_tr_b16 v[160:161], v189 offset:27136
	v_add_f32_e32 v154, v154, v93
	v_exp_f32_e32 v96, v96
	v_exp_f32_e32 v97, v97
	v_add_f32_e32 v193, v94, v154
	s_waitcnt lgkmcnt(6)
	v_mfma_f32_32x32x16_bf16 v[50:65], v[194:197], v[118:121], v[50:65]
	ds_read_b64_tr_b16 v[154:155], v189 offset:27648
	ds_read_b64_tr_b16 v[156:157], v189 offset:28160
	v_add_f32_e32 v125, v193, v95
	v_add_f32_e32 v193, v96, v125
	v_cvt_pk_bf16_f32 v124, v94, v95
	v_cvt_pk_bf16_f32 v125, v96, v97
	v_add_f32_e32 v193, v97, v193
	s_add_u32 s22, s22, 0x2000
	s_addc_u32 s23, s23, 0
	s_add_u32 s20, s20, 0x40000
	s_addc_u32 s21, s21, 0
	s_waitcnt vmcnt(6) lgkmcnt(0)
	s_barrier
	s_waitcnt lgkmcnt(6)
	v_mfma_f32_32x32x16_bf16 v[2:17], v[134:137], v[166:169], v[2:17]
	ds_read_b64_tr_b16 v[66:67], v189 offset:28672
	ds_read_b64_tr_b16 v[68:69], v189 offset:29184
	v_exp_f32_e32 v34, v34
	v_exp_f32_e32 v35, v35
	v_exp_f32_e32 v36, v36
	s_waitcnt lgkmcnt(6)
	v_mfma_f32_32x32x16_bf16 v[2:17], v[130:133], v[162:165], v[2:17]
	ds_read_b64_tr_b16 v[70:71], v189 offset:29696
	ds_read_b64_tr_b16 v[72:73], v189 offset:30208
	v_add_f32_e32 v74, v193, v34
	v_exp_f32_e32 v37, v37
	v_cvt_pk_bf16_f32 v150, v34, v35
	v_add_f32_e32 v78, v35, v74
	s_waitcnt lgkmcnt(6)
	v_mfma_f32_32x32x16_bf16 v[2:17], v[126:129], v[158:161], v[2:17]
	ds_read_b64_tr_b16 v[74:75], v189 offset:30720
	ds_read_b64_tr_b16 v[76:77], v189 offset:31232
	v_exp_f32_e32 v38, v38
	v_exp_f32_e32 v39, v39
	v_add_f32_e32 v82, v78, v36
	v_cvt_pk_bf16_f32 v151, v36, v37
	s_waitcnt lgkmcnt(6)
	v_mfma_f32_32x32x16_bf16 v[2:17], v[122:125], v[154:157], v[2:17]
	ds_read_b64_tr_b16 v[78:79], v189 offset:31744
	ds_read_b64_tr_b16 v[80:81], v189 offset:32256
	v_add_f32_e32 v82, v82, v37
	v_exp_f32_e32 v40, v40
	v_exp_f32_e32 v41, v41
	v_add_f32_e32 v86, v38, v82
	s_waitcnt lgkmcnt(6)
	v_mfma_f32_32x32x16_bf16 v[18:33], v[134:137], v[66:69], v[18:33]
	ds_read_b128 v[82:85], v182 offset:12288
	v_cvt_pk_bf16_f32 v152, v38, v39
	v_add_f32_e32 v90, v86, v39
	v_exp_f32_e32 v42, v42
	v_exp_f32_e32 v43, v43
	s_waitcnt lgkmcnt(5)
	v_mfma_f32_32x32x16_bf16 v[18:33], v[130:133], v[70:73], v[18:33]
	ds_read_b128 v[86:89], v182 offset:16384
	v_add_f32_e32 v66, v90, v40
	v_exp_f32_e32 v44, v44
	v_cvt_pk_bf16_f32 v153, v40, v41
	v_add_f32_e32 v66, v41, v66
	s_waitcnt lgkmcnt(4)
	v_mfma_f32_32x32x16_bf16 v[18:33], v[126:129], v[74:77], v[18:33]
	ds_read_b128 v[154:157], v183 offset:12288
	v_add_f32_e32 v66, v66, v42
	v_exp_f32_e32 v45, v45
	v_cvt_pk_bf16_f32 v146, v42, v43
	v_add_f32_e32 v66, v43, v66
	s_waitcnt lgkmcnt(3)
	v_mfma_f32_32x32x16_bf16 v[18:33], v[122:125], v[78:81], v[18:33]
	ds_read_b128 v[162:165], v183 offset:16384
	v_exp_f32_e32 v46, v46
	v_exp_f32_e32 v47, v47
	v_add_f32_e32 v66, v66, v44
	v_cvt_pk_bf16_f32 v147, v44, v45
	s_nop 0
	v_add_f32_e32 v66, v66, v45
	v_add_f32_e32 v91, v46, v66
	s_waitcnt lgkmcnt(3)
	v_mfma_f32_32x32x16_bf16 v[66:81], v[82:85], v[98:101], 0
	ds_read_b128 v[166:169], v184 offset:12288
	v_exp_f32_e32 v48, v48
	v_exp_f32_e32 v49, v49
	ds_read_b128 v[158:161], v184 offset:16384
	v_add_f32_e32 v193, v91, v47
	s_waitcnt lgkmcnt(4)
	v_mfma_f32_32x32x16_bf16 v[82:97], v[86:89], v[98:101], 0
	v_exp_f32_e32 v50, v50
	v_exp_f32_e32 v51, v51
	v_cvt_pk_bf16_f32 v148, v46, v47
	s_add_u32 s26, s20, 0xfffe0000
	s_addc_u32 s27, s21, -1
	s_add_i32 s31, 0, s8
	s_add_i32 s33, 0, s12
	s_add_u32 s28, s22, 0xfffff000
	s_addc_u32 s29, s23, -1
	s_add_i32 s40, s31, 0x2000
	s_nop 4
	s_mov_b32 s41, m0
	s_mov_b32 m0, s31
	s_nop 0
	global_load_lds_dwordx4 v174, s[26:27]
	s_mov_b32 m0, s40
	s_nop 0
	global_load_lds_dwordx4 v192, s[28:29]
	s_mov_b32 m0, s33
	s_nop 0
	global_load_lds_dwordx4 v191, s[26:27]
	s_mov_b32 m0, s41
	s_waitcnt lgkmcnt(3)
	v_mfma_f32_32x32x16_bf16 v[66:81], v[154:157], v[102:105], v[66:81]
	ds_read_b128 v[194:197], v185 offset:12288
	v_add_f32_e32 v193, v193, v48
	v_cvt_pk_bf16_f32 v149, v48, v49
	v_add_f32_e32 v193, v49, v193
	v_exp_f32_e32 v52, v52
	s_waitcnt lgkmcnt(3)
	v_mfma_f32_32x32x16_bf16 v[82:97], v[162:165], v[102:105], v[82:97]
	ds_read_b128 v[154:157], v185 offset:16384
	v_add_f32_e32 v193, v193, v50
	v_exp_f32_e32 v53, v53
	v_cvt_pk_bf16_f32 v142, v50, v51
	v_add_f32_e32 v193, v51, v193
	s_waitcnt lgkmcnt(3)
	v_mfma_f32_32x32x16_bf16 v[66:81], v[166:169], v[106:109], v[66:81]
	ds_read_b128 v[162:165], v187 offset:20480
	v_exp_f32_e32 v54, v54
	v_exp_f32_e32 v55, v55
	v_add_f32_e32 v193, v193, v52
	v_cvt_pk_bf16_f32 v143, v52, v53
	s_waitcnt lgkmcnt(3)
	v_mfma_f32_32x32x16_bf16 v[82:97], v[158:161], v[106:109], v[82:97]
	ds_read_b128 v[198:201], v187 offset:22528
	v_add_f32_e32 v166, v193, v53
	v_exp_f32_e32 v56, v56
	v_exp_f32_e32 v57, v57
	v_add_f32_e32 v166, v54, v166
	s_waitcnt lgkmcnt(3)
	v_mfma_f32_32x32x16_bf16 v[66:81], v[194:197], v[110:113], v[66:81]
	ds_read_b128 v[202:205], v188 offset:20480
	v_cvt_pk_bf16_f32 v144, v54, v55
	v_add_f32_e32 v159, v166, v55
	v_exp_f32_e32 v58, v58
	v_exp_f32_e32 v59, v59
	s_waitcnt lgkmcnt(3)
	v_mfma_f32_32x32x16_bf16 v[82:97], v[154:157], v[110:113], v[82:97]
	ds_read_b128 v[194:197], v188 offset:22528
	v_add_f32_e32 v158, v159, v56
	v_exp_f32_e32 v60, v60
	v_cvt_pk_bf16_f32 v145, v56, v57
	v_add_f32_e32 v158, v57, v158
	s_waitcnt lgkmcnt(3)
	v_mfma_f32_32x32x16_bf16 v[66:81], v[162:165], v[114:117], v[66:81]
	ds_read_b64_tr_b16 v[166:167], v189 offset:32768
	ds_read_b64_tr_b16 v[168:169], v189 offset:33280
	v_add_f32_e32 v154, v158, v58
	v_exp_f32_e32 v61, v61
	v_cvt_pk_bf16_f32 v138, v58, v59
	v_add_f32_e32 v154, v59, v154
	s_waitcnt lgkmcnt(4)
	v_mfma_f32_32x32x16_bf16 v[82:97], v[198:201], v[114:117], v[82:97]
	ds_read_b64_tr_b16 v[162:163], v189 offset:33792
	ds_read_b64_tr_b16 v[164:165], v189 offset:34304
	v_exp_f32_e32 v62, v62
	v_exp_f32_e32 v63, v63
	v_add_f32_e32 v154, v154, v60
	v_cvt_pk_bf16_f32 v139, v60, v61
	s_waitcnt lgkmcnt(5)
	v_mfma_f32_32x32x16_bf16 v[66:81], v[202:205], v[118:121], v[66:81]
	ds_read_b64_tr_b16 v[158:159], v189 offset:34816
	ds_read_b64_tr_b16 v[160:161], v189 offset:35328
	v_add_f32_e32 v154, v154, v61
	v_exp_f32_e32 v64, v64
	v_exp_f32_e32 v65, v65
	v_add_f32_e32 v198, v62, v154
	s_waitcnt lgkmcnt(6)
	v_mfma_f32_32x32x16_bf16 v[82:97], v[194:197], v[118:121], v[82:97]
	ds_read_b64_tr_b16 v[154:155], v189 offset:35840
	ds_read_b64_tr_b16 v[156:157], v189 offset:36352
	v_add_f32_e32 v141, v198, v63
	v_add_f32_e32 v198, v64, v141
	v_cvt_pk_bf16_f32 v140, v62, v63
	v_cvt_pk_bf16_f32 v141, v64, v65
	v_add_f32_e32 v194, v65, v198
	s_waitcnt vmcnt(6) lgkmcnt(0)
	s_barrier
	s_waitcnt lgkmcnt(6)
	v_mfma_f32_32x32x16_bf16 v[2:17], v[150:153], v[166:169], v[2:17]
	ds_read_b64_tr_b16 v[34:35], v189 offset:36864
	ds_read_b64_tr_b16 v[36:37], v189 offset:37376
	v_exp_f32_e32 v66, v66
	v_exp_f32_e32 v67, v67
	v_exp_f32_e32 v68, v68
	s_waitcnt lgkmcnt(6)
	v_mfma_f32_32x32x16_bf16 v[2:17], v[146:149], v[162:165], v[2:17]
	ds_read_b64_tr_b16 v[38:39], v189 offset:37888
	ds_read_b64_tr_b16 v[40:41], v189 offset:38400
	v_add_f32_e32 v42, v194, v66
	v_exp_f32_e32 v69, v69
	v_cvt_pk_bf16_f32 v134, v66, v67
	v_add_f32_e32 v46, v67, v42
	s_waitcnt lgkmcnt(6)
	v_mfma_f32_32x32x16_bf16 v[2:17], v[142:145], v[158:161], v[2:17]
	ds_read_b64_tr_b16 v[42:43], v189 offset:38912
	ds_read_b64_tr_b16 v[44:45], v189 offset:39424
	v_exp_f32_e32 v70, v70
	v_exp_f32_e32 v71, v71
	v_add_f32_e32 v50, v46, v68
	v_cvt_pk_bf16_f32 v135, v68, v69
	s_waitcnt lgkmcnt(6)
	v_mfma_f32_32x32x16_bf16 v[2:17], v[138:141], v[154:157], v[2:17]
	ds_read_b64_tr_b16 v[46:47], v189 offset:39936
	ds_read_b64_tr_b16 v[48:49], v189 offset:40448
	v_add_f32_e32 v50, v50, v69
	v_exp_f32_e32 v72, v72
	v_exp_f32_e32 v73, v73
	v_add_f32_e32 v54, v70, v50
	s_waitcnt lgkmcnt(6)
	v_mfma_f32_32x32x16_bf16 v[18:33], v[150:153], v[34:37], v[18:33]
	ds_read_b128 v[50:53], v182 offset:24576
	v_cvt_pk_bf16_f32 v136, v70, v71
	v_add_f32_e32 v58, v54, v71
	v_exp_f32_e32 v74, v74
	v_exp_f32_e32 v75, v75
	s_waitcnt lgkmcnt(5)
	v_mfma_f32_32x32x16_bf16 v[18:33], v[146:149], v[38:41], v[18:33]
	ds_read_b128 v[54:57], v182 offset:28672
	v_add_f32_e32 v34, v58, v72
	v_exp_f32_e32 v76, v76
	v_cvt_pk_bf16_f32 v137, v72, v73
	v_add_f32_e32 v34, v73, v34
	s_waitcnt lgkmcnt(4)
	v_mfma_f32_32x32x16_bf16 v[18:33], v[142:145], v[42:45], v[18:33]
	ds_read_b128 v[154:157], v183 offset:24576
	v_add_f32_e32 v34, v34, v74
	v_exp_f32_e32 v77, v77
	v_cvt_pk_bf16_f32 v130, v74, v75
	v_add_f32_e32 v34, v75, v34
	s_waitcnt lgkmcnt(3)
	v_mfma_f32_32x32x16_bf16 v[18:33], v[138:141], v[46:49], v[18:33]
	ds_read_b128 v[162:165], v183 offset:28672
	v_exp_f32_e32 v78, v78
	v_exp_f32_e32 v79, v79
	v_add_f32_e32 v34, v34, v76
	v_cvt_pk_bf16_f32 v131, v76, v77
	s_nop 0
	v_add_f32_e32 v34, v34, v77
	v_add_f32_e32 v59, v78, v34
	s_waitcnt lgkmcnt(3)
	v_mfma_f32_32x32x16_bf16 v[34:49], v[50:53], v[98:101], 0
	ds_read_b128 v[166:169], v184 offset:24576
	v_exp_f32_e32 v80, v80
	v_exp_f32_e32 v81, v81
	ds_read_b128 v[158:161], v184 offset:28672
	v_add_f32_e32 v193, v59, v79
	s_waitcnt lgkmcnt(4)
	v_mfma_f32_32x32x16_bf16 v[50:65], v[54:57], v[98:101], 0
	v_exp_f32_e32 v82, v82
	v_exp_f32_e32 v83, v83
	v_cvt_pk_bf16_f32 v132, v78, v79
	s_add_i32 s26, 0x3000, s8
	s_add_i32 s28, 0x2000, s12
	s_add_i32 s24, s26, 0x2000
	s_nop 4
	s_mov_b32 s25, m0
	s_mov_b32 m0, s26
	s_nop 0
	global_load_lds_dwordx4 v174, s[20:21]
	s_mov_b32 m0, s24
	s_nop 0
	global_load_lds_dwordx4 v192, s[22:23]
	s_mov_b32 m0, s28
	s_nop 0
	global_load_lds_dwordx4 v191, s[20:21]
	s_mov_b32 m0, s25
	s_waitcnt lgkmcnt(3)
	v_mfma_f32_32x32x16_bf16 v[34:49], v[154:157], v[102:105], v[34:49]
	ds_read_b128 v[194:197], v185 offset:24576
	v_add_f32_e32 v154, v193, v80
	v_exp_f32_e32 v84, v84
	v_cvt_pk_bf16_f32 v133, v80, v81
	v_add_f32_e32 v193, v81, v154
	s_waitcnt lgkmcnt(3)
	v_mfma_f32_32x32x16_bf16 v[50:65], v[162:165], v[102:105], v[50:65]
	ds_read_b128 v[154:157], v185 offset:28672
	v_add_f32_e32 v193, v193, v82
	v_exp_f32_e32 v85, v85
	v_cvt_pk_bf16_f32 v126, v82, v83
	v_add_f32_e32 v193, v83, v193
	s_waitcnt lgkmcnt(3)
	v_mfma_f32_32x32x16_bf16 v[34:49], v[166:169], v[106:109], v[34:49]
	ds_read_b128 v[162:165], v187 offset:32768
	v_exp_f32_e32 v86, v86
	v_exp_f32_e32 v87, v87
	v_add_f32_e32 v193, v193, v84
	v_cvt_pk_bf16_f32 v127, v84, v85
	s_waitcnt lgkmcnt(3)
	v_mfma_f32_32x32x16_bf16 v[50:65], v[158:161], v[106:109], v[50:65]
	ds_read_b128 v[198:201], v187 offset:34816
	v_add_f32_e32 v166, v193, v85
	v_exp_f32_e32 v88, v88
	v_exp_f32_e32 v89, v89
	v_add_f32_e32 v166, v86, v166
	s_waitcnt lgkmcnt(3)
	v_mfma_f32_32x32x16_bf16 v[34:49], v[194:197], v[110:113], v[34:49]
	ds_read_b128 v[202:205], v188 offset:32768
	v_cvt_pk_bf16_f32 v128, v86, v87
	v_add_f32_e32 v159, v166, v87
	v_exp_f32_e32 v90, v90
	v_exp_f32_e32 v91, v91
	s_waitcnt lgkmcnt(3)
	v_mfma_f32_32x32x16_bf16 v[50:65], v[154:157], v[110:113], v[50:65]
	ds_read_b128 v[194:197], v188 offset:34816
	v_add_f32_e32 v158, v159, v88
	v_exp_f32_e32 v92, v92
	v_cvt_pk_bf16_f32 v129, v88, v89
	v_add_f32_e32 v158, v89, v158
	s_waitcnt lgkmcnt(3)
	v_mfma_f32_32x32x16_bf16 v[34:49], v[162:165], v[114:117], v[34:49]
	ds_read_b64_tr_b16 v[166:167], v189 offset:40960
	ds_read_b64_tr_b16 v[168:169], v189 offset:41472
	v_add_f32_e32 v154, v158, v90
	v_exp_f32_e32 v93, v93
	v_cvt_pk_bf16_f32 v122, v90, v91
	v_add_f32_e32 v154, v91, v154
	s_waitcnt lgkmcnt(4)
	v_mfma_f32_32x32x16_bf16 v[50:65], v[198:201], v[114:117], v[50:65]
	ds_read_b64_tr_b16 v[162:163], v189 offset:41984
	ds_read_b64_tr_b16 v[164:165], v189 offset:42496
	v_exp_f32_e32 v94, v94
	v_exp_f32_e32 v95, v95
	v_add_f32_e32 v154, v154, v92
	v_cvt_pk_bf16_f32 v123, v92, v93
	s_waitcnt lgkmcnt(5)
	v_mfma_f32_32x32x16_bf16 v[34:49], v[202:205], v[118:121], v[34:49]
	ds_read_b64_tr_b16 v[158:159], v189 offset:43008
	ds_read_b64_tr_b16 v[160:161], v189 offset:43520
	v_add_f32_e32 v154, v154, v93
	v_exp_f32_e32 v96, v96
	v_exp_f32_e32 v97, v97
	v_add_f32_e32 v193, v94, v154
	s_waitcnt lgkmcnt(6)
	v_mfma_f32_32x32x16_bf16 v[50:65], v[194:197], v[118:121], v[50:65]
	ds_read_b64_tr_b16 v[154:155], v189 offset:44032
	ds_read_b64_tr_b16 v[156:157], v189 offset:44544
	v_add_f32_e32 v125, v193, v95
	v_add_f32_e32 v193, v96, v125
	v_cvt_pk_bf16_f32 v124, v94, v95
	v_cvt_pk_bf16_f32 v125, v96, v97
	v_add_f32_e32 v193, v97, v193
	s_add_u32 s22, s22, 0x2000
	s_addc_u32 s23, s23, 0
	s_add_u32 s20, s20, 0x40000
	s_addc_u32 s21, s21, 0
	s_waitcnt vmcnt(6) lgkmcnt(0)
	s_barrier
	s_waitcnt lgkmcnt(6)
	v_mfma_f32_32x32x16_bf16 v[2:17], v[134:137], v[166:169], v[2:17]
	ds_read_b64_tr_b16 v[66:67], v189 offset:45056
	ds_read_b64_tr_b16 v[68:69], v189 offset:45568
	v_exp_f32_e32 v34, v34
	v_exp_f32_e32 v35, v35
	v_exp_f32_e32 v36, v36
	s_waitcnt lgkmcnt(6)
	v_mfma_f32_32x32x16_bf16 v[2:17], v[130:133], v[162:165], v[2:17]
	ds_read_b64_tr_b16 v[70:71], v189 offset:46080
	ds_read_b64_tr_b16 v[72:73], v189 offset:46592
	v_add_f32_e32 v74, v193, v34
	v_exp_f32_e32 v37, v37
	v_cvt_pk_bf16_f32 v150, v34, v35
	v_add_f32_e32 v78, v35, v74
	s_waitcnt lgkmcnt(6)
	v_mfma_f32_32x32x16_bf16 v[2:17], v[126:129], v[158:161], v[2:17]
	ds_read_b64_tr_b16 v[74:75], v189 offset:47104
	ds_read_b64_tr_b16 v[76:77], v189 offset:47616
	v_exp_f32_e32 v38, v38
	v_exp_f32_e32 v39, v39
	v_add_f32_e32 v82, v78, v36
	v_cvt_pk_bf16_f32 v151, v36, v37
	s_waitcnt lgkmcnt(6)
	v_mfma_f32_32x32x16_bf16 v[2:17], v[122:125], v[154:157], v[2:17]
	ds_read_b64_tr_b16 v[78:79], v189 offset:48128
	ds_read_b64_tr_b16 v[80:81], v189 offset:48640
	v_add_f32_e32 v82, v82, v37
	v_exp_f32_e32 v40, v40
	v_exp_f32_e32 v41, v41
	v_add_f32_e32 v86, v38, v82
	s_waitcnt lgkmcnt(6)
	v_mfma_f32_32x32x16_bf16 v[18:33], v[134:137], v[66:69], v[18:33]
	ds_read_b128 v[82:85], v182 offset:36864
	v_cvt_pk_bf16_f32 v152, v38, v39
	v_add_f32_e32 v90, v86, v39
	v_exp_f32_e32 v42, v42
	v_exp_f32_e32 v43, v43
	s_waitcnt lgkmcnt(5)
	v_mfma_f32_32x32x16_bf16 v[18:33], v[130:133], v[70:73], v[18:33]
	ds_read_b128 v[86:89], v182 offset:40960
	v_add_f32_e32 v66, v90, v40
	v_exp_f32_e32 v44, v44
	v_cvt_pk_bf16_f32 v153, v40, v41
	v_add_f32_e32 v66, v41, v66
	s_waitcnt lgkmcnt(4)
	v_mfma_f32_32x32x16_bf16 v[18:33], v[126:129], v[74:77], v[18:33]
	ds_read_b128 v[154:157], v183 offset:36864
	v_add_f32_e32 v66, v66, v42
	v_exp_f32_e32 v45, v45
	v_cvt_pk_bf16_f32 v146, v42, v43
	v_add_f32_e32 v66, v43, v66
	s_waitcnt lgkmcnt(3)
	v_mfma_f32_32x32x16_bf16 v[18:33], v[122:125], v[78:81], v[18:33]
	ds_read_b128 v[162:165], v183 offset:40960
	v_exp_f32_e32 v46, v46
	v_exp_f32_e32 v47, v47
	v_add_f32_e32 v66, v66, v44
	v_cvt_pk_bf16_f32 v147, v44, v45
	s_nop 0
	v_add_f32_e32 v66, v66, v45
	v_add_f32_e32 v91, v46, v66
	s_waitcnt lgkmcnt(3)
	v_mfma_f32_32x32x16_bf16 v[66:81], v[82:85], v[98:101], 0
	ds_read_b128 v[166:169], v184 offset:36864
	v_exp_f32_e32 v48, v48
	v_exp_f32_e32 v49, v49
	ds_read_b128 v[158:161], v184 offset:40960
	v_add_f32_e32 v193, v91, v47
	s_waitcnt lgkmcnt(4)
	v_mfma_f32_32x32x16_bf16 v[82:97], v[86:89], v[98:101], 0
	v_exp_f32_e32 v50, v50
	v_exp_f32_e32 v51, v51
	v_cvt_pk_bf16_f32 v148, v46, v47
	s_add_u32 s26, s20, 0xfffe0000
	s_addc_u32 s27, s21, -1
	s_add_i32 s31, 0x6000, s8
	s_add_i32 s33, 0x4000, s12
	s_add_u32 s28, s22, 0xfffff000
	s_addc_u32 s29, s23, -1
	s_add_i32 s40, s31, 0x2000
	s_nop 4
	s_mov_b32 s41, m0
	s_mov_b32 m0, s31
	s_nop 0
	global_load_lds_dwordx4 v174, s[26:27]
	s_mov_b32 m0, s40
	s_nop 0
	global_load_lds_dwordx4 v192, s[28:29]
	s_mov_b32 m0, s33
	s_nop 0
	global_load_lds_dwordx4 v191, s[26:27]
	s_mov_b32 m0, s41
	s_waitcnt lgkmcnt(3)
	v_mfma_f32_32x32x16_bf16 v[66:81], v[154:157], v[102:105], v[66:81]
	ds_read_b128 v[194:197], v185 offset:36864
	v_add_f32_e32 v193, v193, v48
	v_cvt_pk_bf16_f32 v149, v48, v49
	v_add_f32_e32 v193, v49, v193
	v_exp_f32_e32 v52, v52
	s_waitcnt lgkmcnt(3)
	v_mfma_f32_32x32x16_bf16 v[82:97], v[162:165], v[102:105], v[82:97]
	ds_read_b128 v[154:157], v185 offset:40960
	v_add_f32_e32 v193, v193, v50
	v_exp_f32_e32 v53, v53
	v_cvt_pk_bf16_f32 v142, v50, v51
	v_add_f32_e32 v193, v51, v193
	s_waitcnt lgkmcnt(3)
	v_mfma_f32_32x32x16_bf16 v[66:81], v[166:169], v[106:109], v[66:81]
	ds_read_b128 v[162:165], v187 offset:45056
	v_exp_f32_e32 v54, v54
	v_exp_f32_e32 v55, v55
	v_add_f32_e32 v193, v193, v52
	v_cvt_pk_bf16_f32 v143, v52, v53
	s_waitcnt lgkmcnt(3)
	v_mfma_f32_32x32x16_bf16 v[82:97], v[158:161], v[106:109], v[82:97]
	ds_read_b128 v[198:201], v187 offset:47104
	v_add_f32_e32 v166, v193, v53
	v_exp_f32_e32 v56, v56
	v_exp_f32_e32 v57, v57
	v_add_f32_e32 v166, v54, v166
	s_waitcnt lgkmcnt(3)
	v_mfma_f32_32x32x16_bf16 v[66:81], v[194:197], v[110:113], v[66:81]
	ds_read_b128 v[202:205], v188 offset:45056
	v_cvt_pk_bf16_f32 v144, v54, v55
	v_add_f32_e32 v159, v166, v55
	v_exp_f32_e32 v58, v58
	v_exp_f32_e32 v59, v59
	s_waitcnt lgkmcnt(3)
	v_mfma_f32_32x32x16_bf16 v[82:97], v[154:157], v[110:113], v[82:97]
	ds_read_b128 v[194:197], v188 offset:47104
	v_add_f32_e32 v158, v159, v56
	v_exp_f32_e32 v60, v60
	v_cvt_pk_bf16_f32 v145, v56, v57
	v_add_f32_e32 v158, v57, v158
	s_waitcnt lgkmcnt(3)
	v_mfma_f32_32x32x16_bf16 v[66:81], v[162:165], v[114:117], v[66:81]
	ds_read_b64_tr_b16 v[166:167], v189 offset:49152
	ds_read_b64_tr_b16 v[168:169], v189 offset:49664
	v_add_f32_e32 v154, v158, v58
	v_exp_f32_e32 v61, v61
	v_cvt_pk_bf16_f32 v138, v58, v59
	v_add_f32_e32 v154, v59, v154
	s_waitcnt lgkmcnt(4)
	v_mfma_f32_32x32x16_bf16 v[82:97], v[198:201], v[114:117], v[82:97]
	ds_read_b64_tr_b16 v[162:163], v189 offset:50176
	ds_read_b64_tr_b16 v[164:165], v189 offset:50688
	v_exp_f32_e32 v62, v62
	v_exp_f32_e32 v63, v63
	v_add_f32_e32 v154, v154, v60
	v_cvt_pk_bf16_f32 v139, v60, v61
	s_waitcnt lgkmcnt(5)
	v_mfma_f32_32x32x16_bf16 v[66:81], v[202:205], v[118:121], v[66:81]
	ds_read_b64_tr_b16 v[158:159], v189 offset:51200
	ds_read_b64_tr_b16 v[160:161], v189 offset:51712
	v_add_f32_e32 v154, v154, v61
	v_exp_f32_e32 v64, v64
	v_exp_f32_e32 v65, v65
	v_add_f32_e32 v198, v62, v154
	s_waitcnt lgkmcnt(6)
	v_mfma_f32_32x32x16_bf16 v[82:97], v[194:197], v[118:121], v[82:97]
	ds_read_b64_tr_b16 v[154:155], v189 offset:52224
	ds_read_b64_tr_b16 v[156:157], v189 offset:52736
	v_add_f32_e32 v141, v198, v63
	v_add_f32_e32 v198, v64, v141
	v_cvt_pk_bf16_f32 v140, v62, v63
	v_cvt_pk_bf16_f32 v141, v64, v65
	v_add_f32_e32 v194, v65, v198
	s_waitcnt vmcnt(6) lgkmcnt(0)
	s_barrier
	s_waitcnt lgkmcnt(6)
	v_mfma_f32_32x32x16_bf16 v[2:17], v[150:153], v[166:169], v[2:17]
	ds_read_b64_tr_b16 v[34:35], v189 offset:53248
	ds_read_b64_tr_b16 v[36:37], v189 offset:53760
	v_exp_f32_e32 v66, v66
	v_exp_f32_e32 v67, v67
	v_exp_f32_e32 v68, v68
	s_waitcnt lgkmcnt(6)
	v_mfma_f32_32x32x16_bf16 v[2:17], v[146:149], v[162:165], v[2:17]
	ds_read_b64_tr_b16 v[38:39], v189 offset:54272
	ds_read_b64_tr_b16 v[40:41], v189 offset:54784
	v_add_f32_e32 v42, v194, v66
	v_exp_f32_e32 v69, v69
	v_cvt_pk_bf16_f32 v134, v66, v67
	v_add_f32_e32 v46, v67, v42
	s_waitcnt lgkmcnt(6)
	v_mfma_f32_32x32x16_bf16 v[2:17], v[142:145], v[158:161], v[2:17]
	ds_read_b64_tr_b16 v[42:43], v189 offset:55296
	ds_read_b64_tr_b16 v[44:45], v189 offset:55808
	v_exp_f32_e32 v70, v70
	v_exp_f32_e32 v71, v71
	v_add_f32_e32 v50, v46, v68
	v_cvt_pk_bf16_f32 v135, v68, v69
	s_waitcnt lgkmcnt(6)
	v_mfma_f32_32x32x16_bf16 v[2:17], v[138:141], v[154:157], v[2:17]
	ds_read_b64_tr_b16 v[46:47], v189 offset:56320
	ds_read_b64_tr_b16 v[48:49], v189 offset:56832
	v_add_f32_e32 v50, v50, v69
	v_exp_f32_e32 v72, v72
	v_exp_f32_e32 v73, v73
	v_add_f32_e32 v54, v70, v50
	s_waitcnt lgkmcnt(6)
	v_mfma_f32_32x32x16_bf16 v[18:33], v[150:153], v[34:37], v[18:33]
	ds_read_b128 v[50:53], v182
	v_cvt_pk_bf16_f32 v136, v70, v71
	v_add_f32_e32 v58, v54, v71
	v_exp_f32_e32 v74, v74
	v_exp_f32_e32 v75, v75
	s_waitcnt lgkmcnt(5)
	v_mfma_f32_32x32x16_bf16 v[18:33], v[146:149], v[38:41], v[18:33]
	ds_read_b128 v[54:57], v182 offset:4096
	v_add_f32_e32 v34, v58, v72
	v_exp_f32_e32 v76, v76
	v_cvt_pk_bf16_f32 v137, v72, v73
	v_add_f32_e32 v34, v73, v34
	s_waitcnt lgkmcnt(4)
	v_mfma_f32_32x32x16_bf16 v[18:33], v[142:145], v[42:45], v[18:33]
	ds_read_b128 v[154:157], v183
	v_add_f32_e32 v34, v34, v74
	v_exp_f32_e32 v77, v77
	v_cvt_pk_bf16_f32 v130, v74, v75
	v_add_f32_e32 v34, v75, v34
	s_waitcnt lgkmcnt(3)
	v_mfma_f32_32x32x16_bf16 v[18:33], v[138:141], v[46:49], v[18:33]
	ds_read_b128 v[162:165], v183 offset:4096
	v_exp_f32_e32 v78, v78
	v_exp_f32_e32 v79, v79
	v_add_f32_e32 v34, v34, v76
	v_cvt_pk_bf16_f32 v131, v76, v77
	s_nop 0
	v_add_f32_e32 v34, v34, v77
	v_add_f32_e32 v59, v78, v34
	s_waitcnt lgkmcnt(3)
	v_mfma_f32_32x32x16_bf16 v[34:49], v[50:53], v[98:101], 0
	ds_read_b128 v[166:169], v184
	v_exp_f32_e32 v80, v80
	v_exp_f32_e32 v81, v81
	ds_read_b128 v[158:161], v184 offset:4096
	v_add_f32_e32 v193, v59, v79
	s_waitcnt lgkmcnt(4)
	v_mfma_f32_32x32x16_bf16 v[50:65], v[54:57], v[98:101], 0
	v_exp_f32_e32 v82, v82
	v_exp_f32_e32 v83, v83
	v_cvt_pk_bf16_f32 v132, v78, v79
	s_add_i32 s26, 0x9000, s8
	s_add_i32 s28, 0x6000, s12
	s_add_i32 s24, s26, 0x2000
	s_nop 4
	s_mov_b32 s25, m0
	s_mov_b32 m0, s26
	s_nop 0
	global_load_lds_dwordx4 v174, s[20:21]
	s_mov_b32 m0, s24
	s_nop 0
	global_load_lds_dwordx4 v192, s[22:23]
	s_mov_b32 m0, s28
	s_nop 0
	global_load_lds_dwordx4 v191, s[20:21]
	s_mov_b32 m0, s25
	s_waitcnt lgkmcnt(3)
	v_mfma_f32_32x32x16_bf16 v[34:49], v[154:157], v[102:105], v[34:49]
	ds_read_b128 v[194:197], v185
	v_add_f32_e32 v154, v193, v80
	v_exp_f32_e32 v84, v84
	v_cvt_pk_bf16_f32 v133, v80, v81
	v_add_f32_e32 v193, v81, v154
	s_waitcnt lgkmcnt(3)
	v_mfma_f32_32x32x16_bf16 v[50:65], v[162:165], v[102:105], v[50:65]
	ds_read_b128 v[154:157], v185 offset:4096
	v_add_f32_e32 v193, v193, v82
	v_exp_f32_e32 v85, v85
	v_cvt_pk_bf16_f32 v126, v82, v83
	v_add_f32_e32 v193, v83, v193
	s_waitcnt lgkmcnt(3)
	v_mfma_f32_32x32x16_bf16 v[34:49], v[166:169], v[106:109], v[34:49]
	ds_read_b128 v[162:165], v187 offset:8192
	v_exp_f32_e32 v86, v86
	v_exp_f32_e32 v87, v87
	v_add_f32_e32 v193, v193, v84
	v_cvt_pk_bf16_f32 v127, v84, v85
	s_waitcnt lgkmcnt(3)
	v_mfma_f32_32x32x16_bf16 v[50:65], v[158:161], v[106:109], v[50:65]
	ds_read_b128 v[198:201], v187 offset:10240
	v_add_f32_e32 v166, v193, v85
	v_exp_f32_e32 v88, v88
	v_exp_f32_e32 v89, v89
	v_add_f32_e32 v166, v86, v166
	s_waitcnt lgkmcnt(3)
	v_mfma_f32_32x32x16_bf16 v[34:49], v[194:197], v[110:113], v[34:49]
	ds_read_b128 v[202:205], v188 offset:8192
	v_cvt_pk_bf16_f32 v128, v86, v87
	v_add_f32_e32 v159, v166, v87
	v_exp_f32_e32 v90, v90
	v_exp_f32_e32 v91, v91
	s_waitcnt lgkmcnt(3)
	v_mfma_f32_32x32x16_bf16 v[50:65], v[154:157], v[110:113], v[50:65]
	ds_read_b128 v[194:197], v188 offset:10240
	v_add_f32_e32 v158, v159, v88
	v_exp_f32_e32 v92, v92
	v_cvt_pk_bf16_f32 v129, v88, v89
	v_add_f32_e32 v158, v89, v158
	s_waitcnt lgkmcnt(3)
	v_mfma_f32_32x32x16_bf16 v[34:49], v[162:165], v[114:117], v[34:49]
	ds_read_b64_tr_b16 v[166:167], v189 offset:57344
	ds_read_b64_tr_b16 v[168:169], v189 offset:57856
	v_add_f32_e32 v154, v158, v90
	v_exp_f32_e32 v93, v93
	v_cvt_pk_bf16_f32 v122, v90, v91
	v_add_f32_e32 v154, v91, v154
	s_waitcnt lgkmcnt(4)
	v_mfma_f32_32x32x16_bf16 v[50:65], v[198:201], v[114:117], v[50:65]
	ds_read_b64_tr_b16 v[162:163], v189 offset:58368
	ds_read_b64_tr_b16 v[164:165], v189 offset:58880
	v_exp_f32_e32 v94, v94
	v_exp_f32_e32 v95, v95
	v_add_f32_e32 v154, v154, v92
	v_cvt_pk_bf16_f32 v123, v92, v93
	s_waitcnt lgkmcnt(5)
	v_mfma_f32_32x32x16_bf16 v[34:49], v[202:205], v[118:121], v[34:49]
	ds_read_b64_tr_b16 v[158:159], v189 offset:59392
	ds_read_b64_tr_b16 v[160:161], v189 offset:59904
	v_add_f32_e32 v154, v154, v93
	v_exp_f32_e32 v96, v96
	v_exp_f32_e32 v97, v97
	v_add_f32_e32 v193, v94, v154
	s_waitcnt lgkmcnt(6)
	v_mfma_f32_32x32x16_bf16 v[50:65], v[194:197], v[118:121], v[50:65]
	ds_read_b64_tr_b16 v[154:155], v189 offset:60416
	ds_read_b64_tr_b16 v[156:157], v189 offset:60928
	v_add_f32_e32 v125, v193, v95
	v_add_f32_e32 v193, v96, v125
	v_cvt_pk_bf16_f32 v124, v94, v95
	v_cvt_pk_bf16_f32 v125, v96, v97
	v_add_f32_e32 v193, v97, v193
	s_add_u32 s22, s22, 0x2000
	s_addc_u32 s23, s23, 0
	s_add_u32 s20, s20, 0x40000
	s_addc_u32 s21, s21, 0
	s_waitcnt vmcnt(6) lgkmcnt(0)
	s_barrier
	s_waitcnt lgkmcnt(6)
	v_mfma_f32_32x32x16_bf16 v[2:17], v[134:137], v[166:169], v[2:17]
	ds_read_b64_tr_b16 v[66:67], v189 offset:61440
	ds_read_b64_tr_b16 v[68:69], v189 offset:61952
	v_exp_f32_e32 v34, v34
	v_exp_f32_e32 v35, v35
	v_exp_f32_e32 v36, v36
	s_waitcnt lgkmcnt(6)
	v_mfma_f32_32x32x16_bf16 v[2:17], v[130:133], v[162:165], v[2:17]
	ds_read_b64_tr_b16 v[70:71], v189 offset:62464
	ds_read_b64_tr_b16 v[72:73], v189 offset:62976
	v_add_f32_e32 v74, v193, v34
	v_exp_f32_e32 v37, v37
	v_cvt_pk_bf16_f32 v150, v34, v35
	v_add_f32_e32 v78, v35, v74
	s_waitcnt lgkmcnt(6)
	v_mfma_f32_32x32x16_bf16 v[2:17], v[126:129], v[158:161], v[2:17]
	ds_read_b64_tr_b16 v[74:75], v189 offset:63488
	ds_read_b64_tr_b16 v[76:77], v189 offset:64000
	v_exp_f32_e32 v38, v38
	v_exp_f32_e32 v39, v39
	v_add_f32_e32 v82, v78, v36
	v_cvt_pk_bf16_f32 v151, v36, v37
	s_waitcnt lgkmcnt(6)
	v_mfma_f32_32x32x16_bf16 v[2:17], v[122:125], v[154:157], v[2:17]
	ds_read_b64_tr_b16 v[78:79], v189 offset:64512
	ds_read_b64_tr_b16 v[80:81], v189 offset:65024
	v_add_f32_e32 v82, v82, v37
	v_exp_f32_e32 v40, v40
	v_exp_f32_e32 v41, v41
	v_add_f32_e32 v86, v38, v82
	s_waitcnt lgkmcnt(6)
	v_mfma_f32_32x32x16_bf16 v[18:33], v[134:137], v[66:69], v[18:33]
	ds_read_b128 v[82:85], v182 offset:12288
	v_cvt_pk_bf16_f32 v152, v38, v39
	v_add_f32_e32 v90, v86, v39
	v_exp_f32_e32 v42, v42
	v_exp_f32_e32 v43, v43
	s_waitcnt lgkmcnt(5)
	v_mfma_f32_32x32x16_bf16 v[18:33], v[130:133], v[70:73], v[18:33]
	ds_read_b128 v[86:89], v182 offset:16384
	v_add_f32_e32 v66, v90, v40
	v_exp_f32_e32 v44, v44
	v_cvt_pk_bf16_f32 v153, v40, v41
	v_add_f32_e32 v66, v41, v66
	s_waitcnt lgkmcnt(4)
	v_mfma_f32_32x32x16_bf16 v[18:33], v[126:129], v[74:77], v[18:33]
	ds_read_b128 v[154:157], v183 offset:12288
	v_add_f32_e32 v66, v66, v42
	v_exp_f32_e32 v45, v45
	v_cvt_pk_bf16_f32 v146, v42, v43
	v_add_f32_e32 v66, v43, v66
	s_waitcnt lgkmcnt(3)
	v_mfma_f32_32x32x16_bf16 v[18:33], v[122:125], v[78:81], v[18:33]
	ds_read_b128 v[162:165], v183 offset:16384
	v_exp_f32_e32 v46, v46
	v_exp_f32_e32 v47, v47
	v_add_f32_e32 v66, v66, v44
	v_cvt_pk_bf16_f32 v147, v44, v45
	s_nop 0
	v_add_f32_e32 v66, v66, v45
	v_add_f32_e32 v91, v46, v66
	s_waitcnt lgkmcnt(3)
	v_mfma_f32_32x32x16_bf16 v[66:81], v[82:85], v[98:101], 0
	ds_read_b128 v[166:169], v184 offset:12288
	v_exp_f32_e32 v48, v48
	v_exp_f32_e32 v49, v49
	ds_read_b128 v[158:161], v184 offset:16384
	v_add_f32_e32 v193, v91, v47
	s_waitcnt lgkmcnt(4)
	v_mfma_f32_32x32x16_bf16 v[82:97], v[86:89], v[98:101], 0
	v_exp_f32_e32 v50, v50
	v_exp_f32_e32 v51, v51
	v_cvt_pk_bf16_f32 v148, v46, v47
	s_add_u32 s26, s20, 0xfffe0000
	s_addc_u32 s27, s21, -1
	s_add_i32 s31, 0, s8
	s_add_i32 s33, 0x8000, s12
	s_add_u32 s28, s22, 0xfffff000
	s_addc_u32 s29, s23, -1
	s_add_i32 s40, s31, 0x2000
	s_nop 4
	s_mov_b32 s41, m0
	s_mov_b32 m0, s31
	s_nop 0
	global_load_lds_dwordx4 v174, s[26:27]
	s_mov_b32 m0, s40
	s_nop 0
	global_load_lds_dwordx4 v192, s[28:29]
	s_mov_b32 m0, s33
	s_nop 0
	global_load_lds_dwordx4 v191, s[26:27]
	s_mov_b32 m0, s41
	s_waitcnt lgkmcnt(3)
	v_mfma_f32_32x32x16_bf16 v[66:81], v[154:157], v[102:105], v[66:81]
	ds_read_b128 v[194:197], v185 offset:12288
	v_add_f32_e32 v193, v193, v48
	v_cvt_pk_bf16_f32 v149, v48, v49
	v_add_f32_e32 v193, v49, v193
	v_exp_f32_e32 v52, v52
	s_waitcnt lgkmcnt(3)
	v_mfma_f32_32x32x16_bf16 v[82:97], v[162:165], v[102:105], v[82:97]
	ds_read_b128 v[154:157], v185 offset:16384
	v_add_f32_e32 v193, v193, v50
	v_exp_f32_e32 v53, v53
	v_cvt_pk_bf16_f32 v142, v50, v51
	v_add_f32_e32 v193, v51, v193
	s_waitcnt lgkmcnt(3)
	v_mfma_f32_32x32x16_bf16 v[66:81], v[166:169], v[106:109], v[66:81]
	ds_read_b128 v[162:165], v187 offset:20480
	v_exp_f32_e32 v54, v54
	v_exp_f32_e32 v55, v55
	v_add_f32_e32 v193, v193, v52
	v_cvt_pk_bf16_f32 v143, v52, v53
	s_waitcnt lgkmcnt(3)
	v_mfma_f32_32x32x16_bf16 v[82:97], v[158:161], v[106:109], v[82:97]
	ds_read_b128 v[198:201], v187 offset:22528
	v_add_f32_e32 v166, v193, v53
	v_exp_f32_e32 v56, v56
	v_exp_f32_e32 v57, v57
	v_add_f32_e32 v166, v54, v166
	s_waitcnt lgkmcnt(3)
	v_mfma_f32_32x32x16_bf16 v[66:81], v[194:197], v[110:113], v[66:81]
	ds_read_b128 v[202:205], v188 offset:20480
	v_cvt_pk_bf16_f32 v144, v54, v55
	v_add_f32_e32 v159, v166, v55
	v_exp_f32_e32 v58, v58
	v_exp_f32_e32 v59, v59
	s_waitcnt lgkmcnt(3)
	v_mfma_f32_32x32x16_bf16 v[82:97], v[154:157], v[110:113], v[82:97]
	ds_read_b128 v[194:197], v188 offset:22528
	v_add_f32_e32 v158, v159, v56
	v_exp_f32_e32 v60, v60
	v_cvt_pk_bf16_f32 v145, v56, v57
	v_add_f32_e32 v158, v57, v158
	s_waitcnt lgkmcnt(3)
	v_mfma_f32_32x32x16_bf16 v[66:81], v[162:165], v[114:117], v[66:81]
	ds_read_b64_tr_b16 v[166:167], v189 offset:16384
	ds_read_b64_tr_b16 v[168:169], v189 offset:16896
	v_add_f32_e32 v154, v158, v58
	v_exp_f32_e32 v61, v61
	v_cvt_pk_bf16_f32 v138, v58, v59
	v_add_f32_e32 v154, v59, v154
	s_waitcnt lgkmcnt(4)
	v_mfma_f32_32x32x16_bf16 v[82:97], v[198:201], v[114:117], v[82:97]
	ds_read_b64_tr_b16 v[162:163], v189 offset:17408
	ds_read_b64_tr_b16 v[164:165], v189 offset:17920
	v_exp_f32_e32 v62, v62
	v_exp_f32_e32 v63, v63
	v_add_f32_e32 v154, v154, v60
	v_cvt_pk_bf16_f32 v139, v60, v61
	s_waitcnt lgkmcnt(5)
	v_mfma_f32_32x32x16_bf16 v[66:81], v[202:205], v[118:121], v[66:81]
	ds_read_b64_tr_b16 v[158:159], v189 offset:18432
	ds_read_b64_tr_b16 v[160:161], v189 offset:18944
	v_add_f32_e32 v154, v154, v61
	v_exp_f32_e32 v64, v64
	v_exp_f32_e32 v65, v65
	v_add_f32_e32 v198, v62, v154
	s_waitcnt lgkmcnt(6)
	v_mfma_f32_32x32x16_bf16 v[82:97], v[194:197], v[118:121], v[82:97]
	ds_read_b64_tr_b16 v[154:155], v189 offset:19456
	ds_read_b64_tr_b16 v[156:157], v189 offset:19968
	v_add_f32_e32 v141, v198, v63
	v_add_f32_e32 v198, v64, v141
	v_cvt_pk_bf16_f32 v140, v62, v63
	v_cvt_pk_bf16_f32 v141, v64, v65
	v_add_f32_e32 v194, v65, v198
	s_waitcnt vmcnt(6) lgkmcnt(0)
	s_barrier
	s_waitcnt lgkmcnt(6)
	v_mfma_f32_32x32x16_bf16 v[2:17], v[150:153], v[166:169], v[2:17]
	ds_read_b64_tr_b16 v[34:35], v189 offset:20480
	ds_read_b64_tr_b16 v[36:37], v189 offset:20992
	v_exp_f32_e32 v66, v66
	v_exp_f32_e32 v67, v67
	v_exp_f32_e32 v68, v68
	s_waitcnt lgkmcnt(6)
	v_mfma_f32_32x32x16_bf16 v[2:17], v[146:149], v[162:165], v[2:17]
	ds_read_b64_tr_b16 v[38:39], v189 offset:21504
	ds_read_b64_tr_b16 v[40:41], v189 offset:22016
	v_add_f32_e32 v42, v194, v66
	v_exp_f32_e32 v69, v69
	v_cvt_pk_bf16_f32 v134, v66, v67
	v_add_f32_e32 v46, v67, v42
	s_waitcnt lgkmcnt(6)
	v_mfma_f32_32x32x16_bf16 v[2:17], v[142:145], v[158:161], v[2:17]
	ds_read_b64_tr_b16 v[42:43], v189 offset:22528
	ds_read_b64_tr_b16 v[44:45], v189 offset:23040
	v_exp_f32_e32 v70, v70
	v_exp_f32_e32 v71, v71
	v_add_f32_e32 v50, v46, v68
	v_cvt_pk_bf16_f32 v135, v68, v69
	s_waitcnt lgkmcnt(6)
	v_mfma_f32_32x32x16_bf16 v[2:17], v[138:141], v[154:157], v[2:17]
	ds_read_b64_tr_b16 v[46:47], v189 offset:23552
	ds_read_b64_tr_b16 v[48:49], v189 offset:24064
	v_add_f32_e32 v50, v50, v69
	v_exp_f32_e32 v72, v72
	v_exp_f32_e32 v73, v73
	v_add_f32_e32 v54, v70, v50
	s_waitcnt lgkmcnt(6)
	v_mfma_f32_32x32x16_bf16 v[18:33], v[150:153], v[34:37], v[18:33]
	ds_read_b128 v[50:53], v182 offset:24576
	v_cvt_pk_bf16_f32 v136, v70, v71
	v_add_f32_e32 v58, v54, v71
	v_exp_f32_e32 v74, v74
	v_exp_f32_e32 v75, v75
	s_waitcnt lgkmcnt(5)
	v_mfma_f32_32x32x16_bf16 v[18:33], v[146:149], v[38:41], v[18:33]
	ds_read_b128 v[54:57], v182 offset:28672
	v_add_f32_e32 v34, v58, v72
	v_exp_f32_e32 v76, v76
	v_cvt_pk_bf16_f32 v137, v72, v73
	v_add_f32_e32 v34, v73, v34
	s_waitcnt lgkmcnt(4)
	v_mfma_f32_32x32x16_bf16 v[18:33], v[142:145], v[42:45], v[18:33]
	ds_read_b128 v[154:157], v183 offset:24576
	v_add_f32_e32 v34, v34, v74
	v_exp_f32_e32 v77, v77
	v_cvt_pk_bf16_f32 v130, v74, v75
	v_add_f32_e32 v34, v75, v34
	s_waitcnt lgkmcnt(3)
	v_mfma_f32_32x32x16_bf16 v[18:33], v[138:141], v[46:49], v[18:33]
	ds_read_b128 v[162:165], v183 offset:28672
	v_exp_f32_e32 v78, v78
	v_exp_f32_e32 v79, v79
	v_add_f32_e32 v34, v34, v76
	v_cvt_pk_bf16_f32 v131, v76, v77
	s_nop 0
	v_add_f32_e32 v34, v34, v77
	v_add_f32_e32 v59, v78, v34
	s_waitcnt lgkmcnt(3)
	v_mfma_f32_32x32x16_bf16 v[34:49], v[50:53], v[98:101], 0
	ds_read_b128 v[166:169], v184 offset:24576
	v_exp_f32_e32 v80, v80
	v_exp_f32_e32 v81, v81
	ds_read_b128 v[158:161], v184 offset:28672
	v_add_f32_e32 v193, v59, v79
	s_waitcnt lgkmcnt(4)
	v_mfma_f32_32x32x16_bf16 v[50:65], v[54:57], v[98:101], 0
	v_exp_f32_e32 v82, v82
	v_exp_f32_e32 v83, v83
	v_cvt_pk_bf16_f32 v132, v78, v79
	s_add_i32 s26, 0x3000, s8
	s_add_i32 s28, 0xa000, s12
	s_add_i32 s24, s26, 0x2000
	s_nop 4
	s_mov_b32 s25, m0
	s_mov_b32 m0, s26
	s_nop 0
	global_load_lds_dwordx4 v174, s[20:21]
	s_mov_b32 m0, s24
	s_nop 0
	global_load_lds_dwordx4 v192, s[22:23]
	s_mov_b32 m0, s28
	s_nop 0
	global_load_lds_dwordx4 v191, s[20:21]
	s_mov_b32 m0, s25
	s_waitcnt lgkmcnt(3)
	v_mfma_f32_32x32x16_bf16 v[34:49], v[154:157], v[102:105], v[34:49]
	ds_read_b128 v[194:197], v185 offset:24576
	v_add_f32_e32 v154, v193, v80
	v_exp_f32_e32 v84, v84
	v_cvt_pk_bf16_f32 v133, v80, v81
	v_add_f32_e32 v193, v81, v154
	s_waitcnt lgkmcnt(3)
	v_mfma_f32_32x32x16_bf16 v[50:65], v[162:165], v[102:105], v[50:65]
	ds_read_b128 v[154:157], v185 offset:28672
	v_add_f32_e32 v193, v193, v82
	v_exp_f32_e32 v85, v85
	v_cvt_pk_bf16_f32 v126, v82, v83
	v_add_f32_e32 v193, v83, v193
	s_waitcnt lgkmcnt(3)
	v_mfma_f32_32x32x16_bf16 v[34:49], v[166:169], v[106:109], v[34:49]
	ds_read_b128 v[162:165], v187 offset:32768
	v_exp_f32_e32 v86, v86
	v_exp_f32_e32 v87, v87
	v_add_f32_e32 v193, v193, v84
	v_cvt_pk_bf16_f32 v127, v84, v85
	s_waitcnt lgkmcnt(3)
	v_mfma_f32_32x32x16_bf16 v[50:65], v[158:161], v[106:109], v[50:65]
	ds_read_b128 v[198:201], v187 offset:34816
	v_add_f32_e32 v166, v193, v85
	v_exp_f32_e32 v88, v88
	v_exp_f32_e32 v89, v89
	v_add_f32_e32 v166, v86, v166
	s_waitcnt lgkmcnt(3)
	v_mfma_f32_32x32x16_bf16 v[34:49], v[194:197], v[110:113], v[34:49]
	ds_read_b128 v[202:205], v188 offset:32768
	v_cvt_pk_bf16_f32 v128, v86, v87
	v_add_f32_e32 v159, v166, v87
	v_exp_f32_e32 v90, v90
	v_exp_f32_e32 v91, v91
	s_waitcnt lgkmcnt(3)
	v_mfma_f32_32x32x16_bf16 v[50:65], v[154:157], v[110:113], v[50:65]
	ds_read_b128 v[194:197], v188 offset:34816
	v_add_f32_e32 v158, v159, v88
	v_exp_f32_e32 v92, v92
	v_cvt_pk_bf16_f32 v129, v88, v89
	v_add_f32_e32 v158, v89, v158
	s_waitcnt lgkmcnt(3)
	v_mfma_f32_32x32x16_bf16 v[34:49], v[162:165], v[114:117], v[34:49]
	ds_read_b64_tr_b16 v[166:167], v189 offset:24576
	ds_read_b64_tr_b16 v[168:169], v189 offset:25088
	v_add_f32_e32 v154, v158, v90
	v_exp_f32_e32 v93, v93
	v_cvt_pk_bf16_f32 v122, v90, v91
	v_add_f32_e32 v154, v91, v154
	s_waitcnt lgkmcnt(4)
	v_mfma_f32_32x32x16_bf16 v[50:65], v[198:201], v[114:117], v[50:65]
	ds_read_b64_tr_b16 v[162:163], v189 offset:25600
	ds_read_b64_tr_b16 v[164:165], v189 offset:26112
	v_exp_f32_e32 v94, v94
	v_exp_f32_e32 v95, v95
	v_add_f32_e32 v154, v154, v92
	v_cvt_pk_bf16_f32 v123, v92, v93
	s_waitcnt lgkmcnt(5)
	v_mfma_f32_32x32x16_bf16 v[34:49], v[202:205], v[118:121], v[34:49]
	ds_read_b64_tr_b16 v[158:159], v189 offset:26624
	ds_read_b64_tr_b16 v[160:161], v189 offset:27136
	v_add_f32_e32 v154, v154, v93
	v_exp_f32_e32 v96, v96
	v_exp_f32_e32 v97, v97
	v_add_f32_e32 v193, v94, v154
	s_waitcnt lgkmcnt(6)
	v_mfma_f32_32x32x16_bf16 v[50:65], v[194:197], v[118:121], v[50:65]
	ds_read_b64_tr_b16 v[154:155], v189 offset:27648
	ds_read_b64_tr_b16 v[156:157], v189 offset:28160
	v_add_f32_e32 v125, v193, v95
	v_add_f32_e32 v193, v96, v125
	v_cvt_pk_bf16_f32 v124, v94, v95
	v_cvt_pk_bf16_f32 v125, v96, v97
	v_add_f32_e32 v193, v97, v193
	s_add_u32 s22, s22, 0x2000
	s_addc_u32 s23, s23, 0
	s_add_u32 s20, s20, 0x40000
	s_addc_u32 s21, s21, 0
	s_add_i32 s13, s13, 12
	s_cmp_le_i32 s13, 108
	s_cbranch_scc1 .Lmla_fast_w03
	v_subrev_u32_e32 v189, 0x8000, v189
	s_mov_b32 s2, 0x4000
	s_mov_b32 s17, 0x6000
	s_mov_b32 s26, 0x2000
	s_mov_b32 s14, 0x0
	s_mov_b32 s15, 0x9000
	s_branch .LBB0_1278
.Lmla_fast_w47:
	s_waitcnt vmcnt(4) lgkmcnt(0)
	s_barrier
	s_waitcnt lgkmcnt(6)
	v_mfma_f32_32x32x16_bf16 v[2:17], v[134:137], v[166:169], v[2:17]
	ds_read_b64_tr_b16 v[66:67], v189 offset:28672
	ds_read_b64_tr_b16 v[68:69], v189 offset:29184
	v_exp_f32_e32 v34, v34
	v_exp_f32_e32 v35, v35
	v_exp_f32_e32 v36, v36
	s_waitcnt lgkmcnt(6)
	v_mfma_f32_32x32x16_bf16 v[2:17], v[130:133], v[162:165], v[2:17]
	ds_read_b64_tr_b16 v[70:71], v189 offset:29696
	ds_read_b64_tr_b16 v[72:73], v189 offset:30208
	v_add_f32_e32 v74, v193, v34
	v_exp_f32_e32 v37, v37
	v_cvt_pk_bf16_f32 v150, v34, v35
	v_add_f32_e32 v78, v35, v74
	s_waitcnt lgkmcnt(6)
	v_mfma_f32_32x32x16_bf16 v[2:17], v[126:129], v[158:161], v[2:17]
	ds_read_b64_tr_b16 v[74:75], v189 offset:30720
	ds_read_b64_tr_b16 v[76:77], v189 offset:31232
	v_exp_f32_e32 v38, v38
	v_exp_f32_e32 v39, v39
	v_add_f32_e32 v82, v78, v36
	v_cvt_pk_bf16_f32 v151, v36, v37
	s_waitcnt lgkmcnt(6)
	v_mfma_f32_32x32x16_bf16 v[2:17], v[122:125], v[154:157], v[2:17]
	ds_read_b64_tr_b16 v[78:79], v189 offset:31744
	ds_read_b64_tr_b16 v[80:81], v189 offset:32256
	v_add_f32_e32 v82, v82, v37
	v_exp_f32_e32 v40, v40
	v_exp_f32_e32 v41, v41
	v_add_f32_e32 v86, v38, v82
	s_waitcnt lgkmcnt(6)
	v_mfma_f32_32x32x16_bf16 v[18:33], v[134:137], v[66:69], v[18:33]
	ds_read_b128 v[82:85], v182 offset:36864
	v_cvt_pk_bf16_f32 v152, v38, v39
	v_add_f32_e32 v90, v86, v39
	v_exp_f32_e32 v42, v42
	v_exp_f32_e32 v43, v43
	s_waitcnt lgkmcnt(5)
	v_mfma_f32_32x32x16_bf16 v[18:33], v[130:133], v[70:73], v[18:33]
	ds_read_b128 v[86:89], v182 offset:40960
	v_add_f32_e32 v66, v90, v40
	v_exp_f32_e32 v44, v44
	v_cvt_pk_bf16_f32 v153, v40, v41
	v_add_f32_e32 v66, v41, v66
	s_waitcnt lgkmcnt(4)
	v_mfma_f32_32x32x16_bf16 v[18:33], v[126:129], v[74:77], v[18:33]
	ds_read_b128 v[154:157], v183 offset:36864
	v_add_f32_e32 v66, v66, v42
	v_exp_f32_e32 v45, v45
	v_cvt_pk_bf16_f32 v146, v42, v43
	v_add_f32_e32 v66, v43, v66
	s_waitcnt lgkmcnt(3)
	v_mfma_f32_32x32x16_bf16 v[18:33], v[122:125], v[78:81], v[18:33]
	ds_read_b128 v[162:165], v183 offset:40960
	v_exp_f32_e32 v46, v46
	v_exp_f32_e32 v47, v47
	v_add_f32_e32 v66, v66, v44
	v_cvt_pk_bf16_f32 v147, v44, v45
	s_nop 0
	v_add_f32_e32 v66, v66, v45
	v_add_f32_e32 v91, v46, v66
	s_waitcnt lgkmcnt(3)
	v_mfma_f32_32x32x16_bf16 v[66:81], v[82:85], v[98:101], 0
	ds_read_b128 v[166:169], v184 offset:36864
	v_exp_f32_e32 v48, v48
	v_exp_f32_e32 v49, v49
	ds_read_b128 v[158:161], v184 offset:40960
	v_add_f32_e32 v193, v91, v47
	s_waitcnt lgkmcnt(4)
	v_mfma_f32_32x32x16_bf16 v[82:97], v[86:89], v[98:101], 0
	v_exp_f32_e32 v50, v50
	v_exp_f32_e32 v51, v51
	v_cvt_pk_bf16_f32 v148, v46, v47
	s_add_u32 s26, s20, 0xfffe0000
	s_addc_u32 s27, s21, -1
	s_add_i32 s31, 0x6000, s8
	s_add_i32 s33, 0, s12
	s_nop 4
	s_mov_b32 s28, m0
	s_mov_b32 m0, s31
	s_nop 0
	global_load_lds_dwordx4 v174, s[26:27]
	s_mov_b32 m0, s33
	s_nop 0
	global_load_lds_dwordx4 v191, s[26:27]
	s_mov_b32 m0, s28
	s_waitcnt lgkmcnt(3)
	v_mfma_f32_32x32x16_bf16 v[66:81], v[154:157], v[102:105], v[66:81]
	ds_read_b128 v[194:197], v185 offset:36864
	v_add_f32_e32 v193, v193, v48
	v_cvt_pk_bf16_f32 v149, v48, v49
	v_add_f32_e32 v193, v49, v193
	v_exp_f32_e32 v52, v52
	s_waitcnt lgkmcnt(3)
	v_mfma_f32_32x32x16_bf16 v[82:97], v[162:165], v[102:105], v[82:97]
	ds_read_b128 v[154:157], v185 offset:40960
	v_add_f32_e32 v193, v193, v50
	v_exp_f32_e32 v53, v53
	v_cvt_pk_bf16_f32 v142, v50, v51
	v_add_f32_e32 v193, v51, v193
	s_waitcnt lgkmcnt(3)
	v_mfma_f32_32x32x16_bf16 v[66:81], v[166:169], v[106:109], v[66:81]
	ds_read_b128 v[162:165], v187 offset:45056
	v_exp_f32_e32 v54, v54
	v_exp_f32_e32 v55, v55
	v_add_f32_e32 v193, v193, v52
	v_cvt_pk_bf16_f32 v143, v52, v53
	s_waitcnt lgkmcnt(3)
	v_mfma_f32_32x32x16_bf16 v[82:97], v[158:161], v[106:109], v[82:97]
	ds_read_b128 v[198:201], v187 offset:47104
	v_add_f32_e32 v166, v193, v53
	v_exp_f32_e32 v56, v56
	v_exp_f32_e32 v57, v57
	v_add_f32_e32 v166, v54, v166
	s_waitcnt lgkmcnt(3)
	v_mfma_f32_32x32x16_bf16 v[66:81], v[194:197], v[110:113], v[66:81]
	ds_read_b128 v[202:205], v188 offset:45056
	v_cvt_pk_bf16_f32 v144, v54, v55
	v_add_f32_e32 v159, v166, v55
	v_exp_f32_e32 v58, v58
	v_exp_f32_e32 v59, v59
	s_waitcnt lgkmcnt(3)
	v_mfma_f32_32x32x16_bf16 v[82:97], v[154:157], v[110:113], v[82:97]
	ds_read_b128 v[194:197], v188 offset:47104
	v_add_f32_e32 v158, v159, v56
	v_exp_f32_e32 v60, v60
	v_cvt_pk_bf16_f32 v145, v56, v57
	v_add_f32_e32 v158, v57, v158
	s_waitcnt lgkmcnt(3)
	v_mfma_f32_32x32x16_bf16 v[66:81], v[162:165], v[114:117], v[66:81]
	ds_read_b64_tr_b16 v[166:167], v189 offset:32768
	ds_read_b64_tr_b16 v[168:169], v189 offset:33280
	v_add_f32_e32 v154, v158, v58
	v_exp_f32_e32 v61, v61
	v_cvt_pk_bf16_f32 v138, v58, v59
	v_add_f32_e32 v154, v59, v154
	s_waitcnt lgkmcnt(4)
	v_mfma_f32_32x32x16_bf16 v[82:97], v[198:201], v[114:117], v[82:97]
	ds_read_b64_tr_b16 v[162:163], v189 offset:33792
	ds_read_b64_tr_b16 v[164:165], v189 offset:34304
	v_exp_f32_e32 v62, v62
	v_exp_f32_e32 v63, v63
	v_add_f32_e32 v154, v154, v60
	v_cvt_pk_bf16_f32 v139, v60, v61
	s_waitcnt lgkmcnt(5)
	v_mfma_f32_32x32x16_bf16 v[66:81], v[202:205], v[118:121], v[66:81]
	ds_read_b64_tr_b16 v[158:159], v189 offset:34816
	ds_read_b64_tr_b16 v[160:161], v189 offset:35328
	v_add_f32_e32 v154, v154, v61
	v_exp_f32_e32 v64, v64
	v_exp_f32_e32 v65, v65
	v_add_f32_e32 v198, v62, v154
	s_waitcnt lgkmcnt(6)
	v_mfma_f32_32x32x16_bf16 v[82:97], v[194:197], v[118:121], v[82:97]
	ds_read_b64_tr_b16 v[154:155], v189 offset:35840
	ds_read_b64_tr_b16 v[156:157], v189 offset:36352
	v_add_f32_e32 v141, v198, v63
	v_add_f32_e32 v198, v64, v141
	v_cvt_pk_bf16_f32 v140, v62, v63
	v_cvt_pk_bf16_f32 v141, v64, v65
	v_add_f32_e32 v194, v65, v198
	s_waitcnt vmcnt(4) lgkmcnt(0)
	s_barrier
	s_waitcnt lgkmcnt(6)
	v_mfma_f32_32x32x16_bf16 v[2:17], v[150:153], v[166:169], v[2:17]
	ds_read_b64_tr_b16 v[34:35], v189 offset:36864
	ds_read_b64_tr_b16 v[36:37], v189 offset:37376
	v_exp_f32_e32 v66, v66
	v_exp_f32_e32 v67, v67
	v_exp_f32_e32 v68, v68
	s_waitcnt lgkmcnt(6)
	v_mfma_f32_32x32x16_bf16 v[2:17], v[146:149], v[162:165], v[2:17]
	ds_read_b64_tr_b16 v[38:39], v189 offset:37888
	ds_read_b64_tr_b16 v[40:41], v189 offset:38400
	v_add_f32_e32 v42, v194, v66
	v_exp_f32_e32 v69, v69
	v_cvt_pk_bf16_f32 v134, v66, v67
	v_add_f32_e32 v46, v67, v42
	s_waitcnt lgkmcnt(6)
	v_mfma_f32_32x32x16_bf16 v[2:17], v[142:145], v[158:161], v[2:17]
	ds_read_b64_tr_b16 v[42:43], v189 offset:38912
	ds_read_b64_tr_b16 v[44:45], v189 offset:39424
	v_exp_f32_e32 v70, v70
	v_exp_f32_e32 v71, v71
	v_add_f32_e32 v50, v46, v68
	v_cvt_pk_bf16_f32 v135, v68, v69
	s_waitcnt lgkmcnt(6)
	v_mfma_f32_32x32x16_bf16 v[2:17], v[138:141], v[154:157], v[2:17]
	ds_read_b64_tr_b16 v[46:47], v189 offset:39936
	ds_read_b64_tr_b16 v[48:49], v189 offset:40448
	v_add_f32_e32 v50, v50, v69
	v_exp_f32_e32 v72, v72
	v_exp_f32_e32 v73, v73
	v_add_f32_e32 v54, v70, v50
	s_waitcnt lgkmcnt(6)
	v_mfma_f32_32x32x16_bf16 v[18:33], v[150:153], v[34:37], v[18:33]
	ds_read_b128 v[50:53], v182
	v_cvt_pk_bf16_f32 v136, v70, v71
	v_add_f32_e32 v58, v54, v71
	v_exp_f32_e32 v74, v74
	v_exp_f32_e32 v75, v75
	s_waitcnt lgkmcnt(5)
	v_mfma_f32_32x32x16_bf16 v[18:33], v[146:149], v[38:41], v[18:33]
	ds_read_b128 v[54:57], v182 offset:4096
	v_add_f32_e32 v34, v58, v72
	v_exp_f32_e32 v76, v76
	v_cvt_pk_bf16_f32 v137, v72, v73
	v_add_f32_e32 v34, v73, v34
	s_waitcnt lgkmcnt(4)
	v_mfma_f32_32x32x16_bf16 v[18:33], v[142:145], v[42:45], v[18:33]
	ds_read_b128 v[154:157], v183
	v_add_f32_e32 v34, v34, v74
	v_exp_f32_e32 v77, v77
	v_cvt_pk_bf16_f32 v130, v74, v75
	v_add_f32_e32 v34, v75, v34
	s_waitcnt lgkmcnt(3)
	v_mfma_f32_32x32x16_bf16 v[18:33], v[138:141], v[46:49], v[18:33]
	ds_read_b128 v[162:165], v183 offset:4096
	v_exp_f32_e32 v78, v78
	v_exp_f32_e32 v79, v79
	v_add_f32_e32 v34, v34, v76
	v_cvt_pk_bf16_f32 v131, v76, v77
	s_nop 0
	v_add_f32_e32 v34, v34, v77
	v_add_f32_e32 v59, v78, v34
	s_waitcnt lgkmcnt(3)
	v_mfma_f32_32x32x16_bf16 v[34:49], v[50:53], v[98:101], 0
	ds_read_b128 v[166:169], v184
	v_exp_f32_e32 v80, v80
	v_exp_f32_e32 v81, v81
	ds_read_b128 v[158:161], v184 offset:4096
	v_add_f32_e32 v193, v59, v79
	s_waitcnt lgkmcnt(4)
	v_mfma_f32_32x32x16_bf16 v[50:65], v[54:57], v[98:101], 0
	v_exp_f32_e32 v82, v82
	v_exp_f32_e32 v83, v83
	v_cvt_pk_bf16_f32 v132, v78, v79
	s_add_i32 s26, 0x9000, s8
	s_add_i32 s28, 0x2000, s12
	s_nop 4
	s_mov_b32 s24, m0
	s_mov_b32 m0, s26
	s_nop 0
	global_load_lds_dwordx4 v174, s[20:21]
	s_mov_b32 m0, s28
	s_nop 0
	global_load_lds_dwordx4 v191, s[20:21]
	s_mov_b32 m0, s24
	s_waitcnt lgkmcnt(3)
	v_mfma_f32_32x32x16_bf16 v[34:49], v[154:157], v[102:105], v[34:49]
	ds_read_b128 v[194:197], v185
	v_add_f32_e32 v154, v193, v80
	v_exp_f32_e32 v84, v84
	v_cvt_pk_bf16_f32 v133, v80, v81
	v_add_f32_e32 v193, v81, v154
	s_waitcnt lgkmcnt(3)
	v_mfma_f32_32x32x16_bf16 v[50:65], v[162:165], v[102:105], v[50:65]
	ds_read_b128 v[154:157], v185 offset:4096
	v_add_f32_e32 v193, v193, v82
	v_exp_f32_e32 v85, v85
	v_cvt_pk_bf16_f32 v126, v82, v83
	v_add_f32_e32 v193, v83, v193
	s_waitcnt lgkmcnt(3)
	v_mfma_f32_32x32x16_bf16 v[34:49], v[166:169], v[106:109], v[34:49]
	ds_read_b128 v[162:165], v187 offset:8192
	v_exp_f32_e32 v86, v86
	v_exp_f32_e32 v87, v87
	v_add_f32_e32 v193, v193, v84
	v_cvt_pk_bf16_f32 v127, v84, v85
	s_waitcnt lgkmcnt(3)
	v_mfma_f32_32x32x16_bf16 v[50:65], v[158:161], v[106:109], v[50:65]
	ds_read_b128 v[198:201], v187 offset:10240
	v_add_f32_e32 v166, v193, v85
	v_exp_f32_e32 v88, v88
	v_exp_f32_e32 v89, v89
	v_add_f32_e32 v166, v86, v166
	s_waitcnt lgkmcnt(3)
	v_mfma_f32_32x32x16_bf16 v[34:49], v[194:197], v[110:113], v[34:49]
	ds_read_b128 v[202:205], v188 offset:8192
	v_cvt_pk_bf16_f32 v128, v86, v87
	v_add_f32_e32 v159, v166, v87
	v_exp_f32_e32 v90, v90
	v_exp_f32_e32 v91, v91
	s_waitcnt lgkmcnt(3)
	v_mfma_f32_32x32x16_bf16 v[50:65], v[154:157], v[110:113], v[50:65]
	ds_read_b128 v[194:197], v188 offset:10240
	v_add_f32_e32 v158, v159, v88
	v_exp_f32_e32 v92, v92
	v_cvt_pk_bf16_f32 v129, v88, v89
	v_add_f32_e32 v158, v89, v158
	s_waitcnt lgkmcnt(3)
	v_mfma_f32_32x32x16_bf16 v[34:49], v[162:165], v[114:117], v[34:49]
	ds_read_b64_tr_b16 v[166:167], v189 offset:40960
	ds_read_b64_tr_b16 v[168:169], v189 offset:41472
	v_add_f32_e32 v154, v158, v90
	v_exp_f32_e32 v93, v93
	v_cvt_pk_bf16_f32 v122, v90, v91
	v_add_f32_e32 v154, v91, v154
	s_waitcnt lgkmcnt(4)
	v_mfma_f32_32x32x16_bf16 v[50:65], v[198:201], v[114:117], v[50:65]
	ds_read_b64_tr_b16 v[162:163], v189 offset:41984
	ds_read_b64_tr_b16 v[164:165], v189 offset:42496
	v_exp_f32_e32 v94, v94
	v_exp_f32_e32 v95, v95
	v_add_f32_e32 v154, v154, v92
	v_cvt_pk_bf16_f32 v123, v92, v93
	s_waitcnt lgkmcnt(5)
	v_mfma_f32_32x32x16_bf16 v[34:49], v[202:205], v[118:121], v[34:49]
	ds_read_b64_tr_b16 v[158:159], v189 offset:43008
	ds_read_b64_tr_b16 v[160:161], v189 offset:43520
	v_add_f32_e32 v154, v154, v93
	v_exp_f32_e32 v96, v96
	v_exp_f32_e32 v97, v97
	v_add_f32_e32 v193, v94, v154
	s_waitcnt lgkmcnt(6)
	v_mfma_f32_32x32x16_bf16 v[50:65], v[194:197], v[118:121], v[50:65]
	ds_read_b64_tr_b16 v[154:155], v189 offset:44032
	ds_read_b64_tr_b16 v[156:157], v189 offset:44544
	v_add_f32_e32 v125, v193, v95
	v_add_f32_e32 v193, v96, v125
	v_cvt_pk_bf16_f32 v124, v94, v95
	v_cvt_pk_bf16_f32 v125, v96, v97
	v_add_f32_e32 v193, v97, v193
	s_add_u32 s22, s22, 0x2000
	s_addc_u32 s23, s23, 0
	s_add_u32 s20, s20, 0x40000
	s_addc_u32 s21, s21, 0
	s_waitcnt vmcnt(4) lgkmcnt(0)
	s_barrier
	s_waitcnt lgkmcnt(6)
	v_mfma_f32_32x32x16_bf16 v[2:17], v[134:137], v[166:169], v[2:17]
	ds_read_b64_tr_b16 v[66:67], v189 offset:45056
	ds_read_b64_tr_b16 v[68:69], v189 offset:45568
	v_exp_f32_e32 v34, v34
	v_exp_f32_e32 v35, v35
	v_exp_f32_e32 v36, v36
	s_waitcnt lgkmcnt(6)
	v_mfma_f32_32x32x16_bf16 v[2:17], v[130:133], v[162:165], v[2:17]
	ds_read_b64_tr_b16 v[70:71], v189 offset:46080
	ds_read_b64_tr_b16 v[72:73], v189 offset:46592
	v_add_f32_e32 v74, v193, v34
	v_exp_f32_e32 v37, v37
	v_cvt_pk_bf16_f32 v150, v34, v35
	v_add_f32_e32 v78, v35, v74
	s_waitcnt lgkmcnt(6)
	v_mfma_f32_32x32x16_bf16 v[2:17], v[126:129], v[158:161], v[2:17]
	ds_read_b64_tr_b16 v[74:75], v189 offset:47104
	ds_read_b64_tr_b16 v[76:77], v189 offset:47616
	v_exp_f32_e32 v38, v38
	v_exp_f32_e32 v39, v39
	v_add_f32_e32 v82, v78, v36
	v_cvt_pk_bf16_f32 v151, v36, v37
	s_waitcnt lgkmcnt(6)
	v_mfma_f32_32x32x16_bf16 v[2:17], v[122:125], v[154:157], v[2:17]
	ds_read_b64_tr_b16 v[78:79], v189 offset:48128
	ds_read_b64_tr_b16 v[80:81], v189 offset:48640
	v_add_f32_e32 v82, v82, v37
	v_exp_f32_e32 v40, v40
	v_exp_f32_e32 v41, v41
	v_add_f32_e32 v86, v38, v82
	s_waitcnt lgkmcnt(6)
	v_mfma_f32_32x32x16_bf16 v[18:33], v[134:137], v[66:69], v[18:33]
	ds_read_b128 v[82:85], v182 offset:12288
	v_cvt_pk_bf16_f32 v152, v38, v39
	v_add_f32_e32 v90, v86, v39
	v_exp_f32_e32 v42, v42
	v_exp_f32_e32 v43, v43
	s_waitcnt lgkmcnt(5)
	v_mfma_f32_32x32x16_bf16 v[18:33], v[130:133], v[70:73], v[18:33]
	ds_read_b128 v[86:89], v182 offset:16384
	v_add_f32_e32 v66, v90, v40
	v_exp_f32_e32 v44, v44
	v_cvt_pk_bf16_f32 v153, v40, v41
	v_add_f32_e32 v66, v41, v66
	s_waitcnt lgkmcnt(4)
	v_mfma_f32_32x32x16_bf16 v[18:33], v[126:129], v[74:77], v[18:33]
	ds_read_b128 v[154:157], v183 offset:12288
	v_add_f32_e32 v66, v66, v42
	v_exp_f32_e32 v45, v45
	v_cvt_pk_bf16_f32 v146, v42, v43
	v_add_f32_e32 v66, v43, v66
	s_waitcnt lgkmcnt(3)
	v_mfma_f32_32x32x16_bf16 v[18:33], v[122:125], v[78:81], v[18:33]
	ds_read_b128 v[162:165], v183 offset:16384
	v_exp_f32_e32 v46, v46
	v_exp_f32_e32 v47, v47
	v_add_f32_e32 v66, v66, v44
	v_cvt_pk_bf16_f32 v147, v44, v45
	s_nop 0
	v_add_f32_e32 v66, v66, v45
	v_add_f32_e32 v91, v46, v66
	s_waitcnt lgkmcnt(3)
	v_mfma_f32_32x32x16_bf16 v[66:81], v[82:85], v[98:101], 0
	ds_read_b128 v[166:169], v184 offset:12288
	v_exp_f32_e32 v48, v48
	v_exp_f32_e32 v49, v49
	ds_read_b128 v[158:161], v184 offset:16384
	v_add_f32_e32 v193, v91, v47
	s_waitcnt lgkmcnt(4)
	v_mfma_f32_32x32x16_bf16 v[82:97], v[86:89], v[98:101], 0
	v_exp_f32_e32 v50, v50
	v_exp_f32_e32 v51, v51
	v_cvt_pk_bf16_f32 v148, v46, v47
	s_add_u32 s26, s20, 0xfffe0000
	s_addc_u32 s27, s21, -1
	s_add_i32 s31, 0, s8
	s_add_i32 s33, 0x4000, s12
	s_nop 4
	s_mov_b32 s28, m0
	s_mov_b32 m0, s31
	s_nop 0
	global_load_lds_dwordx4 v174, s[26:27]
	s_mov_b32 m0, s33
	s_nop 0
	global_load_lds_dwordx4 v191, s[26:27]
	s_mov_b32 m0, s28
	s_waitcnt lgkmcnt(3)
	v_mfma_f32_32x32x16_bf16 v[66:81], v[154:157], v[102:105], v[66:81]
	ds_read_b128 v[194:197], v185 offset:12288
	v_add_f32_e32 v193, v193, v48
	v_cvt_pk_bf16_f32 v149, v48, v49
	v_add_f32_e32 v193, v49, v193
	v_exp_f32_e32 v52, v52
	s_waitcnt lgkmcnt(3)
	v_mfma_f32_32x32x16_bf16 v[82:97], v[162:165], v[102:105], v[82:97]
	ds_read_b128 v[154:157], v185 offset:16384
	v_add_f32_e32 v193, v193, v50
	v_exp_f32_e32 v53, v53
	v_cvt_pk_bf16_f32 v142, v50, v51
	v_add_f32_e32 v193, v51, v193
	s_waitcnt lgkmcnt(3)
	v_mfma_f32_32x32x16_bf16 v[66:81], v[166:169], v[106:109], v[66:81]
	ds_read_b128 v[162:165], v187 offset:20480
	v_exp_f32_e32 v54, v54
	v_exp_f32_e32 v55, v55
	v_add_f32_e32 v193, v193, v52
	v_cvt_pk_bf16_f32 v143, v52, v53
	s_waitcnt lgkmcnt(3)
	v_mfma_f32_32x32x16_bf16 v[82:97], v[158:161], v[106:109], v[82:97]
	ds_read_b128 v[198:201], v187 offset:22528
	v_add_f32_e32 v166, v193, v53
	v_exp_f32_e32 v56, v56
	v_exp_f32_e32 v57, v57
	v_add_f32_e32 v166, v54, v166
	s_waitcnt lgkmcnt(3)
	v_mfma_f32_32x32x16_bf16 v[66:81], v[194:197], v[110:113], v[66:81]
	ds_read_b128 v[202:205], v188 offset:20480
	v_cvt_pk_bf16_f32 v144, v54, v55
	v_add_f32_e32 v159, v166, v55
	v_exp_f32_e32 v58, v58
	v_exp_f32_e32 v59, v59
	s_waitcnt lgkmcnt(3)
	v_mfma_f32_32x32x16_bf16 v[82:97], v[154:157], v[110:113], v[82:97]
	ds_read_b128 v[194:197], v188 offset:22528
	v_add_f32_e32 v158, v159, v56
	v_exp_f32_e32 v60, v60
	v_cvt_pk_bf16_f32 v145, v56, v57
	v_add_f32_e32 v158, v57, v158
	s_waitcnt lgkmcnt(3)
	v_mfma_f32_32x32x16_bf16 v[66:81], v[162:165], v[114:117], v[66:81]
	ds_read_b64_tr_b16 v[166:167], v189 offset:49152
	ds_read_b64_tr_b16 v[168:169], v189 offset:49664
	v_add_f32_e32 v154, v158, v58
	v_exp_f32_e32 v61, v61
	v_cvt_pk_bf16_f32 v138, v58, v59
	v_add_f32_e32 v154, v59, v154
	s_waitcnt lgkmcnt(4)
	v_mfma_f32_32x32x16_bf16 v[82:97], v[198:201], v[114:117], v[82:97]
	ds_read_b64_tr_b16 v[162:163], v189 offset:50176
	ds_read_b64_tr_b16 v[164:165], v189 offset:50688
	v_exp_f32_e32 v62, v62
	v_exp_f32_e32 v63, v63
	v_add_f32_e32 v154, v154, v60
	v_cvt_pk_bf16_f32 v139, v60, v61
	s_waitcnt lgkmcnt(5)
	v_mfma_f32_32x32x16_bf16 v[66:81], v[202:205], v[118:121], v[66:81]
	ds_read_b64_tr_b16 v[158:159], v189 offset:51200
	ds_read_b64_tr_b16 v[160:161], v189 offset:51712
	v_add_f32_e32 v154, v154, v61
	v_exp_f32_e32 v64, v64
	v_exp_f32_e32 v65, v65
	v_add_f32_e32 v198, v62, v154
	s_waitcnt lgkmcnt(6)
	v_mfma_f32_32x32x16_bf16 v[82:97], v[194:197], v[118:121], v[82:97]
	ds_read_b64_tr_b16 v[154:155], v189 offset:52224
	ds_read_b64_tr_b16 v[156:157], v189 offset:52736
	v_add_f32_e32 v141, v198, v63
	v_add_f32_e32 v198, v64, v141
	v_cvt_pk_bf16_f32 v140, v62, v63
	v_cvt_pk_bf16_f32 v141, v64, v65
	v_add_f32_e32 v194, v65, v198
	s_waitcnt vmcnt(4) lgkmcnt(0)
	s_barrier
	s_waitcnt lgkmcnt(6)
	v_mfma_f32_32x32x16_bf16 v[2:17], v[150:153], v[166:169], v[2:17]
	ds_read_b64_tr_b16 v[34:35], v189 offset:53248
	ds_read_b64_tr_b16 v[36:37], v189 offset:53760
	v_exp_f32_e32 v66, v66
	v_exp_f32_e32 v67, v67
	v_exp_f32_e32 v68, v68
	s_waitcnt lgkmcnt(6)
	v_mfma_f32_32x32x16_bf16 v[2:17], v[146:149], v[162:165], v[2:17]
	ds_read_b64_tr_b16 v[38:39], v189 offset:54272
	ds_read_b64_tr_b16 v[40:41], v189 offset:54784
	v_add_f32_e32 v42, v194, v66
	v_exp_f32_e32 v69, v69
	v_cvt_pk_bf16_f32 v134, v66, v67
	v_add_f32_e32 v46, v67, v42
	s_waitcnt lgkmcnt(6)
	v_mfma_f32_32x32x16_bf16 v[2:17], v[142:145], v[158:161], v[2:17]
	ds_read_b64_tr_b16 v[42:43], v189 offset:55296
	ds_read_b64_tr_b16 v[44:45], v189 offset:55808
	v_exp_f32_e32 v70, v70
	v_exp_f32_e32 v71, v71
	v_add_f32_e32 v50, v46, v68
	v_cvt_pk_bf16_f32 v135, v68, v69
	s_waitcnt lgkmcnt(6)
	v_mfma_f32_32x32x16_bf16 v[2:17], v[138:141], v[154:157], v[2:17]
	ds_read_b64_tr_b16 v[46:47], v189 offset:56320
	ds_read_b64_tr_b16 v[48:49], v189 offset:56832
	v_add_f32_e32 v50, v50, v69
	v_exp_f32_e32 v72, v72
	v_exp_f32_e32 v73, v73
	v_add_f32_e32 v54, v70, v50
	s_waitcnt lgkmcnt(6)
	v_mfma_f32_32x32x16_bf16 v[18:33], v[150:153], v[34:37], v[18:33]
	ds_read_b128 v[50:53], v182 offset:24576
	v_cvt_pk_bf16_f32 v136, v70, v71
	v_add_f32_e32 v58, v54, v71
	v_exp_f32_e32 v74, v74
	v_exp_f32_e32 v75, v75
	s_waitcnt lgkmcnt(5)
	v_mfma_f32_32x32x16_bf16 v[18:33], v[146:149], v[38:41], v[18:33]
	ds_read_b128 v[54:57], v182 offset:28672
	v_add_f32_e32 v34, v58, v72
	v_exp_f32_e32 v76, v76
	v_cvt_pk_bf16_f32 v137, v72, v73
	v_add_f32_e32 v34, v73, v34
	s_waitcnt lgkmcnt(4)
	v_mfma_f32_32x32x16_bf16 v[18:33], v[142:145], v[42:45], v[18:33]
	ds_read_b128 v[154:157], v183 offset:24576
	v_add_f32_e32 v34, v34, v74
	v_exp_f32_e32 v77, v77
	v_cvt_pk_bf16_f32 v130, v74, v75
	v_add_f32_e32 v34, v75, v34
	s_waitcnt lgkmcnt(3)
	v_mfma_f32_32x32x16_bf16 v[18:33], v[138:141], v[46:49], v[18:33]
	ds_read_b128 v[162:165], v183 offset:28672
	v_exp_f32_e32 v78, v78
	v_exp_f32_e32 v79, v79
	v_add_f32_e32 v34, v34, v76
	v_cvt_pk_bf16_f32 v131, v76, v77
	s_nop 0
	v_add_f32_e32 v34, v34, v77
	v_add_f32_e32 v59, v78, v34
	s_waitcnt lgkmcnt(3)
	v_mfma_f32_32x32x16_bf16 v[34:49], v[50:53], v[98:101], 0
	ds_read_b128 v[166:169], v184 offset:24576
	v_exp_f32_e32 v80, v80
	v_exp_f32_e32 v81, v81
	ds_read_b128 v[158:161], v184 offset:28672
	v_add_f32_e32 v193, v59, v79
	s_waitcnt lgkmcnt(4)
	v_mfma_f32_32x32x16_bf16 v[50:65], v[54:57], v[98:101], 0
	v_exp_f32_e32 v82, v82
	v_exp_f32_e32 v83, v83
	v_cvt_pk_bf16_f32 v132, v78, v79
	s_add_i32 s26, 0x3000, s8
	s_add_i32 s28, 0x6000, s12
	s_nop 4
	s_mov_b32 s24, m0
	s_mov_b32 m0, s26
	s_nop 0
	global_load_lds_dwordx4 v174, s[20:21]
	s_mov_b32 m0, s28
	s_nop 0
	global_load_lds_dwordx4 v191, s[20:21]
	s_mov_b32 m0, s24
	s_waitcnt lgkmcnt(3)
	v_mfma_f32_32x32x16_bf16 v[34:49], v[154:157], v[102:105], v[34:49]
	ds_read_b128 v[194:197], v185 offset:24576
	v_add_f32_e32 v154, v193, v80
	v_exp_f32_e32 v84, v84
	v_cvt_pk_bf16_f32 v133, v80, v81
	v_add_f32_e32 v193, v81, v154
	s_waitcnt lgkmcnt(3)
	v_mfma_f32_32x32x16_bf16 v[50:65], v[162:165], v[102:105], v[50:65]
	ds_read_b128 v[154:157], v185 offset:28672
	v_add_f32_e32 v193, v193, v82
	v_exp_f32_e32 v85, v85
	v_cvt_pk_bf16_f32 v126, v82, v83
	v_add_f32_e32 v193, v83, v193
	s_waitcnt lgkmcnt(3)
	v_mfma_f32_32x32x16_bf16 v[34:49], v[166:169], v[106:109], v[34:49]
	ds_read_b128 v[162:165], v187 offset:32768
	v_exp_f32_e32 v86, v86
	v_exp_f32_e32 v87, v87
	v_add_f32_e32 v193, v193, v84
	v_cvt_pk_bf16_f32 v127, v84, v85
	s_waitcnt lgkmcnt(3)
	v_mfma_f32_32x32x16_bf16 v[50:65], v[158:161], v[106:109], v[50:65]
	ds_read_b128 v[198:201], v187 offset:34816
	v_add_f32_e32 v166, v193, v85
	v_exp_f32_e32 v88, v88
	v_exp_f32_e32 v89, v89
	v_add_f32_e32 v166, v86, v166
	s_waitcnt lgkmcnt(3)
	v_mfma_f32_32x32x16_bf16 v[34:49], v[194:197], v[110:113], v[34:49]
	ds_read_b128 v[202:205], v188 offset:32768
	v_cvt_pk_bf16_f32 v128, v86, v87
	v_add_f32_e32 v159, v166, v87
	v_exp_f32_e32 v90, v90
	v_exp_f32_e32 v91, v91
	s_waitcnt lgkmcnt(3)
	v_mfma_f32_32x32x16_bf16 v[50:65], v[154:157], v[110:113], v[50:65]
	ds_read_b128 v[194:197], v188 offset:34816
	v_add_f32_e32 v158, v159, v88
	v_exp_f32_e32 v92, v92
	v_cvt_pk_bf16_f32 v129, v88, v89
	v_add_f32_e32 v158, v89, v158
	s_waitcnt lgkmcnt(3)
	v_mfma_f32_32x32x16_bf16 v[34:49], v[162:165], v[114:117], v[34:49]
	ds_read_b64_tr_b16 v[166:167], v189 offset:57344
	ds_read_b64_tr_b16 v[168:169], v189 offset:57856
	v_add_f32_e32 v154, v158, v90
	v_exp_f32_e32 v93, v93
	v_cvt_pk_bf16_f32 v122, v90, v91
	v_add_f32_e32 v154, v91, v154
	s_waitcnt lgkmcnt(4)
	v_mfma_f32_32x32x16_bf16 v[50:65], v[198:201], v[114:117], v[50:65]
	ds_read_b64_tr_b16 v[162:163], v189 offset:58368
	ds_read_b64_tr_b16 v[164:165], v189 offset:58880
	v_exp_f32_e32 v94, v94
	v_exp_f32_e32 v95, v95
	v_add_f32_e32 v154, v154, v92
	v_cvt_pk_bf16_f32 v123, v92, v93
	s_waitcnt lgkmcnt(5)
	v_mfma_f32_32x32x16_bf16 v[34:49], v[202:205], v[118:121], v[34:49]
	ds_read_b64_tr_b16 v[158:159], v189 offset:59392
	ds_read_b64_tr_b16 v[160:161], v189 offset:59904
	v_add_f32_e32 v154, v154, v93
	v_exp_f32_e32 v96, v96
	v_exp_f32_e32 v97, v97
	v_add_f32_e32 v193, v94, v154
	s_waitcnt lgkmcnt(6)
	v_mfma_f32_32x32x16_bf16 v[50:65], v[194:197], v[118:121], v[50:65]
	ds_read_b64_tr_b16 v[154:155], v189 offset:60416
	ds_read_b64_tr_b16 v[156:157], v189 offset:60928
	v_add_f32_e32 v125, v193, v95
	v_add_f32_e32 v193, v96, v125
	v_cvt_pk_bf16_f32 v124, v94, v95
	v_cvt_pk_bf16_f32 v125, v96, v97
	v_add_f32_e32 v193, v97, v193
	s_add_u32 s22, s22, 0x2000
	s_addc_u32 s23, s23, 0
	s_add_u32 s20, s20, 0x40000
	s_addc_u32 s21, s21, 0
	s_waitcnt vmcnt(4) lgkmcnt(0)
	s_barrier
	s_waitcnt lgkmcnt(6)
	v_mfma_f32_32x32x16_bf16 v[2:17], v[134:137], v[166:169], v[2:17]
	ds_read_b64_tr_b16 v[66:67], v189 offset:61440
	ds_read_b64_tr_b16 v[68:69], v189 offset:61952
	v_exp_f32_e32 v34, v34
	v_exp_f32_e32 v35, v35
	v_exp_f32_e32 v36, v36
	s_waitcnt lgkmcnt(6)
	v_mfma_f32_32x32x16_bf16 v[2:17], v[130:133], v[162:165], v[2:17]
	ds_read_b64_tr_b16 v[70:71], v189 offset:62464
	ds_read_b64_tr_b16 v[72:73], v189 offset:62976
	v_add_f32_e32 v74, v193, v34
	v_exp_f32_e32 v37, v37
	v_cvt_pk_bf16_f32 v150, v34, v35
	v_add_f32_e32 v78, v35, v74
	s_waitcnt lgkmcnt(6)
	v_mfma_f32_32x32x16_bf16 v[2:17], v[126:129], v[158:161], v[2:17]
	ds_read_b64_tr_b16 v[74:75], v189 offset:63488
	ds_read_b64_tr_b16 v[76:77], v189 offset:64000
	v_exp_f32_e32 v38, v38
	v_exp_f32_e32 v39, v39
	v_add_f32_e32 v82, v78, v36
	v_cvt_pk_bf16_f32 v151, v36, v37
	s_waitcnt lgkmcnt(6)
	v_mfma_f32_32x32x16_bf16 v[2:17], v[122:125], v[154:157], v[2:17]
	ds_read_b64_tr_b16 v[78:79], v189 offset:64512
	ds_read_b64_tr_b16 v[80:81], v189 offset:65024
	v_add_f32_e32 v82, v82, v37
	v_exp_f32_e32 v40, v40
	v_exp_f32_e32 v41, v41
	v_add_f32_e32 v86, v38, v82
	s_waitcnt lgkmcnt(6)
	v_mfma_f32_32x32x16_bf16 v[18:33], v[134:137], v[66:69], v[18:33]
	ds_read_b128 v[82:85], v182 offset:36864
	v_cvt_pk_bf16_f32 v152, v38, v39
	v_add_f32_e32 v90, v86, v39
	v_exp_f32_e32 v42, v42
	v_exp_f32_e32 v43, v43
	s_waitcnt lgkmcnt(5)
	v_mfma_f32_32x32x16_bf16 v[18:33], v[130:133], v[70:73], v[18:33]
	ds_read_b128 v[86:89], v182 offset:40960
	v_add_f32_e32 v66, v90, v40
	v_exp_f32_e32 v44, v44
	v_cvt_pk_bf16_f32 v153, v40, v41
	v_add_f32_e32 v66, v41, v66
	s_waitcnt lgkmcnt(4)
	v_mfma_f32_32x32x16_bf16 v[18:33], v[126:129], v[74:77], v[18:33]
	ds_read_b128 v[154:157], v183 offset:36864
	v_add_f32_e32 v66, v66, v42
	v_exp_f32_e32 v45, v45
	v_cvt_pk_bf16_f32 v146, v42, v43
	v_add_f32_e32 v66, v43, v66
	s_waitcnt lgkmcnt(3)
	v_mfma_f32_32x32x16_bf16 v[18:33], v[122:125], v[78:81], v[18:33]
	ds_read_b128 v[162:165], v183 offset:40960
	v_exp_f32_e32 v46, v46
	v_exp_f32_e32 v47, v47
	v_add_f32_e32 v66, v66, v44
	v_cvt_pk_bf16_f32 v147, v44, v45
	s_nop 0
	v_add_f32_e32 v66, v66, v45
	v_add_f32_e32 v91, v46, v66
	s_waitcnt lgkmcnt(3)
	v_mfma_f32_32x32x16_bf16 v[66:81], v[82:85], v[98:101], 0
	ds_read_b128 v[166:169], v184 offset:36864
	v_exp_f32_e32 v48, v48
	v_exp_f32_e32 v49, v49
	ds_read_b128 v[158:161], v184 offset:40960
	v_add_f32_e32 v193, v91, v47
	s_waitcnt lgkmcnt(4)
	v_mfma_f32_32x32x16_bf16 v[82:97], v[86:89], v[98:101], 0
	v_exp_f32_e32 v50, v50
	v_exp_f32_e32 v51, v51
	v_cvt_pk_bf16_f32 v148, v46, v47
	s_add_u32 s26, s20, 0xfffe0000
	s_addc_u32 s27, s21, -1
	s_add_i32 s31, 0x6000, s8
	s_add_i32 s33, 0x8000, s12
	s_nop 4
	s_mov_b32 s28, m0
	s_mov_b32 m0, s31
	s_nop 0
	global_load_lds_dwordx4 v174, s[26:27]
	s_mov_b32 m0, s33
	s_nop 0
	global_load_lds_dwordx4 v191, s[26:27]
	s_mov_b32 m0, s28
	s_waitcnt lgkmcnt(3)
	v_mfma_f32_32x32x16_bf16 v[66:81], v[154:157], v[102:105], v[66:81]
	ds_read_b128 v[194:197], v185 offset:36864
	v_add_f32_e32 v193, v193, v48
	v_cvt_pk_bf16_f32 v149, v48, v49
	v_add_f32_e32 v193, v49, v193
	v_exp_f32_e32 v52, v52
	s_waitcnt lgkmcnt(3)
	v_mfma_f32_32x32x16_bf16 v[82:97], v[162:165], v[102:105], v[82:97]
	ds_read_b128 v[154:157], v185 offset:40960
	v_add_f32_e32 v193, v193, v50
	v_exp_f32_e32 v53, v53
	v_cvt_pk_bf16_f32 v142, v50, v51
	v_add_f32_e32 v193, v51, v193
	s_waitcnt lgkmcnt(3)
	v_mfma_f32_32x32x16_bf16 v[66:81], v[166:169], v[106:109], v[66:81]
	ds_read_b128 v[162:165], v187 offset:45056
	v_exp_f32_e32 v54, v54
	v_exp_f32_e32 v55, v55
	v_add_f32_e32 v193, v193, v52
	v_cvt_pk_bf16_f32 v143, v52, v53
	s_waitcnt lgkmcnt(3)
	v_mfma_f32_32x32x16_bf16 v[82:97], v[158:161], v[106:109], v[82:97]
	ds_read_b128 v[198:201], v187 offset:47104
	v_add_f32_e32 v166, v193, v53
	v_exp_f32_e32 v56, v56
	v_exp_f32_e32 v57, v57
	v_add_f32_e32 v166, v54, v166
	s_waitcnt lgkmcnt(3)
	v_mfma_f32_32x32x16_bf16 v[66:81], v[194:197], v[110:113], v[66:81]
	ds_read_b128 v[202:205], v188 offset:45056
	v_cvt_pk_bf16_f32 v144, v54, v55
	v_add_f32_e32 v159, v166, v55
	v_exp_f32_e32 v58, v58
	v_exp_f32_e32 v59, v59
	s_waitcnt lgkmcnt(3)
	v_mfma_f32_32x32x16_bf16 v[82:97], v[154:157], v[110:113], v[82:97]
	ds_read_b128 v[194:197], v188 offset:47104
	v_add_f32_e32 v158, v159, v56
	v_exp_f32_e32 v60, v60
	v_cvt_pk_bf16_f32 v145, v56, v57
	v_add_f32_e32 v158, v57, v158
	s_waitcnt lgkmcnt(3)
	v_mfma_f32_32x32x16_bf16 v[66:81], v[162:165], v[114:117], v[66:81]
	ds_read_b64_tr_b16 v[166:167], v189 offset:16384
	ds_read_b64_tr_b16 v[168:169], v189 offset:16896
	v_add_f32_e32 v154, v158, v58
	v_exp_f32_e32 v61, v61
	v_cvt_pk_bf16_f32 v138, v58, v59
	v_add_f32_e32 v154, v59, v154
	s_waitcnt lgkmcnt(4)
	v_mfma_f32_32x32x16_bf16 v[82:97], v[198:201], v[114:117], v[82:97]
	ds_read_b64_tr_b16 v[162:163], v189 offset:17408
	ds_read_b64_tr_b16 v[164:165], v189 offset:17920
	v_exp_f32_e32 v62, v62
	v_exp_f32_e32 v63, v63
	v_add_f32_e32 v154, v154, v60
	v_cvt_pk_bf16_f32 v139, v60, v61
	s_waitcnt lgkmcnt(5)
	v_mfma_f32_32x32x16_bf16 v[66:81], v[202:205], v[118:121], v[66:81]
	ds_read_b64_tr_b16 v[158:159], v189 offset:18432
	ds_read_b64_tr_b16 v[160:161], v189 offset:18944
	v_add_f32_e32 v154, v154, v61
	v_exp_f32_e32 v64, v64
	v_exp_f32_e32 v65, v65
	v_add_f32_e32 v198, v62, v154
	s_waitcnt lgkmcnt(6)
	v_mfma_f32_32x32x16_bf16 v[82:97], v[194:197], v[118:121], v[82:97]
	ds_read_b64_tr_b16 v[154:155], v189 offset:19456
	ds_read_b64_tr_b16 v[156:157], v189 offset:19968
	v_add_f32_e32 v141, v198, v63
	v_add_f32_e32 v198, v64, v141
	v_cvt_pk_bf16_f32 v140, v62, v63
	v_cvt_pk_bf16_f32 v141, v64, v65
	v_add_f32_e32 v194, v65, v198
	s_waitcnt vmcnt(4) lgkmcnt(0)
	s_barrier
	s_waitcnt lgkmcnt(6)
	v_mfma_f32_32x32x16_bf16 v[2:17], v[150:153], v[166:169], v[2:17]
	ds_read_b64_tr_b16 v[34:35], v189 offset:20480
	ds_read_b64_tr_b16 v[36:37], v189 offset:20992
	v_exp_f32_e32 v66, v66
	v_exp_f32_e32 v67, v67
	v_exp_f32_e32 v68, v68
	s_waitcnt lgkmcnt(6)
	v_mfma_f32_32x32x16_bf16 v[2:17], v[146:149], v[162:165], v[2:17]
	ds_read_b64_tr_b16 v[38:39], v189 offset:21504
	ds_read_b64_tr_b16 v[40:41], v189 offset:22016
	v_add_f32_e32 v42, v194, v66
	v_exp_f32_e32 v69, v69
	v_cvt_pk_bf16_f32 v134, v66, v67
	v_add_f32_e32 v46, v67, v42
	s_waitcnt lgkmcnt(6)
	v_mfma_f32_32x32x16_bf16 v[2:17], v[142:145], v[158:161], v[2:17]
	ds_read_b64_tr_b16 v[42:43], v189 offset:22528
	ds_read_b64_tr_b16 v[44:45], v189 offset:23040
	v_exp_f32_e32 v70, v70
	v_exp_f32_e32 v71, v71
	v_add_f32_e32 v50, v46, v68
	v_cvt_pk_bf16_f32 v135, v68, v69
	s_waitcnt lgkmcnt(6)
	v_mfma_f32_32x32x16_bf16 v[2:17], v[138:141], v[154:157], v[2:17]
	ds_read_b64_tr_b16 v[46:47], v189 offset:23552
	ds_read_b64_tr_b16 v[48:49], v189 offset:24064
	v_add_f32_e32 v50, v50, v69
	v_exp_f32_e32 v72, v72
	v_exp_f32_e32 v73, v73
	v_add_f32_e32 v54, v70, v50
	s_waitcnt lgkmcnt(6)
	v_mfma_f32_32x32x16_bf16 v[18:33], v[150:153], v[34:37], v[18:33]
	ds_read_b128 v[50:53], v182
	v_cvt_pk_bf16_f32 v136, v70, v71
	v_add_f32_e32 v58, v54, v71
	v_exp_f32_e32 v74, v74
	v_exp_f32_e32 v75, v75
	s_waitcnt lgkmcnt(5)
	v_mfma_f32_32x32x16_bf16 v[18:33], v[146:149], v[38:41], v[18:33]
	ds_read_b128 v[54:57], v182 offset:4096
	v_add_f32_e32 v34, v58, v72
	v_exp_f32_e32 v76, v76
	v_cvt_pk_bf16_f32 v137, v72, v73
	v_add_f32_e32 v34, v73, v34
	s_waitcnt lgkmcnt(4)
	v_mfma_f32_32x32x16_bf16 v[18:33], v[142:145], v[42:45], v[18:33]
	ds_read_b128 v[154:157], v183
	v_add_f32_e32 v34, v34, v74
	v_exp_f32_e32 v77, v77
	v_cvt_pk_bf16_f32 v130, v74, v75
	v_add_f32_e32 v34, v75, v34
	s_waitcnt lgkmcnt(3)
	v_mfma_f32_32x32x16_bf16 v[18:33], v[138:141], v[46:49], v[18:33]
	ds_read_b128 v[162:165], v183 offset:4096
	v_exp_f32_e32 v78, v78
	v_exp_f32_e32 v79, v79
	v_add_f32_e32 v34, v34, v76
	v_cvt_pk_bf16_f32 v131, v76, v77
	s_nop 0
	v_add_f32_e32 v34, v34, v77
	v_add_f32_e32 v59, v78, v34
	s_waitcnt lgkmcnt(3)
	v_mfma_f32_32x32x16_bf16 v[34:49], v[50:53], v[98:101], 0
	ds_read_b128 v[166:169], v184
	v_exp_f32_e32 v80, v80
	v_exp_f32_e32 v81, v81
	ds_read_b128 v[158:161], v184 offset:4096
	v_add_f32_e32 v193, v59, v79
	s_waitcnt lgkmcnt(4)
	v_mfma_f32_32x32x16_bf16 v[50:65], v[54:57], v[98:101], 0
	v_exp_f32_e32 v82, v82
	v_exp_f32_e32 v83, v83
	v_cvt_pk_bf16_f32 v132, v78, v79
	s_add_i32 s26, 0x9000, s8
	s_add_i32 s28, 0xa000, s12
	s_nop 4
	s_mov_b32 s24, m0
	s_mov_b32 m0, s26
	s_nop 0
	global_load_lds_dwordx4 v174, s[20:21]
	s_mov_b32 m0, s28
	s_nop 0
	global_load_lds_dwordx4 v191, s[20:21]
	s_mov_b32 m0, s24
	s_waitcnt lgkmcnt(3)
	v_mfma_f32_32x32x16_bf16 v[34:49], v[154:157], v[102:105], v[34:49]
	ds_read_b128 v[194:197], v185
	v_add_f32_e32 v154, v193, v80
	v_exp_f32_e32 v84, v84
	v_cvt_pk_bf16_f32 v133, v80, v81
	v_add_f32_e32 v193, v81, v154
	s_waitcnt lgkmcnt(3)
	v_mfma_f32_32x32x16_bf16 v[50:65], v[162:165], v[102:105], v[50:65]
	ds_read_b128 v[154:157], v185 offset:4096
	v_add_f32_e32 v193, v193, v82
	v_exp_f32_e32 v85, v85
	v_cvt_pk_bf16_f32 v126, v82, v83
	v_add_f32_e32 v193, v83, v193
	s_waitcnt lgkmcnt(3)
	v_mfma_f32_32x32x16_bf16 v[34:49], v[166:169], v[106:109], v[34:49]
	ds_read_b128 v[162:165], v187 offset:8192
	v_exp_f32_e32 v86, v86
	v_exp_f32_e32 v87, v87
	v_add_f32_e32 v193, v193, v84
	v_cvt_pk_bf16_f32 v127, v84, v85
	s_waitcnt lgkmcnt(3)
	v_mfma_f32_32x32x16_bf16 v[50:65], v[158:161], v[106:109], v[50:65]
	ds_read_b128 v[198:201], v187 offset:10240
	v_add_f32_e32 v166, v193, v85
	v_exp_f32_e32 v88, v88
	v_exp_f32_e32 v89, v89
	v_add_f32_e32 v166, v86, v166
	s_waitcnt lgkmcnt(3)
	v_mfma_f32_32x32x16_bf16 v[34:49], v[194:197], v[110:113], v[34:49]
	ds_read_b128 v[202:205], v188 offset:8192
	v_cvt_pk_bf16_f32 v128, v86, v87
	v_add_f32_e32 v159, v166, v87
	v_exp_f32_e32 v90, v90
	v_exp_f32_e32 v91, v91
	s_waitcnt lgkmcnt(3)
	v_mfma_f32_32x32x16_bf16 v[50:65], v[154:157], v[110:113], v[50:65]
	ds_read_b128 v[194:197], v188 offset:10240
	v_add_f32_e32 v158, v159, v88
	v_exp_f32_e32 v92, v92
	v_cvt_pk_bf16_f32 v129, v88, v89
	v_add_f32_e32 v158, v89, v158
	s_waitcnt lgkmcnt(3)
	v_mfma_f32_32x32x16_bf16 v[34:49], v[162:165], v[114:117], v[34:49]
	ds_read_b64_tr_b16 v[166:167], v189 offset:24576
	ds_read_b64_tr_b16 v[168:169], v189 offset:25088
	v_add_f32_e32 v154, v158, v90
	v_exp_f32_e32 v93, v93
	v_cvt_pk_bf16_f32 v122, v90, v91
	v_add_f32_e32 v154, v91, v154
	s_waitcnt lgkmcnt(4)
	v_mfma_f32_32x32x16_bf16 v[50:65], v[198:201], v[114:117], v[50:65]
	ds_read_b64_tr_b16 v[162:163], v189 offset:25600
	ds_read_b64_tr_b16 v[164:165], v189 offset:26112
	v_exp_f32_e32 v94, v94
	v_exp_f32_e32 v95, v95
	v_add_f32_e32 v154, v154, v92
	v_cvt_pk_bf16_f32 v123, v92, v93
	s_waitcnt lgkmcnt(5)
	v_mfma_f32_32x32x16_bf16 v[34:49], v[202:205], v[118:121], v[34:49]
	ds_read_b64_tr_b16 v[158:159], v189 offset:26624
	ds_read_b64_tr_b16 v[160:161], v189 offset:27136
	v_add_f32_e32 v154, v154, v93
	v_exp_f32_e32 v96, v96
	v_exp_f32_e32 v97, v97
	v_add_f32_e32 v193, v94, v154
	s_waitcnt lgkmcnt(6)
	v_mfma_f32_32x32x16_bf16 v[50:65], v[194:197], v[118:121], v[50:65]
	ds_read_b64_tr_b16 v[154:155], v189 offset:27648
	ds_read_b64_tr_b16 v[156:157], v189 offset:28160
	v_add_f32_e32 v125, v193, v95
	v_add_f32_e32 v193, v96, v125
	v_cvt_pk_bf16_f32 v124, v94, v95
	v_cvt_pk_bf16_f32 v125, v96, v97
	v_add_f32_e32 v193, v97, v193
	s_add_u32 s22, s22, 0x2000
	s_addc_u32 s23, s23, 0
	s_add_u32 s20, s20, 0x40000
	s_addc_u32 s21, s21, 0
	s_waitcnt vmcnt(4) lgkmcnt(0)
	s_barrier
	s_waitcnt lgkmcnt(6)
	v_mfma_f32_32x32x16_bf16 v[2:17], v[134:137], v[166:169], v[2:17]
	ds_read_b64_tr_b16 v[66:67], v189 offset:28672
	ds_read_b64_tr_b16 v[68:69], v189 offset:29184
	v_exp_f32_e32 v34, v34
	v_exp_f32_e32 v35, v35
	v_exp_f32_e32 v36, v36
	s_waitcnt lgkmcnt(6)
	v_mfma_f32_32x32x16_bf16 v[2:17], v[130:133], v[162:165], v[2:17]
	ds_read_b64_tr_b16 v[70:71], v189 offset:29696
	ds_read_b64_tr_b16 v[72:73], v189 offset:30208
	v_add_f32_e32 v74, v193, v34
	v_exp_f32_e32 v37, v37
	v_cvt_pk_bf16_f32 v150, v34, v35
	v_add_f32_e32 v78, v35, v74
	s_waitcnt lgkmcnt(6)
	v_mfma_f32_32x32x16_bf16 v[2:17], v[126:129], v[158:161], v[2:17]
	ds_read_b64_tr_b16 v[74:75], v189 offset:30720
	ds_read_b64_tr_b16 v[76:77], v189 offset:31232
	v_exp_f32_e32 v38, v38
	v_exp_f32_e32 v39, v39
	v_add_f32_e32 v82, v78, v36
	v_cvt_pk_bf16_f32 v151, v36, v37
	s_waitcnt lgkmcnt(6)
	v_mfma_f32_32x32x16_bf16 v[2:17], v[122:125], v[154:157], v[2:17]
	ds_read_b64_tr_b16 v[78:79], v189 offset:31744
	ds_read_b64_tr_b16 v[80:81], v189 offset:32256
	v_add_f32_e32 v82, v82, v37
	v_exp_f32_e32 v40, v40
	v_exp_f32_e32 v41, v41
	v_add_f32_e32 v86, v38, v82
	s_waitcnt lgkmcnt(6)
	v_mfma_f32_32x32x16_bf16 v[18:33], v[134:137], v[66:69], v[18:33]
	ds_read_b128 v[82:85], v182 offset:12288
	v_cvt_pk_bf16_f32 v152, v38, v39
	v_add_f32_e32 v90, v86, v39
	v_exp_f32_e32 v42, v42
	v_exp_f32_e32 v43, v43
	s_waitcnt lgkmcnt(5)
	v_mfma_f32_32x32x16_bf16 v[18:33], v[130:133], v[70:73], v[18:33]
	ds_read_b128 v[86:89], v182 offset:16384
	v_add_f32_e32 v66, v90, v40
	v_exp_f32_e32 v44, v44
	v_cvt_pk_bf16_f32 v153, v40, v41
	v_add_f32_e32 v66, v41, v66
	s_waitcnt lgkmcnt(4)
	v_mfma_f32_32x32x16_bf16 v[18:33], v[126:129], v[74:77], v[18:33]
	ds_read_b128 v[154:157], v183 offset:12288
	v_add_f32_e32 v66, v66, v42
	v_exp_f32_e32 v45, v45
	v_cvt_pk_bf16_f32 v146, v42, v43
	v_add_f32_e32 v66, v43, v66
	s_waitcnt lgkmcnt(3)
	v_mfma_f32_32x32x16_bf16 v[18:33], v[122:125], v[78:81], v[18:33]
	ds_read_b128 v[162:165], v183 offset:16384
	v_exp_f32_e32 v46, v46
	v_exp_f32_e32 v47, v47
	v_add_f32_e32 v66, v66, v44
	v_cvt_pk_bf16_f32 v147, v44, v45
	s_nop 0
	v_add_f32_e32 v66, v66, v45
	v_add_f32_e32 v91, v46, v66
	s_waitcnt lgkmcnt(3)
	v_mfma_f32_32x32x16_bf16 v[66:81], v[82:85], v[98:101], 0
	ds_read_b128 v[166:169], v184 offset:12288
	v_exp_f32_e32 v48, v48
	v_exp_f32_e32 v49, v49
	ds_read_b128 v[158:161], v184 offset:16384
	v_add_f32_e32 v193, v91, v47
	s_waitcnt lgkmcnt(4)
	v_mfma_f32_32x32x16_bf16 v[82:97], v[86:89], v[98:101], 0
	v_exp_f32_e32 v50, v50
	v_exp_f32_e32 v51, v51
	v_cvt_pk_bf16_f32 v148, v46, v47
	s_add_u32 s26, s20, 0xfffe0000
	s_addc_u32 s27, s21, -1
	s_add_i32 s31, 0, s8
	s_add_i32 s33, 0, s12
	s_nop 4
	s_mov_b32 s28, m0
	s_mov_b32 m0, s31
	s_nop 0
	global_load_lds_dwordx4 v174, s[26:27]
	s_mov_b32 m0, s33
	s_nop 0
	global_load_lds_dwordx4 v191, s[26:27]
	s_mov_b32 m0, s28
	s_waitcnt lgkmcnt(3)
	v_mfma_f32_32x32x16_bf16 v[66:81], v[154:157], v[102:105], v[66:81]
	ds_read_b128 v[194:197], v185 offset:12288
	v_add_f32_e32 v193, v193, v48
	v_cvt_pk_bf16_f32 v149, v48, v49
	v_add_f32_e32 v193, v49, v193
	v_exp_f32_e32 v52, v52
	s_waitcnt lgkmcnt(3)
	v_mfma_f32_32x32x16_bf16 v[82:97], v[162:165], v[102:105], v[82:97]
	ds_read_b128 v[154:157], v185 offset:16384
	v_add_f32_e32 v193, v193, v50
	v_exp_f32_e32 v53, v53
	v_cvt_pk_bf16_f32 v142, v50, v51
	v_add_f32_e32 v193, v51, v193
	s_waitcnt lgkmcnt(3)
	v_mfma_f32_32x32x16_bf16 v[66:81], v[166:169], v[106:109], v[66:81]
	ds_read_b128 v[162:165], v187 offset:20480
	v_exp_f32_e32 v54, v54
	v_exp_f32_e32 v55, v55
	v_add_f32_e32 v193, v193, v52
	v_cvt_pk_bf16_f32 v143, v52, v53
	s_waitcnt lgkmcnt(3)
	v_mfma_f32_32x32x16_bf16 v[82:97], v[158:161], v[106:109], v[82:97]
	ds_read_b128 v[198:201], v187 offset:22528
	v_add_f32_e32 v166, v193, v53
	v_exp_f32_e32 v56, v56
	v_exp_f32_e32 v57, v57
	v_add_f32_e32 v166, v54, v166
	s_waitcnt lgkmcnt(3)
	v_mfma_f32_32x32x16_bf16 v[66:81], v[194:197], v[110:113], v[66:81]
	ds_read_b128 v[202:205], v188 offset:20480
	v_cvt_pk_bf16_f32 v144, v54, v55
	v_add_f32_e32 v159, v166, v55
	v_exp_f32_e32 v58, v58
	v_exp_f32_e32 v59, v59
	s_waitcnt lgkmcnt(3)
	v_mfma_f32_32x32x16_bf16 v[82:97], v[154:157], v[110:113], v[82:97]
	ds_read_b128 v[194:197], v188 offset:22528
	v_add_f32_e32 v158, v159, v56
	v_exp_f32_e32 v60, v60
	v_cvt_pk_bf16_f32 v145, v56, v57
	v_add_f32_e32 v158, v57, v158
	s_waitcnt lgkmcnt(3)
	v_mfma_f32_32x32x16_bf16 v[66:81], v[162:165], v[114:117], v[66:81]
	ds_read_b64_tr_b16 v[166:167], v189 offset:32768
	ds_read_b64_tr_b16 v[168:169], v189 offset:33280
	v_add_f32_e32 v154, v158, v58
	v_exp_f32_e32 v61, v61
	v_cvt_pk_bf16_f32 v138, v58, v59
	v_add_f32_e32 v154, v59, v154
	s_waitcnt lgkmcnt(4)
	v_mfma_f32_32x32x16_bf16 v[82:97], v[198:201], v[114:117], v[82:97]
	ds_read_b64_tr_b16 v[162:163], v189 offset:33792
	ds_read_b64_tr_b16 v[164:165], v189 offset:34304
	v_exp_f32_e32 v62, v62
	v_exp_f32_e32 v63, v63
	v_add_f32_e32 v154, v154, v60
	v_cvt_pk_bf16_f32 v139, v60, v61
	s_waitcnt lgkmcnt(5)
	v_mfma_f32_32x32x16_bf16 v[66:81], v[202:205], v[118:121], v[66:81]
	ds_read_b64_tr_b16 v[158:159], v189 offset:34816
	ds_read_b64_tr_b16 v[160:161], v189 offset:35328
	v_add_f32_e32 v154, v154, v61
	v_exp_f32_e32 v64, v64
	v_exp_f32_e32 v65, v65
	v_add_f32_e32 v198, v62, v154
	s_waitcnt lgkmcnt(6)
	v_mfma_f32_32x32x16_bf16 v[82:97], v[194:197], v[118:121], v[82:97]
	ds_read_b64_tr_b16 v[154:155], v189 offset:35840
	ds_read_b64_tr_b16 v[156:157], v189 offset:36352
	v_add_f32_e32 v141, v198, v63
	v_add_f32_e32 v198, v64, v141
	v_cvt_pk_bf16_f32 v140, v62, v63
	v_cvt_pk_bf16_f32 v141, v64, v65
	v_add_f32_e32 v194, v65, v198
	s_waitcnt vmcnt(4) lgkmcnt(0)
	s_barrier
	s_waitcnt lgkmcnt(6)
	v_mfma_f32_32x32x16_bf16 v[2:17], v[150:153], v[166:169], v[2:17]
	ds_read_b64_tr_b16 v[34:35], v189 offset:36864
	ds_read_b64_tr_b16 v[36:37], v189 offset:37376
	v_exp_f32_e32 v66, v66
	v_exp_f32_e32 v67, v67
	v_exp_f32_e32 v68, v68
	s_waitcnt lgkmcnt(6)
	v_mfma_f32_32x32x16_bf16 v[2:17], v[146:149], v[162:165], v[2:17]
	ds_read_b64_tr_b16 v[38:39], v189 offset:37888
	ds_read_b64_tr_b16 v[40:41], v189 offset:38400
	v_add_f32_e32 v42, v194, v66
	v_exp_f32_e32 v69, v69
	v_cvt_pk_bf16_f32 v134, v66, v67
	v_add_f32_e32 v46, v67, v42
	s_waitcnt lgkmcnt(6)
	v_mfma_f32_32x32x16_bf16 v[2:17], v[142:145], v[158:161], v[2:17]
	ds_read_b64_tr_b16 v[42:43], v189 offset:38912
	ds_read_b64_tr_b16 v[44:45], v189 offset:39424
	v_exp_f32_e32 v70, v70
	v_exp_f32_e32 v71, v71
	v_add_f32_e32 v50, v46, v68
	v_cvt_pk_bf16_f32 v135, v68, v69
	s_waitcnt lgkmcnt(6)
	v_mfma_f32_32x32x16_bf16 v[2:17], v[138:141], v[154:157], v[2:17]
	ds_read_b64_tr_b16 v[46:47], v189 offset:39936
	ds_read_b64_tr_b16 v[48:49], v189 offset:40448
	v_add_f32_e32 v50, v50, v69
	v_exp_f32_e32 v72, v72
	v_exp_f32_e32 v73, v73
	v_add_f32_e32 v54, v70, v50
	s_waitcnt lgkmcnt(6)
	v_mfma_f32_32x32x16_bf16 v[18:33], v[150:153], v[34:37], v[18:33]
	ds_read_b128 v[50:53], v182 offset:24576
	v_cvt_pk_bf16_f32 v136, v70, v71
	v_add_f32_e32 v58, v54, v71
	v_exp_f32_e32 v74, v74
	v_exp_f32_e32 v75, v75
	s_waitcnt lgkmcnt(5)
	v_mfma_f32_32x32x16_bf16 v[18:33], v[146:149], v[38:41], v[18:33]
	ds_read_b128 v[54:57], v182 offset:28672
	v_add_f32_e32 v34, v58, v72
	v_exp_f32_e32 v76, v76
	v_cvt_pk_bf16_f32 v137, v72, v73
	v_add_f32_e32 v34, v73, v34
	s_waitcnt lgkmcnt(4)
	v_mfma_f32_32x32x16_bf16 v[18:33], v[142:145], v[42:45], v[18:33]
	ds_read_b128 v[154:157], v183 offset:24576
	v_add_f32_e32 v34, v34, v74
	v_exp_f32_e32 v77, v77
	v_cvt_pk_bf16_f32 v130, v74, v75
	v_add_f32_e32 v34, v75, v34
	s_waitcnt lgkmcnt(3)
	v_mfma_f32_32x32x16_bf16 v[18:33], v[138:141], v[46:49], v[18:33]
	ds_read_b128 v[162:165], v183 offset:28672
	v_exp_f32_e32 v78, v78
	v_exp_f32_e32 v79, v79
	v_add_f32_e32 v34, v34, v76
	v_cvt_pk_bf16_f32 v131, v76, v77
	s_nop 0
	v_add_f32_e32 v34, v34, v77
	v_add_f32_e32 v59, v78, v34
	s_waitcnt lgkmcnt(3)
	v_mfma_f32_32x32x16_bf16 v[34:49], v[50:53], v[98:101], 0
	ds_read_b128 v[166:169], v184 offset:24576
	v_exp_f32_e32 v80, v80
	v_exp_f32_e32 v81, v81
	ds_read_b128 v[158:161], v184 offset:28672
	v_add_f32_e32 v193, v59, v79
	s_waitcnt lgkmcnt(4)
	v_mfma_f32_32x32x16_bf16 v[50:65], v[54:57], v[98:101], 0
	v_exp_f32_e32 v82, v82
	v_exp_f32_e32 v83, v83
	v_cvt_pk_bf16_f32 v132, v78, v79
	s_add_i32 s26, 0x3000, s8
	s_add_i32 s28, 0x2000, s12
	s_nop 4
	s_mov_b32 s24, m0
	s_mov_b32 m0, s26
	s_nop 0
	global_load_lds_dwordx4 v174, s[20:21]
	s_mov_b32 m0, s28
	s_nop 0
	global_load_lds_dwordx4 v191, s[20:21]
	s_mov_b32 m0, s24
	s_waitcnt lgkmcnt(3)
	v_mfma_f32_32x32x16_bf16 v[34:49], v[154:157], v[102:105], v[34:49]
	ds_read_b128 v[194:197], v185 offset:24576
	v_add_f32_e32 v154, v193, v80
	v_exp_f32_e32 v84, v84
	v_cvt_pk_bf16_f32 v133, v80, v81
	v_add_f32_e32 v193, v81, v154
	s_waitcnt lgkmcnt(3)
	v_mfma_f32_32x32x16_bf16 v[50:65], v[162:165], v[102:105], v[50:65]
	ds_read_b128 v[154:157], v185 offset:28672
	v_add_f32_e32 v193, v193, v82
	v_exp_f32_e32 v85, v85
	v_cvt_pk_bf16_f32 v126, v82, v83
	v_add_f32_e32 v193, v83, v193
	s_waitcnt lgkmcnt(3)
	v_mfma_f32_32x32x16_bf16 v[34:49], v[166:169], v[106:109], v[34:49]
	ds_read_b128 v[162:165], v187 offset:32768
	v_exp_f32_e32 v86, v86
	v_exp_f32_e32 v87, v87
	v_add_f32_e32 v193, v193, v84
	v_cvt_pk_bf16_f32 v127, v84, v85
	s_waitcnt lgkmcnt(3)
	v_mfma_f32_32x32x16_bf16 v[50:65], v[158:161], v[106:109], v[50:65]
	ds_read_b128 v[198:201], v187 offset:34816
	v_add_f32_e32 v166, v193, v85
	v_exp_f32_e32 v88, v88
	v_exp_f32_e32 v89, v89
	v_add_f32_e32 v166, v86, v166
	s_waitcnt lgkmcnt(3)
	v_mfma_f32_32x32x16_bf16 v[34:49], v[194:197], v[110:113], v[34:49]
	ds_read_b128 v[202:205], v188 offset:32768
	v_cvt_pk_bf16_f32 v128, v86, v87
	v_add_f32_e32 v159, v166, v87
	v_exp_f32_e32 v90, v90
	v_exp_f32_e32 v91, v91
	s_waitcnt lgkmcnt(3)
	v_mfma_f32_32x32x16_bf16 v[50:65], v[154:157], v[110:113], v[50:65]
	ds_read_b128 v[194:197], v188 offset:34816
	v_add_f32_e32 v158, v159, v88
	v_exp_f32_e32 v92, v92
	v_cvt_pk_bf16_f32 v129, v88, v89
	v_add_f32_e32 v158, v89, v158
	s_waitcnt lgkmcnt(3)
	v_mfma_f32_32x32x16_bf16 v[34:49], v[162:165], v[114:117], v[34:49]
	ds_read_b64_tr_b16 v[166:167], v189 offset:40960
	ds_read_b64_tr_b16 v[168:169], v189 offset:41472
	v_add_f32_e32 v154, v158, v90
	v_exp_f32_e32 v93, v93
	v_cvt_pk_bf16_f32 v122, v90, v91
	v_add_f32_e32 v154, v91, v154
	s_waitcnt lgkmcnt(4)
	v_mfma_f32_32x32x16_bf16 v[50:65], v[198:201], v[114:117], v[50:65]
	ds_read_b64_tr_b16 v[162:163], v189 offset:41984
	ds_read_b64_tr_b16 v[164:165], v189 offset:42496
	v_exp_f32_e32 v94, v94
	v_exp_f32_e32 v95, v95
	v_add_f32_e32 v154, v154, v92
	v_cvt_pk_bf16_f32 v123, v92, v93
	s_waitcnt lgkmcnt(5)
	v_mfma_f32_32x32x16_bf16 v[34:49], v[202:205], v[118:121], v[34:49]
	ds_read_b64_tr_b16 v[158:159], v189 offset:43008
	ds_read_b64_tr_b16 v[160:161], v189 offset:43520
	v_add_f32_e32 v154, v154, v93
	v_exp_f32_e32 v96, v96
	v_exp_f32_e32 v97, v97
	v_add_f32_e32 v193, v94, v154
	s_waitcnt lgkmcnt(6)
	v_mfma_f32_32x32x16_bf16 v[50:65], v[194:197], v[118:121], v[50:65]
	ds_read_b64_tr_b16 v[154:155], v189 offset:44032
	ds_read_b64_tr_b16 v[156:157], v189 offset:44544
	v_add_f32_e32 v125, v193, v95
	v_add_f32_e32 v193, v96, v125
	v_cvt_pk_bf16_f32 v124, v94, v95
	v_cvt_pk_bf16_f32 v125, v96, v97
	v_add_f32_e32 v193, v97, v193
	s_add_u32 s22, s22, 0x2000
	s_addc_u32 s23, s23, 0
	s_add_u32 s20, s20, 0x40000
	s_addc_u32 s21, s21, 0
	s_waitcnt vmcnt(4) lgkmcnt(0)
	s_barrier
	s_waitcnt lgkmcnt(6)
	v_mfma_f32_32x32x16_bf16 v[2:17], v[134:137], v[166:169], v[2:17]
	ds_read_b64_tr_b16 v[66:67], v189 offset:45056
	ds_read_b64_tr_b16 v[68:69], v189 offset:45568
	v_exp_f32_e32 v34, v34
	v_exp_f32_e32 v35, v35
	v_exp_f32_e32 v36, v36
	s_waitcnt lgkmcnt(6)
	v_mfma_f32_32x32x16_bf16 v[2:17], v[130:133], v[162:165], v[2:17]
	ds_read_b64_tr_b16 v[70:71], v189 offset:46080
	ds_read_b64_tr_b16 v[72:73], v189 offset:46592
	v_add_f32_e32 v74, v193, v34
	v_exp_f32_e32 v37, v37
	v_cvt_pk_bf16_f32 v150, v34, v35
	v_add_f32_e32 v78, v35, v74
	s_waitcnt lgkmcnt(6)
	v_mfma_f32_32x32x16_bf16 v[2:17], v[126:129], v[158:161], v[2:17]
	ds_read_b64_tr_b16 v[74:75], v189 offset:47104
	ds_read_b64_tr_b16 v[76:77], v189 offset:47616
	v_exp_f32_e32 v38, v38
	v_exp_f32_e32 v39, v39
	v_add_f32_e32 v82, v78, v36
	v_cvt_pk_bf16_f32 v151, v36, v37
	s_waitcnt lgkmcnt(6)
	v_mfma_f32_32x32x16_bf16 v[2:17], v[122:125], v[154:157], v[2:17]
	ds_read_b64_tr_b16 v[78:79], v189 offset:48128
	ds_read_b64_tr_b16 v[80:81], v189 offset:48640
	v_add_f32_e32 v82, v82, v37
	v_exp_f32_e32 v40, v40
	v_exp_f32_e32 v41, v41
	v_add_f32_e32 v86, v38, v82
	s_waitcnt lgkmcnt(6)
	v_mfma_f32_32x32x16_bf16 v[18:33], v[134:137], v[66:69], v[18:33]
	ds_read_b128 v[82:85], v182 offset:36864
	v_cvt_pk_bf16_f32 v152, v38, v39
	v_add_f32_e32 v90, v86, v39
	v_exp_f32_e32 v42, v42
	v_exp_f32_e32 v43, v43
	s_waitcnt lgkmcnt(5)
	v_mfma_f32_32x32x16_bf16 v[18:33], v[130:133], v[70:73], v[18:33]
	ds_read_b128 v[86:89], v182 offset:40960
	v_add_f32_e32 v66, v90, v40
	v_exp_f32_e32 v44, v44
	v_cvt_pk_bf16_f32 v153, v40, v41
	v_add_f32_e32 v66, v41, v66
	s_waitcnt lgkmcnt(4)
	v_mfma_f32_32x32x16_bf16 v[18:33], v[126:129], v[74:77], v[18:33]
	ds_read_b128 v[154:157], v183 offset:36864
	v_add_f32_e32 v66, v66, v42
	v_exp_f32_e32 v45, v45
	v_cvt_pk_bf16_f32 v146, v42, v43
	v_add_f32_e32 v66, v43, v66
	s_waitcnt lgkmcnt(3)
	v_mfma_f32_32x32x16_bf16 v[18:33], v[122:125], v[78:81], v[18:33]
	ds_read_b128 v[162:165], v183 offset:40960
	v_exp_f32_e32 v46, v46
	v_exp_f32_e32 v47, v47
	v_add_f32_e32 v66, v66, v44
	v_cvt_pk_bf16_f32 v147, v44, v45
	s_nop 0
	v_add_f32_e32 v66, v66, v45
	v_add_f32_e32 v91, v46, v66
	s_waitcnt lgkmcnt(3)
	v_mfma_f32_32x32x16_bf16 v[66:81], v[82:85], v[98:101], 0
	ds_read_b128 v[166:169], v184 offset:36864
	v_exp_f32_e32 v48, v48
	v_exp_f32_e32 v49, v49
	ds_read_b128 v[158:161], v184 offset:40960
	v_add_f32_e32 v193, v91, v47
	s_waitcnt lgkmcnt(4)
	v_mfma_f32_32x32x16_bf16 v[82:97], v[86:89], v[98:101], 0
	v_exp_f32_e32 v50, v50
	v_exp_f32_e32 v51, v51
	v_cvt_pk_bf16_f32 v148, v46, v47
	s_add_u32 s26, s20, 0xfffe0000
	s_addc_u32 s27, s21, -1
	s_add_i32 s31, 0x6000, s8
	s_add_i32 s33, 0x4000, s12
	s_nop 4
	s_mov_b32 s28, m0
	s_mov_b32 m0, s31
	s_nop 0
	global_load_lds_dwordx4 v174, s[26:27]
	s_mov_b32 m0, s33
	s_nop 0
	global_load_lds_dwordx4 v191, s[26:27]
	s_mov_b32 m0, s28
	s_waitcnt lgkmcnt(3)
	v_mfma_f32_32x32x16_bf16 v[66:81], v[154:157], v[102:105], v[66:81]
	ds_read_b128 v[194:197], v185 offset:36864
	v_add_f32_e32 v193, v193, v48
	v_cvt_pk_bf16_f32 v149, v48, v49
	v_add_f32_e32 v193, v49, v193
	v_exp_f32_e32 v52, v52
	s_waitcnt lgkmcnt(3)
	v_mfma_f32_32x32x16_bf16 v[82:97], v[162:165], v[102:105], v[82:97]
	ds_read_b128 v[154:157], v185 offset:40960
	v_add_f32_e32 v193, v193, v50
	v_exp_f32_e32 v53, v53
	v_cvt_pk_bf16_f32 v142, v50, v51
	v_add_f32_e32 v193, v51, v193
	s_waitcnt lgkmcnt(3)
	v_mfma_f32_32x32x16_bf16 v[66:81], v[166:169], v[106:109], v[66:81]
	ds_read_b128 v[162:165], v187 offset:45056
	v_exp_f32_e32 v54, v54
	v_exp_f32_e32 v55, v55
	v_add_f32_e32 v193, v193, v52
	v_cvt_pk_bf16_f32 v143, v52, v53
	s_waitcnt lgkmcnt(3)
	v_mfma_f32_32x32x16_bf16 v[82:97], v[158:161], v[106:109], v[82:97]
	ds_read_b128 v[198:201], v187 offset:47104
	v_add_f32_e32 v166, v193, v53
	v_exp_f32_e32 v56, v56
	v_exp_f32_e32 v57, v57
	v_add_f32_e32 v166, v54, v166
	s_waitcnt lgkmcnt(3)
	v_mfma_f32_32x32x16_bf16 v[66:81], v[194:197], v[110:113], v[66:81]
	ds_read_b128 v[202:205], v188 offset:45056
	v_cvt_pk_bf16_f32 v144, v54, v55
	v_add_f32_e32 v159, v166, v55
	v_exp_f32_e32 v58, v58
	v_exp_f32_e32 v59, v59
	s_waitcnt lgkmcnt(3)
	v_mfma_f32_32x32x16_bf16 v[82:97], v[154:157], v[110:113], v[82:97]
	ds_read_b128 v[194:197], v188 offset:47104
	v_add_f32_e32 v158, v159, v56
	v_exp_f32_e32 v60, v60
	v_cvt_pk_bf16_f32 v145, v56, v57
	v_add_f32_e32 v158, v57, v158
	s_waitcnt lgkmcnt(3)
	v_mfma_f32_32x32x16_bf16 v[66:81], v[162:165], v[114:117], v[66:81]
	ds_read_b64_tr_b16 v[166:167], v189 offset:49152
	ds_read_b64_tr_b16 v[168:169], v189 offset:49664
	v_add_f32_e32 v154, v158, v58
	v_exp_f32_e32 v61, v61
	v_cvt_pk_bf16_f32 v138, v58, v59
	v_add_f32_e32 v154, v59, v154
	s_waitcnt lgkmcnt(4)
	v_mfma_f32_32x32x16_bf16 v[82:97], v[198:201], v[114:117], v[82:97]
	ds_read_b64_tr_b16 v[162:163], v189 offset:50176
	ds_read_b64_tr_b16 v[164:165], v189 offset:50688
	v_exp_f32_e32 v62, v62
	v_exp_f32_e32 v63, v63
	v_add_f32_e32 v154, v154, v60
	v_cvt_pk_bf16_f32 v139, v60, v61
	s_waitcnt lgkmcnt(5)
	v_mfma_f32_32x32x16_bf16 v[66:81], v[202:205], v[118:121], v[66:81]
	ds_read_b64_tr_b16 v[158:159], v189 offset:51200
	ds_read_b64_tr_b16 v[160:161], v189 offset:51712
	v_add_f32_e32 v154, v154, v61
	v_exp_f32_e32 v64, v64
	v_exp_f32_e32 v65, v65
	v_add_f32_e32 v198, v62, v154
	s_waitcnt lgkmcnt(6)
	v_mfma_f32_32x32x16_bf16 v[82:97], v[194:197], v[118:121], v[82:97]
	ds_read_b64_tr_b16 v[154:155], v189 offset:52224
	ds_read_b64_tr_b16 v[156:157], v189 offset:52736
	v_add_f32_e32 v141, v198, v63
	v_add_f32_e32 v198, v64, v141
	v_cvt_pk_bf16_f32 v140, v62, v63
	v_cvt_pk_bf16_f32 v141, v64, v65
	v_add_f32_e32 v194, v65, v198
	s_waitcnt vmcnt(4) lgkmcnt(0)
	s_barrier
	s_waitcnt lgkmcnt(6)
	v_mfma_f32_32x32x16_bf16 v[2:17], v[150:153], v[166:169], v[2:17]
	ds_read_b64_tr_b16 v[34:35], v189 offset:53248
	ds_read_b64_tr_b16 v[36:37], v189 offset:53760
	v_exp_f32_e32 v66, v66
	v_exp_f32_e32 v67, v67
	v_exp_f32_e32 v68, v68
	s_waitcnt lgkmcnt(6)
	v_mfma_f32_32x32x16_bf16 v[2:17], v[146:149], v[162:165], v[2:17]
	ds_read_b64_tr_b16 v[38:39], v189 offset:54272
	ds_read_b64_tr_b16 v[40:41], v189 offset:54784
	v_add_f32_e32 v42, v194, v66
	v_exp_f32_e32 v69, v69
	v_cvt_pk_bf16_f32 v134, v66, v67
	v_add_f32_e32 v46, v67, v42
	s_waitcnt lgkmcnt(6)
	v_mfma_f32_32x32x16_bf16 v[2:17], v[142:145], v[158:161], v[2:17]
	ds_read_b64_tr_b16 v[42:43], v189 offset:55296
	ds_read_b64_tr_b16 v[44:45], v189 offset:55808
	v_exp_f32_e32 v70, v70
	v_exp_f32_e32 v71, v71
	v_add_f32_e32 v50, v46, v68
	v_cvt_pk_bf16_f32 v135, v68, v69
	s_waitcnt lgkmcnt(6)
	v_mfma_f32_32x32x16_bf16 v[2:17], v[138:141], v[154:157], v[2:17]
	ds_read_b64_tr_b16 v[46:47], v189 offset:56320
	ds_read_b64_tr_b16 v[48:49], v189 offset:56832
	v_add_f32_e32 v50, v50, v69
	v_exp_f32_e32 v72, v72
	v_exp_f32_e32 v73, v73
	v_add_f32_e32 v54, v70, v50
	s_waitcnt lgkmcnt(6)
	v_mfma_f32_32x32x16_bf16 v[18:33], v[150:153], v[34:37], v[18:33]
	ds_read_b128 v[50:53], v182
	v_cvt_pk_bf16_f32 v136, v70, v71
	v_add_f32_e32 v58, v54, v71
	v_exp_f32_e32 v74, v74
	v_exp_f32_e32 v75, v75
	s_waitcnt lgkmcnt(5)
	v_mfma_f32_32x32x16_bf16 v[18:33], v[146:149], v[38:41], v[18:33]
	ds_read_b128 v[54:57], v182 offset:4096
	v_add_f32_e32 v34, v58, v72
	v_exp_f32_e32 v76, v76
	v_cvt_pk_bf16_f32 v137, v72, v73
	v_add_f32_e32 v34, v73, v34
	s_waitcnt lgkmcnt(4)
	v_mfma_f32_32x32x16_bf16 v[18:33], v[142:145], v[42:45], v[18:33]
	ds_read_b128 v[154:157], v183
	v_add_f32_e32 v34, v34, v74
	v_exp_f32_e32 v77, v77
	v_cvt_pk_bf16_f32 v130, v74, v75
	v_add_f32_e32 v34, v75, v34
	s_waitcnt lgkmcnt(3)
	v_mfma_f32_32x32x16_bf16 v[18:33], v[138:141], v[46:49], v[18:33]
	ds_read_b128 v[162:165], v183 offset:4096
	v_exp_f32_e32 v78, v78
	v_exp_f32_e32 v79, v79
	v_add_f32_e32 v34, v34, v76
	v_cvt_pk_bf16_f32 v131, v76, v77
	s_nop 0
	v_add_f32_e32 v34, v34, v77
	v_add_f32_e32 v59, v78, v34
	s_waitcnt lgkmcnt(3)
	v_mfma_f32_32x32x16_bf16 v[34:49], v[50:53], v[98:101], 0
	ds_read_b128 v[166:169], v184
	v_exp_f32_e32 v80, v80
	v_exp_f32_e32 v81, v81
	ds_read_b128 v[158:161], v184 offset:4096
	v_add_f32_e32 v193, v59, v79
	s_waitcnt lgkmcnt(4)
	v_mfma_f32_32x32x16_bf16 v[50:65], v[54:57], v[98:101], 0
	v_exp_f32_e32 v82, v82
	v_exp_f32_e32 v83, v83
	v_cvt_pk_bf16_f32 v132, v78, v79
	s_add_i32 s26, 0x9000, s8
	s_add_i32 s28, 0x6000, s12
	s_nop 4
	s_mov_b32 s24, m0
	s_mov_b32 m0, s26
	s_nop 0
	global_load_lds_dwordx4 v174, s[20:21]
	s_mov_b32 m0, s28
	s_nop 0
	global_load_lds_dwordx4 v191, s[20:21]
	s_mov_b32 m0, s24
	s_waitcnt lgkmcnt(3)
	v_mfma_f32_32x32x16_bf16 v[34:49], v[154:157], v[102:105], v[34:49]
	ds_read_b128 v[194:197], v185
	v_add_f32_e32 v154, v193, v80
	v_exp_f32_e32 v84, v84
	v_cvt_pk_bf16_f32 v133, v80, v81
	v_add_f32_e32 v193, v81, v154
	s_waitcnt lgkmcnt(3)
	v_mfma_f32_32x32x16_bf16 v[50:65], v[162:165], v[102:105], v[50:65]
	ds_read_b128 v[154:157], v185 offset:4096
	v_add_f32_e32 v193, v193, v82
	v_exp_f32_e32 v85, v85
	v_cvt_pk_bf16_f32 v126, v82, v83
	v_add_f32_e32 v193, v83, v193
	s_waitcnt lgkmcnt(3)
	v_mfma_f32_32x32x16_bf16 v[34:49], v[166:169], v[106:109], v[34:49]
	ds_read_b128 v[162:165], v187 offset:8192
	v_exp_f32_e32 v86, v86
	v_exp_f32_e32 v87, v87
	v_add_f32_e32 v193, v193, v84
	v_cvt_pk_bf16_f32 v127, v84, v85
	s_waitcnt lgkmcnt(3)
	v_mfma_f32_32x32x16_bf16 v[50:65], v[158:161], v[106:109], v[50:65]
	ds_read_b128 v[198:201], v187 offset:10240
	v_add_f32_e32 v166, v193, v85
	v_exp_f32_e32 v88, v88
	v_exp_f32_e32 v89, v89
	v_add_f32_e32 v166, v86, v166
	s_waitcnt lgkmcnt(3)
	v_mfma_f32_32x32x16_bf16 v[34:49], v[194:197], v[110:113], v[34:49]
	ds_read_b128 v[202:205], v188 offset:8192
	v_cvt_pk_bf16_f32 v128, v86, v87
	v_add_f32_e32 v159, v166, v87
	v_exp_f32_e32 v90, v90
	v_exp_f32_e32 v91, v91
	s_waitcnt lgkmcnt(3)
	v_mfma_f32_32x32x16_bf16 v[50:65], v[154:157], v[110:113], v[50:65]
	ds_read_b128 v[194:197], v188 offset:10240
	v_add_f32_e32 v158, v159, v88
	v_exp_f32_e32 v92, v92
	v_cvt_pk_bf16_f32 v129, v88, v89
	v_add_f32_e32 v158, v89, v158
	s_waitcnt lgkmcnt(3)
	v_mfma_f32_32x32x16_bf16 v[34:49], v[162:165], v[114:117], v[34:49]
	ds_read_b64_tr_b16 v[166:167], v189 offset:57344
	ds_read_b64_tr_b16 v[168:169], v189 offset:57856
	v_add_f32_e32 v154, v158, v90
	v_exp_f32_e32 v93, v93
	v_cvt_pk_bf16_f32 v122, v90, v91
	v_add_f32_e32 v154, v91, v154
	s_waitcnt lgkmcnt(4)
	v_mfma_f32_32x32x16_bf16 v[50:65], v[198:201], v[114:117], v[50:65]
	ds_read_b64_tr_b16 v[162:163], v189 offset:58368
	ds_read_b64_tr_b16 v[164:165], v189 offset:58880
	v_exp_f32_e32 v94, v94
	v_exp_f32_e32 v95, v95
	v_add_f32_e32 v154, v154, v92
	v_cvt_pk_bf16_f32 v123, v92, v93
	s_waitcnt lgkmcnt(5)
	v_mfma_f32_32x32x16_bf16 v[34:49], v[202:205], v[118:121], v[34:49]
	ds_read_b64_tr_b16 v[158:159], v189 offset:59392
	ds_read_b64_tr_b16 v[160:161], v189 offset:59904
	v_add_f32_e32 v154, v154, v93
	v_exp_f32_e32 v96, v96
	v_exp_f32_e32 v97, v97
	v_add_f32_e32 v193, v94, v154
	s_waitcnt lgkmcnt(6)
	v_mfma_f32_32x32x16_bf16 v[50:65], v[194:197], v[118:121], v[50:65]
	ds_read_b64_tr_b16 v[154:155], v189 offset:60416
	ds_read_b64_tr_b16 v[156:157], v189 offset:60928
	v_add_f32_e32 v125, v193, v95
	v_add_f32_e32 v193, v96, v125
	v_cvt_pk_bf16_f32 v124, v94, v95
	v_cvt_pk_bf16_f32 v125, v96, v97
	v_add_f32_e32 v193, v97, v193
	s_add_u32 s22, s22, 0x2000
	s_addc_u32 s23, s23, 0
	s_add_u32 s20, s20, 0x40000
	s_addc_u32 s21, s21, 0
	s_waitcnt vmcnt(4) lgkmcnt(0)
	s_barrier
	s_waitcnt lgkmcnt(6)
	v_mfma_f32_32x32x16_bf16 v[2:17], v[134:137], v[166:169], v[2:17]
	ds_read_b64_tr_b16 v[66:67], v189 offset:61440
	ds_read_b64_tr_b16 v[68:69], v189 offset:61952
	v_exp_f32_e32 v34, v34
	v_exp_f32_e32 v35, v35
	v_exp_f32_e32 v36, v36
	s_waitcnt lgkmcnt(6)
	v_mfma_f32_32x32x16_bf16 v[2:17], v[130:133], v[162:165], v[2:17]
	ds_read_b64_tr_b16 v[70:71], v189 offset:62464
	ds_read_b64_tr_b16 v[72:73], v189 offset:62976
	v_add_f32_e32 v74, v193, v34
	v_exp_f32_e32 v37, v37
	v_cvt_pk_bf16_f32 v150, v34, v35
	v_add_f32_e32 v78, v35, v74
	s_waitcnt lgkmcnt(6)
	v_mfma_f32_32x32x16_bf16 v[2:17], v[126:129], v[158:161], v[2:17]
	ds_read_b64_tr_b16 v[74:75], v189 offset:63488
	ds_read_b64_tr_b16 v[76:77], v189 offset:64000
	v_exp_f32_e32 v38, v38
	v_exp_f32_e32 v39, v39
	v_add_f32_e32 v82, v78, v36
	v_cvt_pk_bf16_f32 v151, v36, v37
	s_waitcnt lgkmcnt(6)
	v_mfma_f32_32x32x16_bf16 v[2:17], v[122:125], v[154:157], v[2:17]
	ds_read_b64_tr_b16 v[78:79], v189 offset:64512
	ds_read_b64_tr_b16 v[80:81], v189 offset:65024
	v_add_f32_e32 v82, v82, v37
	v_exp_f32_e32 v40, v40
	v_exp_f32_e32 v41, v41
	v_add_f32_e32 v86, v38, v82
	s_waitcnt lgkmcnt(6)
	v_mfma_f32_32x32x16_bf16 v[18:33], v[134:137], v[66:69], v[18:33]
	ds_read_b128 v[82:85], v182 offset:12288
	v_cvt_pk_bf16_f32 v152, v38, v39
	v_add_f32_e32 v90, v86, v39
	v_exp_f32_e32 v42, v42
	v_exp_f32_e32 v43, v43
	s_waitcnt lgkmcnt(5)
	v_mfma_f32_32x32x16_bf16 v[18:33], v[130:133], v[70:73], v[18:33]
	ds_read_b128 v[86:89], v182 offset:16384
	v_add_f32_e32 v66, v90, v40
	v_exp_f32_e32 v44, v44
	v_cvt_pk_bf16_f32 v153, v40, v41
	v_add_f32_e32 v66, v41, v66
	s_waitcnt lgkmcnt(4)
	v_mfma_f32_32x32x16_bf16 v[18:33], v[126:129], v[74:77], v[18:33]
	ds_read_b128 v[154:157], v183 offset:12288
	v_add_f32_e32 v66, v66, v42
	v_exp_f32_e32 v45, v45
	v_cvt_pk_bf16_f32 v146, v42, v43
	v_add_f32_e32 v66, v43, v66
	s_waitcnt lgkmcnt(3)
	v_mfma_f32_32x32x16_bf16 v[18:33], v[122:125], v[78:81], v[18:33]
	ds_read_b128 v[162:165], v183 offset:16384
	v_exp_f32_e32 v46, v46
	v_exp_f32_e32 v47, v47
	v_add_f32_e32 v66, v66, v44
	v_cvt_pk_bf16_f32 v147, v44, v45
	s_nop 0
	v_add_f32_e32 v66, v66, v45
	v_add_f32_e32 v91, v46, v66
	s_waitcnt lgkmcnt(3)
	v_mfma_f32_32x32x16_bf16 v[66:81], v[82:85], v[98:101], 0
	ds_read_b128 v[166:169], v184 offset:12288
	v_exp_f32_e32 v48, v48
	v_exp_f32_e32 v49, v49
	ds_read_b128 v[158:161], v184 offset:16384
	v_add_f32_e32 v193, v91, v47
	s_waitcnt lgkmcnt(4)
	v_mfma_f32_32x32x16_bf16 v[82:97], v[86:89], v[98:101], 0
	v_exp_f32_e32 v50, v50
	v_exp_f32_e32 v51, v51
	v_cvt_pk_bf16_f32 v148, v46, v47
	s_add_u32 s26, s20, 0xfffe0000
	s_addc_u32 s27, s21, -1
	s_add_i32 s31, 0, s8
	s_add_i32 s33, 0x8000, s12
	s_nop 4
	s_mov_b32 s28, m0
	s_mov_b32 m0, s31
	s_nop 0
	global_load_lds_dwordx4 v174, s[26:27]
	s_mov_b32 m0, s33
	s_nop 0
	global_load_lds_dwordx4 v191, s[26:27]
	s_mov_b32 m0, s28
	s_waitcnt lgkmcnt(3)
	v_mfma_f32_32x32x16_bf16 v[66:81], v[154:157], v[102:105], v[66:81]
	ds_read_b128 v[194:197], v185 offset:12288
	v_add_f32_e32 v193, v193, v48
	v_cvt_pk_bf16_f32 v149, v48, v49
	v_add_f32_e32 v193, v49, v193
	v_exp_f32_e32 v52, v52
	s_waitcnt lgkmcnt(3)
	v_mfma_f32_32x32x16_bf16 v[82:97], v[162:165], v[102:105], v[82:97]
	ds_read_b128 v[154:157], v185 offset:16384
	v_add_f32_e32 v193, v193, v50
	v_exp_f32_e32 v53, v53
	v_cvt_pk_bf16_f32 v142, v50, v51
	v_add_f32_e32 v193, v51, v193
	s_waitcnt lgkmcnt(3)
	v_mfma_f32_32x32x16_bf16 v[66:81], v[166:169], v[106:109], v[66:81]
	ds_read_b128 v[162:165], v187 offset:20480
	v_exp_f32_e32 v54, v54
	v_exp_f32_e32 v55, v55
	v_add_f32_e32 v193, v193, v52
	v_cvt_pk_bf16_f32 v143, v52, v53
	s_waitcnt lgkmcnt(3)
	v_mfma_f32_32x32x16_bf16 v[82:97], v[158:161], v[106:109], v[82:97]
	ds_read_b128 v[198:201], v187 offset:22528
	v_add_f32_e32 v166, v193, v53
	v_exp_f32_e32 v56, v56
	v_exp_f32_e32 v57, v57
	v_add_f32_e32 v166, v54, v166
	s_waitcnt lgkmcnt(3)
	v_mfma_f32_32x32x16_bf16 v[66:81], v[194:197], v[110:113], v[66:81]
	ds_read_b128 v[202:205], v188 offset:20480
	v_cvt_pk_bf16_f32 v144, v54, v55
	v_add_f32_e32 v159, v166, v55
	v_exp_f32_e32 v58, v58
	v_exp_f32_e32 v59, v59
	s_waitcnt lgkmcnt(3)
	v_mfma_f32_32x32x16_bf16 v[82:97], v[154:157], v[110:113], v[82:97]
	ds_read_b128 v[194:197], v188 offset:22528
	v_add_f32_e32 v158, v159, v56
	v_exp_f32_e32 v60, v60
	v_cvt_pk_bf16_f32 v145, v56, v57
	v_add_f32_e32 v158, v57, v158
	s_waitcnt lgkmcnt(3)
	v_mfma_f32_32x32x16_bf16 v[66:81], v[162:165], v[114:117], v[66:81]
	ds_read_b64_tr_b16 v[166:167], v189 offset:16384
	ds_read_b64_tr_b16 v[168:169], v189 offset:16896
	v_add_f32_e32 v154, v158, v58
	v_exp_f32_e32 v61, v61
	v_cvt_pk_bf16_f32 v138, v58, v59
	v_add_f32_e32 v154, v59, v154
	s_waitcnt lgkmcnt(4)
	v_mfma_f32_32x32x16_bf16 v[82:97], v[198:201], v[114:117], v[82:97]
	ds_read_b64_tr_b16 v[162:163], v189 offset:17408
	ds_read_b64_tr_b16 v[164:165], v189 offset:17920
	v_exp_f32_e32 v62, v62
	v_exp_f32_e32 v63, v63
	v_add_f32_e32 v154, v154, v60
	v_cvt_pk_bf16_f32 v139, v60, v61
	s_waitcnt lgkmcnt(5)
	v_mfma_f32_32x32x16_bf16 v[66:81], v[202:205], v[118:121], v[66:81]
	ds_read_b64_tr_b16 v[158:159], v189 offset:18432
	ds_read_b64_tr_b16 v[160:161], v189 offset:18944
	v_add_f32_e32 v154, v154, v61
	v_exp_f32_e32 v64, v64
	v_exp_f32_e32 v65, v65
	v_add_f32_e32 v198, v62, v154
	s_waitcnt lgkmcnt(6)
	v_mfma_f32_32x32x16_bf16 v[82:97], v[194:197], v[118:121], v[82:97]
	ds_read_b64_tr_b16 v[154:155], v189 offset:19456
	ds_read_b64_tr_b16 v[156:157], v189 offset:19968
	v_add_f32_e32 v141, v198, v63
	v_add_f32_e32 v198, v64, v141
	v_cvt_pk_bf16_f32 v140, v62, v63
	v_cvt_pk_bf16_f32 v141, v64, v65
	v_add_f32_e32 v194, v65, v198
	s_waitcnt vmcnt(4) lgkmcnt(0)
	s_barrier
	s_waitcnt lgkmcnt(6)
	v_mfma_f32_32x32x16_bf16 v[2:17], v[150:153], v[166:169], v[2:17]
	ds_read_b64_tr_b16 v[34:35], v189 offset:20480
	ds_read_b64_tr_b16 v[36:37], v189 offset:20992
	v_exp_f32_e32 v66, v66
	v_exp_f32_e32 v67, v67
	v_exp_f32_e32 v68, v68
	s_waitcnt lgkmcnt(6)
	v_mfma_f32_32x32x16_bf16 v[2:17], v[146:149], v[162:165], v[2:17]
	ds_read_b64_tr_b16 v[38:39], v189 offset:21504
	ds_read_b64_tr_b16 v[40:41], v189 offset:22016
	v_add_f32_e32 v42, v194, v66
	v_exp_f32_e32 v69, v69
	v_cvt_pk_bf16_f32 v134, v66, v67
	v_add_f32_e32 v46, v67, v42
	s_waitcnt lgkmcnt(6)
	v_mfma_f32_32x32x16_bf16 v[2:17], v[142:145], v[158:161], v[2:17]
	ds_read_b64_tr_b16 v[42:43], v189 offset:22528
	ds_read_b64_tr_b16 v[44:45], v189 offset:23040
	v_exp_f32_e32 v70, v70
	v_exp_f32_e32 v71, v71
	v_add_f32_e32 v50, v46, v68
	v_cvt_pk_bf16_f32 v135, v68, v69
	s_waitcnt lgkmcnt(6)
	v_mfma_f32_32x32x16_bf16 v[2:17], v[138:141], v[154:157], v[2:17]
	ds_read_b64_tr_b16 v[46:47], v189 offset:23552
	ds_read_b64_tr_b16 v[48:49], v189 offset:24064
	v_add_f32_e32 v50, v50, v69
	v_exp_f32_e32 v72, v72
	v_exp_f32_e32 v73, v73
	v_add_f32_e32 v54, v70, v50
	s_waitcnt lgkmcnt(6)
	v_mfma_f32_32x32x16_bf16 v[18:33], v[150:153], v[34:37], v[18:33]
	ds_read_b128 v[50:53], v182 offset:24576
	v_cvt_pk_bf16_f32 v136, v70, v71
	v_add_f32_e32 v58, v54, v71
	v_exp_f32_e32 v74, v74
	v_exp_f32_e32 v75, v75
	s_waitcnt lgkmcnt(5)
	v_mfma_f32_32x32x16_bf16 v[18:33], v[146:149], v[38:41], v[18:33]
	ds_read_b128 v[54:57], v182 offset:28672
	v_add_f32_e32 v34, v58, v72
	v_exp_f32_e32 v76, v76
	v_cvt_pk_bf16_f32 v137, v72, v73
	v_add_f32_e32 v34, v73, v34
	s_waitcnt lgkmcnt(4)
	v_mfma_f32_32x32x16_bf16 v[18:33], v[142:145], v[42:45], v[18:33]
	ds_read_b128 v[154:157], v183 offset:24576
	v_add_f32_e32 v34, v34, v74
	v_exp_f32_e32 v77, v77
	v_cvt_pk_bf16_f32 v130, v74, v75
	v_add_f32_e32 v34, v75, v34
	s_waitcnt lgkmcnt(3)
	v_mfma_f32_32x32x16_bf16 v[18:33], v[138:141], v[46:49], v[18:33]
	ds_read_b128 v[162:165], v183 offset:28672
	v_exp_f32_e32 v78, v78
	v_exp_f32_e32 v79, v79
	v_add_f32_e32 v34, v34, v76
	v_cvt_pk_bf16_f32 v131, v76, v77
	s_nop 0
	v_add_f32_e32 v34, v34, v77
	v_add_f32_e32 v59, v78, v34
	s_waitcnt lgkmcnt(3)
	v_mfma_f32_32x32x16_bf16 v[34:49], v[50:53], v[98:101], 0
	ds_read_b128 v[166:169], v184 offset:24576
	v_exp_f32_e32 v80, v80
	v_exp_f32_e32 v81, v81
	ds_read_b128 v[158:161], v184 offset:28672
	v_add_f32_e32 v193, v59, v79
	s_waitcnt lgkmcnt(4)
	v_mfma_f32_32x32x16_bf16 v[50:65], v[54:57], v[98:101], 0
	v_exp_f32_e32 v82, v82
	v_exp_f32_e32 v83, v83
	v_cvt_pk_bf16_f32 v132, v78, v79
	s_add_i32 s26, 0x3000, s8
	s_add_i32 s28, 0xa000, s12
	s_nop 4
	s_mov_b32 s24, m0
	s_mov_b32 m0, s26
	s_nop 0
	global_load_lds_dwordx4 v174, s[20:21]
	s_mov_b32 m0, s28
	s_nop 0
	global_load_lds_dwordx4 v191, s[20:21]
	s_mov_b32 m0, s24
	s_waitcnt lgkmcnt(3)
	v_mfma_f32_32x32x16_bf16 v[34:49], v[154:157], v[102:105], v[34:49]
	ds_read_b128 v[194:197], v185 offset:24576
	v_add_f32_e32 v154, v193, v80
	v_exp_f32_e32 v84, v84
	v_cvt_pk_bf16_f32 v133, v80, v81
	v_add_f32_e32 v193, v81, v154
	s_waitcnt lgkmcnt(3)
	v_mfma_f32_32x32x16_bf16 v[50:65], v[162:165], v[102:105], v[50:65]
	ds_read_b128 v[154:157], v185 offset:28672
	v_add_f32_e32 v193, v193, v82
	v_exp_f32_e32 v85, v85
	v_cvt_pk_bf16_f32 v126, v82, v83
	v_add_f32_e32 v193, v83, v193
	s_waitcnt lgkmcnt(3)
	v_mfma_f32_32x32x16_bf16 v[34:49], v[166:169], v[106:109], v[34:49]
	ds_read_b128 v[162:165], v187 offset:32768
	v_exp_f32_e32 v86, v86
	v_exp_f32_e32 v87, v87
	v_add_f32_e32 v193, v193, v84
	v_cvt_pk_bf16_f32 v127, v84, v85
	s_waitcnt lgkmcnt(3)
	v_mfma_f32_32x32x16_bf16 v[50:65], v[158:161], v[106:109], v[50:65]
	ds_read_b128 v[198:201], v187 offset:34816
	v_add_f32_e32 v166, v193, v85
	v_exp_f32_e32 v88, v88
	v_exp_f32_e32 v89, v89
	v_add_f32_e32 v166, v86, v166
	s_waitcnt lgkmcnt(3)
	v_mfma_f32_32x32x16_bf16 v[34:49], v[194:197], v[110:113], v[34:49]
	ds_read_b128 v[202:205], v188 offset:32768
	v_cvt_pk_bf16_f32 v128, v86, v87
	v_add_f32_e32 v159, v166, v87
	v_exp_f32_e32 v90, v90
	v_exp_f32_e32 v91, v91
	s_waitcnt lgkmcnt(3)
	v_mfma_f32_32x32x16_bf16 v[50:65], v[154:157], v[110:113], v[50:65]
	ds_read_b128 v[194:197], v188 offset:34816
	v_add_f32_e32 v158, v159, v88
	v_exp_f32_e32 v92, v92
	v_cvt_pk_bf16_f32 v129, v88, v89
	v_add_f32_e32 v158, v89, v158
	s_waitcnt lgkmcnt(3)
	v_mfma_f32_32x32x16_bf16 v[34:49], v[162:165], v[114:117], v[34:49]
	ds_read_b64_tr_b16 v[166:167], v189 offset:24576
	ds_read_b64_tr_b16 v[168:169], v189 offset:25088
	v_add_f32_e32 v154, v158, v90
	v_exp_f32_e32 v93, v93
	v_cvt_pk_bf16_f32 v122, v90, v91
	v_add_f32_e32 v154, v91, v154
	s_waitcnt lgkmcnt(4)
	v_mfma_f32_32x32x16_bf16 v[50:65], v[198:201], v[114:117], v[50:65]
	ds_read_b64_tr_b16 v[162:163], v189 offset:25600
	ds_read_b64_tr_b16 v[164:165], v189 offset:26112
	v_exp_f32_e32 v94, v94
	v_exp_f32_e32 v95, v95
	v_add_f32_e32 v154, v154, v92
	v_cvt_pk_bf16_f32 v123, v92, v93
	s_waitcnt lgkmcnt(5)
	v_mfma_f32_32x32x16_bf16 v[34:49], v[202:205], v[118:121], v[34:49]
	ds_read_b64_tr_b16 v[158:159], v189 offset:26624
	ds_read_b64_tr_b16 v[160:161], v189 offset:27136
	v_add_f32_e32 v154, v154, v93
	v_exp_f32_e32 v96, v96
	v_exp_f32_e32 v97, v97
	v_add_f32_e32 v193, v94, v154
	s_waitcnt lgkmcnt(6)
	v_mfma_f32_32x32x16_bf16 v[50:65], v[194:197], v[118:121], v[50:65]
	ds_read_b64_tr_b16 v[154:155], v189 offset:27648
	ds_read_b64_tr_b16 v[156:157], v189 offset:28160
	v_add_f32_e32 v125, v193, v95
	v_add_f32_e32 v193, v96, v125
	v_cvt_pk_bf16_f32 v124, v94, v95
	v_cvt_pk_bf16_f32 v125, v96, v97
	v_add_f32_e32 v193, v97, v193
	s_add_u32 s22, s22, 0x2000
	s_addc_u32 s23, s23, 0
	s_add_u32 s20, s20, 0x40000
	s_addc_u32 s21, s21, 0
	s_add_i32 s13, s13, 12
	s_cmp_le_i32 s13, 108
	s_cbranch_scc1 .Lmla_fast_w47
	v_subrev_u32_e32 v189, 0x8000, v189
	s_mov_b32 s2, 0x4000
	s_mov_b32 s17, 0x6000
	s_mov_b32 s26, 0x2000
	s_mov_b32 s14, 0x0
	s_mov_b32 s15, 0x9000
	s_branch .LBB0_1278
.Lmla_dispatch:
	v_add_u32_e32 v189, 0x8000, v189
	s_and_b64 vcc, exec, s[18:19]
	s_cbranch_vccz .Lmla_fast_w03
	s_branch .Lmla_fast_w47
